# dn_prep forward substitution: L-row LDS reads issued one read-interval ahead into a rotating set of fresh VGPRs (alloc 256), on top of the epilogue ss-load hoist
# speedup vs baseline: 1.0001x; 1.0001x over previous
; #define LAS __attribute__((address_space(3)))
; __device__ __forceinline__ float bf2f(unsigned short v) { return __uint_as_float(((unsigned)v) << 16); }
; __device__ __forceinline__ void dn_prep_item(const Args& a, LAS unsigned char* lds, int item, int tid, int wave, int lane, int& cwh, int next_item) {
;     ...
;         { const LAS unsigned char* src = lds + (tid < 128 ? L_V : L_KH) + 2 * (tid & 127); const LAS float* fac = tid < 128 ? betas : bks;
; #pragma unroll
;           for (int i = 0; i < 64; ++i) x[i] = bf2f(*(const LAS unsigned short*)(src + i * KS_)) * fac[i]; }
.LBB0_878:
	s_and_b64 vcc, exec, s[22:23]
	s_cbranch_vccz .LBB0_880
	ds_read_b128 v[0:3], v190
	ds_read_u16 v4, v189
	ds_read_u16 v5, v189 offset:272
	ds_read_u16 v6, v189 offset:544
	ds_read_u16 v10, v189 offset:816
	ds_read_u16 v11, v189 offset:1088
	ds_read_u16 v12, v189 offset:1360
	ds_read_u16 v13, v189 offset:1632
	ds_read_u16 v14, v189 offset:1904
	s_waitcnt lgkmcnt(7)
	v_lshlrev_b32_e32 v4, 16, v4
	v_mul_f32_e32 v71, v0, v4
	s_waitcnt lgkmcnt(6)
	v_lshlrev_b32_e32 v0, 16, v5
	v_mul_f32_e32 v1, v1, v0
	s_waitcnt lgkmcnt(5)
	v_lshlrev_b32_e32 v0, 16, v6
	ds_read_b128 v[6:9], v191
	v_mul_f32_e32 v5, v2, v0
	s_waitcnt lgkmcnt(5)
	v_lshlrev_b32_e32 v0, 16, v10
	v_mul_f32_e32 v2, v3, v0
	s_waitcnt lgkmcnt(4)
	v_lshlrev_b32_e32 v0, 16, v11
	s_waitcnt lgkmcnt(0)
	v_mul_f32_e32 v4, v6, v0
	v_lshlrev_b32_e32 v0, 16, v12
	v_mul_f32_e32 v6, v7, v0
	v_lshlrev_b32_e32 v0, 16, v13
	v_mul_f32_e32 v8, v8, v0
	v_lshlrev_b32_e32 v0, 16, v14
	v_mul_f32_e32 v10, v9, v0
	ds_read_b128 v[14:17], v192
	ds_read_u16 v0, v189 offset:2176
	ds_read_u16 v3, v189 offset:2448
	ds_read_u16 v7, v189 offset:2720
	ds_read_u16 v9, v189 offset:2992
	ds_read_u16 v11, v189 offset:3264
	ds_read_u16 v13, v189 offset:3536
	ds_read_u16 v19, v189 offset:3808
	ds_read_u16 v21, v189 offset:4080
	s_waitcnt lgkmcnt(7)
	v_lshlrev_b32_e32 v0, 16, v0
	ds_read_b128 v[24:27], v193
	v_mul_f32_e32 v12, v14, v0
	s_waitcnt lgkmcnt(7)
	v_lshlrev_b32_e32 v0, 16, v3
	v_mul_f32_e32 v14, v15, v0
	s_waitcnt lgkmcnt(6)
	v_lshlrev_b32_e32 v0, 16, v7
	v_mul_f32_e32 v18, v16, v0
	s_waitcnt lgkmcnt(5)
	v_lshlrev_b32_e32 v0, 16, v9
	v_mul_f32_e32 v20, v17, v0
	s_waitcnt lgkmcnt(4)
	v_lshlrev_b32_e32 v0, 16, v11
	s_waitcnt lgkmcnt(0)
	v_mul_f32_e32 v22, v24, v0
	v_lshlrev_b32_e32 v0, 16, v13
	v_mul_f32_e32 v24, v25, v0
	v_lshlrev_b32_e32 v0, 16, v19
	v_mul_f32_e32 v26, v26, v0
	v_lshlrev_b32_e32 v0, 16, v21
	v_mul_f32_e32 v30, v27, v0
	ds_read_b128 v[34:37], v194
	ds_read_u16 v0, v189 offset:4352
	ds_read_u16 v3, v189 offset:4624
	ds_read_u16 v7, v189 offset:4896
	ds_read_u16 v9, v189 offset:5168
	ds_read_u16 v11, v189 offset:5440
	ds_read_u16 v13, v189 offset:5712
	ds_read_u16 v15, v189 offset:5984
	ds_read_u16 v16, v189 offset:6256
	s_waitcnt lgkmcnt(7)
	v_lshlrev_b32_e32 v0, 16, v0
	ds_read_b128 v[42:45], v195
	v_mul_f32_e32 v32, v34, v0
	s_waitcnt lgkmcnt(7)
	v_lshlrev_b32_e32 v0, 16, v3
	v_mul_f32_e32 v34, v35, v0
	s_waitcnt lgkmcnt(6)
	v_lshlrev_b32_e32 v0, 16, v7
	v_mul_f32_e32 v38, v36, v0
	s_waitcnt lgkmcnt(5)
	v_lshlrev_b32_e32 v0, 16, v9
	v_mul_f32_e32 v40, v37, v0
	s_waitcnt lgkmcnt(4)
	v_lshlrev_b32_e32 v0, 16, v11
	s_waitcnt lgkmcnt(0)
	v_mul_f32_e32 v42, v42, v0
	v_lshlrev_b32_e32 v0, 16, v13
	v_mul_f32_e32 v46, v43, v0
	v_lshlrev_b32_e32 v0, 16, v15
	v_mul_f32_e32 v72, v44, v0
	v_lshlrev_b32_e32 v0, 16, v16
	v_mul_f32_e32 v74, v45, v0
	ds_read_b128 v[80:83], v196
	ds_read_u16 v0, v189 offset:6528
	ds_read_u16 v3, v189 offset:6800
	ds_read_u16 v7, v189 offset:7072
	ds_read_u16 v9, v189 offset:7344
	ds_read_u16 v11, v189 offset:7616
	ds_read_u16 v13, v189 offset:7888
	ds_read_u16 v15, v189 offset:8160
	ds_read_u16 v16, v189 offset:8432
	s_waitcnt lgkmcnt(7)
	v_lshlrev_b32_e32 v0, 16, v0
	ds_read_b128 v[92:95], v197
	v_mul_f32_e32 v78, v80, v0
	s_waitcnt lgkmcnt(7)
	v_lshlrev_b32_e32 v0, 16, v3
	v_mul_f32_e32 v80, v81, v0
	s_waitcnt lgkmcnt(6)
	v_lshlrev_b32_e32 v0, 16, v7
	v_mul_f32_e32 v84, v82, v0
	s_waitcnt lgkmcnt(5)
	v_lshlrev_b32_e32 v0, 16, v9
	v_mul_f32_e32 v86, v83, v0
	s_waitcnt lgkmcnt(4)
	v_lshlrev_b32_e32 v0, 16, v11
	s_waitcnt lgkmcnt(0)
	v_mul_f32_e32 v90, v92, v0
	v_lshlrev_b32_e32 v0, 16, v13
	v_mul_f32_e32 v92, v93, v0
	v_lshlrev_b32_e32 v0, 16, v15
	v_mul_f32_e32 v96, v94, v0
	v_lshlrev_b32_e32 v0, 16, v16
	v_mul_f32_e32 v98, v95, v0
	ds_read_b128 v[102:105], v198
	ds_read_u16 v0, v189 offset:8704
	ds_read_u16 v3, v189 offset:8976
	ds_read_u16 v7, v189 offset:9248
	ds_read_u16 v9, v189 offset:9520
	ds_read_u16 v11, v189 offset:9792
	ds_read_u16 v13, v189 offset:10064
	ds_read_u16 v15, v189 offset:10336
	ds_read_u16 v16, v189 offset:10608
	s_waitcnt lgkmcnt(7)
	v_lshlrev_b32_e32 v0, 16, v0
	ds_read_b128 v[118:121], v199
	v_mul_f32_e32 v102, v102, v0
	s_waitcnt lgkmcnt(7)
	v_lshlrev_b32_e32 v0, 16, v3
	v_mul_f32_e32 v106, v103, v0
	s_waitcnt lgkmcnt(6)
	v_lshlrev_b32_e32 v0, 16, v7
	v_mul_f32_e32 v108, v104, v0
	s_waitcnt lgkmcnt(5)
	v_lshlrev_b32_e32 v0, 16, v9
	v_mul_f32_e32 v112, v105, v0
	s_waitcnt lgkmcnt(4)
	v_lshlrev_b32_e32 v0, 16, v11
	s_waitcnt lgkmcnt(0)
	v_mul_f32_e32 v116, v118, v0
	v_lshlrev_b32_e32 v0, 16, v13
	v_mul_f32_e32 v118, v119, v0
	v_lshlrev_b32_e32 v0, 16, v15
	v_mul_f32_e32 v122, v120, v0
	v_lshlrev_b32_e32 v0, 16, v16
	v_mul_f32_e32 v126, v121, v0
	ds_read_b128 v[130:133], v201
	ds_read_u16 v0, v189 offset:10880
	ds_read_u16 v3, v189 offset:11152
	ds_read_u16 v7, v189 offset:11424
	ds_read_u16 v9, v189 offset:11696
	ds_read_u16 v11, v189 offset:11968
	ds_read_u16 v13, v189 offset:12240
	ds_read_u16 v15, v189 offset:12512
	ds_read_u16 v16, v189 offset:12784
	s_waitcnt lgkmcnt(7)
	v_lshlrev_b32_e32 v0, 16, v0
	ds_read_b128 v[144:147], v202
	v_mul_f32_e32 v130, v130, v0
	s_waitcnt lgkmcnt(7)
	v_lshlrev_b32_e32 v0, 16, v3
	v_mul_f32_e32 v134, v131, v0
	s_waitcnt lgkmcnt(6)
	v_lshlrev_b32_e32 v0, 16, v7
	v_mul_f32_e32 v138, v132, v0
	s_waitcnt lgkmcnt(5)
	v_lshlrev_b32_e32 v0, 16, v9
	v_mul_f32_e32 v142, v133, v0
	s_waitcnt lgkmcnt(4)
	v_lshlrev_b32_e32 v0, 16, v11
	s_waitcnt lgkmcnt(0)
; #define LAS __attribute__((address_space(3)))
; __device__ __forceinline__ float bf2f(unsigned short v) { return __uint_as_float(((unsigned)v) << 16); }
; __device__ __forceinline__ void dn_prep_item(const Args& a, LAS unsigned char* lds, int item, int tid, int wave, int lane, int& cwh, int next_item) {
;     ...
;           for (int i = 0; i < 64; ++i) x[i] = bf2f(*(const LAS unsigned short*)(src + i * KS_)) * fac[i]; }
;         { const LAS float* lrow = Lm + (lane & 15);
; #pragma unroll
;         for (int i = 1; i < 64; ++i) { float sa[4] = { x[i], 0.f, 0.f, 0.f };
;             int lr[4];
; #pragma unroll
;             for (int g = 0; g < (i + 15) / 16; ++g) lr[g] = __float_as_int(lrow[i * 68 + 16 * g]);
; #pragma unroll
;             for (int j = 0; j < i; ++j) { fmac_rowbcast_sel(sa[j & 3], lr[j >> 4], x[j], j); }
;             x[i] = (sa[0] + sa[1]) + (sa[2] + sa[3]); } }
	v_mul_f32_e32 v144, v144, v0
	v_lshlrev_b32_e32 v0, 16, v13
	v_mul_f32_e32 v140, v145, v0
	v_lshlrev_b32_e32 v0, 16, v15
	v_mul_f32_e32 v136, v146, v0
	v_lshlrev_b32_e32 v0, 16, v16
	v_mul_f32_e32 v132, v147, v0
	ds_read_b128 v[234:237], v203
	ds_read_u16 v0, v189 offset:13056
	ds_read_u16 v3, v189 offset:13328
	ds_read_u16 v7, v189 offset:13600
	ds_read_u16 v9, v189 offset:13872
	ds_read_u16 v11, v189 offset:14144
	ds_read_u16 v13, v189 offset:14416
	ds_read_u16 v15, v189 offset:14688
	ds_read_u16 v16, v189 offset:14960
	s_waitcnt lgkmcnt(7)
	v_lshlrev_b32_e32 v0, 16, v0
	ds_read_b128 v[238:241], v204
	v_mul_f32_e32 v128, v234, v0
	s_waitcnt lgkmcnt(7)
	v_lshlrev_b32_e32 v0, 16, v3
	v_mul_f32_e32 v124, v235, v0
	s_waitcnt lgkmcnt(6)
	v_lshlrev_b32_e32 v0, 16, v7
	v_mul_f32_e32 v120, v236, v0
	s_waitcnt lgkmcnt(5)
	v_lshlrev_b32_e32 v0, 16, v9
	v_mul_f32_e32 v114, v237, v0
	s_waitcnt lgkmcnt(4)
	v_lshlrev_b32_e32 v0, 16, v11
	s_waitcnt lgkmcnt(0)
	v_mul_f32_e32 v110, v238, v0
	v_lshlrev_b32_e32 v0, 16, v13
	v_mul_f32_e32 v104, v239, v0
	v_lshlrev_b32_e32 v0, 16, v15
	v_mul_f32_e32 v100, v240, v0
	v_lshlrev_b32_e32 v0, 16, v16
	v_mul_f32_e32 v94, v241, v0
	ds_read_b128 v[234:237], v205
	ds_read_u16 v0, v189 offset:15232
	ds_read_u16 v3, v189 offset:15504
	ds_read_u16 v7, v189 offset:15776
	ds_read_u16 v9, v189 offset:16048
	ds_read_u16 v11, v189 offset:16320
	ds_read_u16 v13, v189 offset:16592
	ds_read_u16 v15, v189 offset:16864
	ds_read_u16 v17, v189 offset:17136
	s_waitcnt lgkmcnt(7)
	v_lshlrev_b32_e32 v0, 16, v0
	ds_read_b128 v[238:241], v207
	v_mul_f32_e32 v88, v234, v0
	s_waitcnt lgkmcnt(7)
	v_lshlrev_b32_e32 v0, 16, v3
	v_mul_f32_e32 v82, v235, v0
	s_waitcnt lgkmcnt(6)
	v_lshlrev_b32_e32 v0, 16, v7
	v_mul_f32_e32 v76, v236, v0
	s_waitcnt lgkmcnt(5)
	v_lshlrev_b32_e32 v0, 16, v9
	v_mul_f32_e32 v44, v237, v0
	s_waitcnt lgkmcnt(4)
	v_lshlrev_b32_e32 v0, 16, v11
	s_waitcnt lgkmcnt(0)
	v_mul_f32_e32 v36, v238, v0
	v_lshlrev_b32_e32 v0, 16, v13
	v_mul_f32_e32 v28, v239, v0
	v_add_u32_e32 v0, 0x8800, v208
	ds_read2_b32 v[242:243], v0 offset0:68 offset1:136
	s_waitcnt lgkmcnt(0)
	v_add_u32_e32 v254, 0x8a00, v208
	ds_read2_b32 v[246:247], v254 offset0:76 offset1:144
	v_fmac_f32_dpp v1, v242, v71 row_newbcast:0 row_mask:0xf bank_mask:0xf
	v_fmac_f32_dpp v5, v243, v71 row_newbcast:0 row_mask:0xf bank_mask:0xf
	v_mov_b32_e32 v3, v57
	v_add_f32_e32 v234, 0, v1
	v_add_u32_e32 v1, 0x8a00, v208
	s_nop 0
	v_mov_b32_e32 v1, v57
	v_fmac_f32_dpp v1, v243, v234 row_newbcast:1 row_mask:0xf bank_mask:0xf
	s_waitcnt lgkmcnt(0)
	v_add_u32_e32 v254, 0x8c00, v208
	ds_read2_b32 v[248:249], v254 offset0:84 offset1:152
	v_fmac_f32_dpp v2, v246, v71 row_newbcast:0 row_mask:0xf bank_mask:0xf
	v_mov_b32_e32 v56, v57
	v_add_f32_e32 v1, v5, v1
	v_add_f32_e32 v235, 0, v1
	v_fmac_f32_dpp v3, v246, v235 row_newbcast:2 row_mask:0xf bank_mask:0xf
	v_mov_b32_e32 v146, v57
	v_mov_b32_e32 v5, v57
	v_fmac_f32_dpp v56, v246, v234 row_newbcast:1 row_mask:0xf bank_mask:0xf
	v_fmac_f32_dpp v4, v247, v71 row_newbcast:0 row_mask:0xf bank_mask:0xf
	v_fmac_f32_dpp v146, v247, v234 row_newbcast:1 row_mask:0xf bank_mask:0xf
	v_fmac_f32_dpp v5, v247, v235 row_newbcast:2 row_mask:0xf bank_mask:0xf
	v_add_u32_e32 v1, 0x8c00, v208
	v_pk_add_f32 v[2:3], v[2:3], v[56:57]
	v_mov_b32_e32 v147, v57
	v_pk_add_f32 v[2:3], v[2:3], v[2:3] op_sel:[0,1] op_sel_hi:[1,0]
	s_nop 0
	v_fmac_f32_dpp v147, v247, v2 row_newbcast:3 row_mask:0xf bank_mask:0xf
	s_waitcnt lgkmcnt(0)
	v_add_u32_e32 v254, 0x8e00, v208
	ds_read2_b32 v[250:251], v254 offset0:92 offset1:160
	v_fmac_f32_dpp v6, v248, v71 row_newbcast:0 row_mask:0xf bank_mask:0xf
	v_mov_b32_e32 v7, v57
	v_pk_add_f32 v[4:5], v[4:5], v[146:147]
	v_mov_b32_e32 v146, v57
	v_pk_add_f32 v[4:5], v[4:5], v[4:5] op_sel:[0,1] op_sel_hi:[1,0]
	v_fmac_f32_dpp v146, v248, v234 row_newbcast:1 row_mask:0xf bank_mask:0xf
	v_fmac_f32_dpp v7, v248, v235 row_newbcast:2 row_mask:0xf bank_mask:0xf
	v_mov_b32_e32 v147, v57
	v_fmac_f32_dpp v6, v248, v4 row_newbcast:4 row_mask:0xf bank_mask:0xf
	v_fmac_f32_dpp v147, v248, v2 row_newbcast:3 row_mask:0xf bank_mask:0xf
	v_fmac_f32_dpp v8, v249, v71 row_newbcast:0 row_mask:0xf bank_mask:0xf
	v_mov_b32_e32 v9, v57
	v_pk_add_f32 v[6:7], v[6:7], v[146:147]
	v_mov_b32_e32 v146, v57
	v_fmac_f32_dpp v146, v249, v234 row_newbcast:1 row_mask:0xf bank_mask:0xf
	v_pk_add_f32 v[6:7], v[6:7], v[6:7] op_sel:[0,1] op_sel_hi:[1,0]
	v_fmac_f32_dpp v9, v249, v235 row_newbcast:2 row_mask:0xf bank_mask:0xf
	v_mov_b32_e32 v147, v57
	v_fmac_f32_dpp v8, v249, v4 row_newbcast:4 row_mask:0xf bank_mask:0xf
	v_fmac_f32_dpp v146, v249, v6 row_newbcast:5 row_mask:0xf bank_mask:0xf
	v_fmac_f32_dpp v147, v249, v2 row_newbcast:3 row_mask:0xf bank_mask:0xf
	v_add_u32_e32 v1, 0x8e00, v208
	v_pk_add_f32 v[8:9], v[8:9], v[146:147]
	v_mov_b32_e32 v146, v57
	v_mov_b32_e32 v11, v57
	s_nop 0
	s_waitcnt lgkmcnt(0)
; #define LAS __attribute__((address_space(3)))
; __device__ __forceinline__ void dn_prep_item(const Args& a, LAS unsigned char* lds, int item, int tid, int wave, int lane, int& cwh, int next_item) {
;     ...
;         { const LAS float* lrow = Lm + (lane & 15);
; #pragma unroll
;         for (int i = 1; i < 64; ++i) { float sa[4] = { x[i], 0.f, 0.f, 0.f };
;             int lr[4];
; #pragma unroll
;             for (int g = 0; g < (i + 15) / 16; ++g) lr[g] = __float_as_int(lrow[i * 68 + 16 * g]);
; #pragma unroll
;             for (int j = 0; j < i; ++j) { fmac_rowbcast_sel(sa[j & 3], lr[j >> 4], x[j], j); }
;             x[i] = (sa[0] + sa[1]) + (sa[2] + sa[3]); } }
	v_add_u32_e32 v254, 0x9000, v208
	ds_read2_b32 v[252:253], v254 offset0:100 offset1:168
	v_fmac_f32_dpp v10, v250, v71 row_newbcast:0 row_mask:0xf bank_mask:0xf
	v_fmac_f32_dpp v146, v250, v234 row_newbcast:1 row_mask:0xf bank_mask:0xf
	v_fmac_f32_dpp v11, v250, v235 row_newbcast:2 row_mask:0xf bank_mask:0xf
	v_pk_add_f32 v[8:9], v[8:9], v[8:9] op_sel:[0,1] op_sel_hi:[1,0]
	v_mov_b32_e32 v147, v57
	v_fmac_f32_dpp v10, v250, v4 row_newbcast:4 row_mask:0xf bank_mask:0xf
	v_fmac_f32_dpp v146, v250, v6 row_newbcast:5 row_mask:0xf bank_mask:0xf
	v_fmac_f32_dpp v11, v250, v8 row_newbcast:6 row_mask:0xf bank_mask:0xf
	v_fmac_f32_dpp v147, v250, v2 row_newbcast:3 row_mask:0xf bank_mask:0xf
	v_mov_b32_e32 v13, v57
	v_pk_add_f32 v[10:11], v[10:11], v[146:147]
	v_mov_b32_e32 v146, v57
	v_fmac_f32_dpp v12, v251, v71 row_newbcast:0 row_mask:0xf bank_mask:0xf
	v_fmac_f32_dpp v146, v251, v234 row_newbcast:1 row_mask:0xf bank_mask:0xf
	v_fmac_f32_dpp v13, v251, v235 row_newbcast:2 row_mask:0xf bank_mask:0xf
	v_mov_b32_e32 v147, v57
	v_fmac_f32_dpp v147, v251, v2 row_newbcast:3 row_mask:0xf bank_mask:0xf
	v_fmac_f32_dpp v12, v251, v4 row_newbcast:4 row_mask:0xf bank_mask:0xf
	v_fmac_f32_dpp v146, v251, v6 row_newbcast:5 row_mask:0xf bank_mask:0xf
	v_add_u32_e32 v1, 0x9000, v208
	v_fmac_f32_dpp v13, v251, v8 row_newbcast:6 row_mask:0xf bank_mask:0xf
	v_lshlrev_b32_e32 v0, 16, v15
	v_pk_add_f32 v[10:11], v[10:11], v[10:11] op_sel:[0,1] op_sel_hi:[1,0]
	s_nop 0
	v_fmac_f32_dpp v147, v251, v10 row_newbcast:7 row_mask:0xf bank_mask:0xf
	s_waitcnt lgkmcnt(0)
	v_add_u32_e32 v254, 0x9200, v208
	ds_read2_b32 v[242:243], v254 offset0:108 offset1:176
	v_fmac_f32_dpp v14, v252, v71 row_newbcast:0 row_mask:0xf bank_mask:0xf
	v_mov_b32_e32 v15, v57
	v_pk_add_f32 v[12:13], v[12:13], v[146:147]
	v_mov_b32_e32 v146, v57
	v_fmac_f32_dpp v146, v252, v234 row_newbcast:1 row_mask:0xf bank_mask:0xf
	v_fmac_f32_dpp v15, v252, v235 row_newbcast:2 row_mask:0xf bank_mask:0xf
	v_mov_b32_e32 v147, v57
	v_fmac_f32_dpp v14, v252, v4 row_newbcast:4 row_mask:0xf bank_mask:0xf
	v_pk_add_f32 v[12:13], v[12:13], v[12:13] op_sel:[0,1] op_sel_hi:[1,0]
	v_fmac_f32_dpp v147, v252, v2 row_newbcast:3 row_mask:0xf bank_mask:0xf
	v_fmac_f32_dpp v146, v252, v6 row_newbcast:5 row_mask:0xf bank_mask:0xf
	v_fmac_f32_dpp v15, v252, v8 row_newbcast:6 row_mask:0xf bank_mask:0xf
	v_fmac_f32_dpp v18, v253, v71 row_newbcast:0 row_mask:0xf bank_mask:0xf
	v_mov_b32_e32 v19, v57
	v_fmac_f32_dpp v14, v252, v12 row_newbcast:8 row_mask:0xf bank_mask:0xf
	v_fmac_f32_dpp v147, v252, v10 row_newbcast:7 row_mask:0xf bank_mask:0xf
	v_fmac_f32_dpp v19, v253, v235 row_newbcast:2 row_mask:0xf bank_mask:0xf
	v_fmac_f32_dpp v18, v253, v4 row_newbcast:4 row_mask:0xf bank_mask:0xf
	v_add_u32_e32 v1, 0x9200, v208
	v_pk_add_f32 v[14:15], v[14:15], v[146:147]
	v_mov_b32_e32 v146, v57
	v_fmac_f32_dpp v146, v253, v234 row_newbcast:1 row_mask:0xf bank_mask:0xf
	v_mov_b32_e32 v147, v57
	v_fmac_f32_dpp v146, v253, v6 row_newbcast:5 row_mask:0xf bank_mask:0xf
	v_pk_add_f32 v[14:15], v[14:15], v[14:15] op_sel:[0,1] op_sel_hi:[1,0]
	v_fmac_f32_dpp v147, v253, v2 row_newbcast:3 row_mask:0xf bank_mask:0xf
	v_fmac_f32_dpp v19, v253, v8 row_newbcast:6 row_mask:0xf bank_mask:0xf
	v_fmac_f32_dpp v18, v253, v12 row_newbcast:8 row_mask:0xf bank_mask:0xf
	v_mov_b32_e32 v21, v57
	v_fmac_f32_dpp v146, v253, v14 row_newbcast:9 row_mask:0xf bank_mask:0xf
	v_fmac_f32_dpp v147, v253, v10 row_newbcast:7 row_mask:0xf bank_mask:0xf
	s_nop 0
	v_pk_add_f32 v[18:19], v[18:19], v[146:147]
	v_mov_b32_e32 v146, v57
	s_waitcnt lgkmcnt(0)
	v_add_u32_e32 v254, 0x9400, v208
	ds_read2_b32 v[246:247], v254 offset0:116 offset1:184
	v_fmac_f32_dpp v20, v242, v71 row_newbcast:0 row_mask:0xf bank_mask:0xf
	v_fmac_f32_dpp v146, v242, v234 row_newbcast:1 row_mask:0xf bank_mask:0xf
	v_fmac_f32_dpp v21, v242, v235 row_newbcast:2 row_mask:0xf bank_mask:0xf
	v_mov_b32_e32 v147, v57
	v_fmac_f32_dpp v20, v242, v4 row_newbcast:4 row_mask:0xf bank_mask:0xf
	v_fmac_f32_dpp v146, v242, v6 row_newbcast:5 row_mask:0xf bank_mask:0xf
	v_fmac_f32_dpp v21, v242, v8 row_newbcast:6 row_mask:0xf bank_mask:0xf
	v_pk_add_f32 v[18:19], v[18:19], v[18:19] op_sel:[0,1] op_sel_hi:[1,0]
	v_fmac_f32_dpp v147, v242, v2 row_newbcast:3 row_mask:0xf bank_mask:0xf
	v_fmac_f32_dpp v20, v242, v12 row_newbcast:8 row_mask:0xf bank_mask:0xf
	v_fmac_f32_dpp v146, v242, v14 row_newbcast:9 row_mask:0xf bank_mask:0xf
	v_mov_b32_e32 v23, v57
	v_fmac_f32_dpp v21, v242, v18 row_newbcast:10 row_mask:0xf bank_mask:0xf
	v_fmac_f32_dpp v147, v242, v10 row_newbcast:7 row_mask:0xf bank_mask:0xf
	v_fmac_f32_dpp v22, v243, v71 row_newbcast:0 row_mask:0xf bank_mask:0xf
	v_fmac_f32_dpp v23, v243, v235 row_newbcast:2 row_mask:0xf bank_mask:0xf
	v_add_u32_e32 v1, 0x9400, v208
	v_pk_add_f32 v[20:21], v[20:21], v[146:147]
	v_mov_b32_e32 v146, v57
	v_fmac_f32_dpp v146, v243, v234 row_newbcast:1 row_mask:0xf bank_mask:0xf
	v_mov_b32_e32 v147, v57
	v_fmac_f32_dpp v147, v243, v2 row_newbcast:3 row_mask:0xf bank_mask:0xf
	v_fmac_f32_dpp v22, v243, v4 row_newbcast:4 row_mask:0xf bank_mask:0xf
	v_fmac_f32_dpp v146, v243, v6 row_newbcast:5 row_mask:0xf bank_mask:0xf
	v_fmac_f32_dpp v23, v243, v8 row_newbcast:6 row_mask:0xf bank_mask:0xf
	v_pk_add_f32 v[20:21], v[20:21], v[20:21] op_sel:[0,1] op_sel_hi:[1,0]
	v_fmac_f32_dpp v147, v243, v10 row_newbcast:7 row_mask:0xf bank_mask:0xf
	v_fmac_f32_dpp v22, v243, v12 row_newbcast:8 row_mask:0xf bank_mask:0xf
	v_fmac_f32_dpp v146, v243, v14 row_newbcast:9 row_mask:0xf bank_mask:0xf
	v_fmac_f32_dpp v23, v243, v18 row_newbcast:10 row_mask:0xf bank_mask:0xf
	s_nop 0
	v_fmac_f32_dpp v147, v243, v20 row_newbcast:11 row_mask:0xf bank_mask:0xf
	s_waitcnt lgkmcnt(0)
; #define LAS __attribute__((address_space(3)))
; __device__ __forceinline__ void dn_prep_item(const Args& a, LAS unsigned char* lds, int item, int tid, int wave, int lane, int& cwh, int next_item) {
;     ...
;         { const LAS float* lrow = Lm + (lane & 15);
; #pragma unroll
;         for (int i = 1; i < 64; ++i) { float sa[4] = { x[i], 0.f, 0.f, 0.f };
;             int lr[4];
; #pragma unroll
;             for (int g = 0; g < (i + 15) / 16; ++g) lr[g] = __float_as_int(lrow[i * 68 + 16 * g]);
; #pragma unroll
;             for (int j = 0; j < i; ++j) { fmac_rowbcast_sel(sa[j & 3], lr[j >> 4], x[j], j); }
;             x[i] = (sa[0] + sa[1]) + (sa[2] + sa[3]); } }
	v_add_u32_e32 v254, 0x9600, v208
	ds_read2_b32 v[248:249], v254 offset0:124 offset1:192
	v_fmac_f32_dpp v24, v246, v71 row_newbcast:0 row_mask:0xf bank_mask:0xf
	v_mov_b32_e32 v25, v57
	v_pk_add_f32 v[22:23], v[22:23], v[146:147]
	v_mov_b32_e32 v146, v57
	v_fmac_f32_dpp v146, v246, v234 row_newbcast:1 row_mask:0xf bank_mask:0xf
	v_fmac_f32_dpp v25, v246, v235 row_newbcast:2 row_mask:0xf bank_mask:0xf
	v_mov_b32_e32 v147, v57
	v_fmac_f32_dpp v24, v246, v4 row_newbcast:4 row_mask:0xf bank_mask:0xf
	v_fmac_f32_dpp v147, v246, v2 row_newbcast:3 row_mask:0xf bank_mask:0xf
	v_fmac_f32_dpp v146, v246, v6 row_newbcast:5 row_mask:0xf bank_mask:0xf
	v_fmac_f32_dpp v25, v246, v8 row_newbcast:6 row_mask:0xf bank_mask:0xf
	v_pk_add_f32 v[22:23], v[22:23], v[22:23] op_sel:[0,1] op_sel_hi:[1,0]
	v_fmac_f32_dpp v24, v246, v12 row_newbcast:8 row_mask:0xf bank_mask:0xf
	v_fmac_f32_dpp v147, v246, v10 row_newbcast:7 row_mask:0xf bank_mask:0xf
	v_fmac_f32_dpp v146, v246, v14 row_newbcast:9 row_mask:0xf bank_mask:0xf
	v_fmac_f32_dpp v25, v246, v18 row_newbcast:10 row_mask:0xf bank_mask:0xf
	v_fmac_f32_dpp v26, v247, v71 row_newbcast:0 row_mask:0xf bank_mask:0xf
	v_mov_b32_e32 v27, v57
	v_fmac_f32_dpp v24, v246, v22 row_newbcast:12 row_mask:0xf bank_mask:0xf
	v_fmac_f32_dpp v147, v246, v20 row_newbcast:11 row_mask:0xf bank_mask:0xf
	v_fmac_f32_dpp v27, v247, v235 row_newbcast:2 row_mask:0xf bank_mask:0xf
	v_fmac_f32_dpp v26, v247, v4 row_newbcast:4 row_mask:0xf bank_mask:0xf
	v_add_u32_e32 v1, 0x9600, v208
	v_pk_add_f32 v[24:25], v[24:25], v[146:147]
	v_mov_b32_e32 v146, v57
	v_fmac_f32_dpp v146, v247, v234 row_newbcast:1 row_mask:0xf bank_mask:0xf
	v_mov_b32_e32 v147, v57
	v_fmac_f32_dpp v146, v247, v6 row_newbcast:5 row_mask:0xf bank_mask:0xf
	v_fmac_f32_dpp v147, v247, v2 row_newbcast:3 row_mask:0xf bank_mask:0xf
	v_fmac_f32_dpp v27, v247, v8 row_newbcast:6 row_mask:0xf bank_mask:0xf
	v_fmac_f32_dpp v26, v247, v12 row_newbcast:8 row_mask:0xf bank_mask:0xf
	v_pk_add_f32 v[24:25], v[24:25], v[24:25] op_sel:[0,1] op_sel_hi:[1,0]
	v_fmac_f32_dpp v146, v247, v14 row_newbcast:9 row_mask:0xf bank_mask:0xf
	v_fmac_f32_dpp v147, v247, v10 row_newbcast:7 row_mask:0xf bank_mask:0xf
	v_fmac_f32_dpp v27, v247, v18 row_newbcast:10 row_mask:0xf bank_mask:0xf
	v_fmac_f32_dpp v26, v247, v22 row_newbcast:12 row_mask:0xf bank_mask:0xf
	v_mov_b32_e32 v31, v57
	v_fmac_f32_dpp v146, v247, v24 row_newbcast:13 row_mask:0xf bank_mask:0xf
	v_fmac_f32_dpp v147, v247, v20 row_newbcast:11 row_mask:0xf bank_mask:0xf
	s_nop 0
	v_pk_add_f32 v[26:27], v[26:27], v[146:147]
	v_mov_b32_e32 v146, v57
	s_waitcnt lgkmcnt(0)
	v_add_u32_e32 v254, 0x9800, v208
	ds_read2_b32 v[250:251], v254 offset0:132 offset1:148
	v_fmac_f32_dpp v30, v248, v71 row_newbcast:0 row_mask:0xf bank_mask:0xf
	v_fmac_f32_dpp v146, v248, v234 row_newbcast:1 row_mask:0xf bank_mask:0xf
	v_fmac_f32_dpp v31, v248, v235 row_newbcast:2 row_mask:0xf bank_mask:0xf
	v_mov_b32_e32 v147, v57
	v_fmac_f32_dpp v30, v248, v4 row_newbcast:4 row_mask:0xf bank_mask:0xf
	v_fmac_f32_dpp v146, v248, v6 row_newbcast:5 row_mask:0xf bank_mask:0xf
	v_fmac_f32_dpp v31, v248, v8 row_newbcast:6 row_mask:0xf bank_mask:0xf
	v_fmac_f32_dpp v147, v248, v2 row_newbcast:3 row_mask:0xf bank_mask:0xf
	v_pk_add_f32 v[26:27], v[26:27], v[26:27] op_sel:[0,1] op_sel_hi:[1,0]
	v_fmac_f32_dpp v30, v248, v12 row_newbcast:8 row_mask:0xf bank_mask:0xf
	v_fmac_f32_dpp v146, v248, v14 row_newbcast:9 row_mask:0xf bank_mask:0xf
	v_fmac_f32_dpp v31, v248, v18 row_newbcast:10 row_mask:0xf bank_mask:0xf
	v_fmac_f32_dpp v147, v248, v10 row_newbcast:7 row_mask:0xf bank_mask:0xf
	v_mov_b32_e32 v33, v57
	v_fmac_f32_dpp v30, v248, v22 row_newbcast:12 row_mask:0xf bank_mask:0xf
	v_fmac_f32_dpp v146, v248, v24 row_newbcast:13 row_mask:0xf bank_mask:0xf
	v_fmac_f32_dpp v31, v248, v26 row_newbcast:14 row_mask:0xf bank_mask:0xf
	v_fmac_f32_dpp v147, v248, v20 row_newbcast:11 row_mask:0xf bank_mask:0xf
	v_fmac_f32_dpp v32, v249, v71 row_newbcast:0 row_mask:0xf bank_mask:0xf
	v_fmac_f32_dpp v33, v249, v235 row_newbcast:2 row_mask:0xf bank_mask:0xf
	v_add_u32_e32 v1, 0x9800, v208
	v_pk_add_f32 v[30:31], v[30:31], v[146:147]
	v_mov_b32_e32 v146, v57
	v_fmac_f32_dpp v146, v249, v234 row_newbcast:1 row_mask:0xf bank_mask:0xf
	v_mov_b32_e32 v147, v57
	v_fmac_f32_dpp v147, v249, v2 row_newbcast:3 row_mask:0xf bank_mask:0xf
	v_fmac_f32_dpp v32, v249, v4 row_newbcast:4 row_mask:0xf bank_mask:0xf
	v_fmac_f32_dpp v146, v249, v6 row_newbcast:5 row_mask:0xf bank_mask:0xf
	v_fmac_f32_dpp v33, v249, v8 row_newbcast:6 row_mask:0xf bank_mask:0xf
	v_pk_add_f32 v[30:31], v[30:31], v[30:31] op_sel:[0,1] op_sel_hi:[1,0]
	v_fmac_f32_dpp v147, v249, v10 row_newbcast:7 row_mask:0xf bank_mask:0xf
	v_fmac_f32_dpp v32, v249, v12 row_newbcast:8 row_mask:0xf bank_mask:0xf
	v_fmac_f32_dpp v146, v249, v14 row_newbcast:9 row_mask:0xf bank_mask:0xf
	v_fmac_f32_dpp v33, v249, v18 row_newbcast:10 row_mask:0xf bank_mask:0xf
	s_nop 0
	v_fmac_f32_dpp v147, v249, v20 row_newbcast:11 row_mask:0xf bank_mask:0xf
	v_fmac_f32_dpp v32, v249, v22 row_newbcast:12 row_mask:0xf bank_mask:0xf
	v_fmac_f32_dpp v146, v249, v24 row_newbcast:13 row_mask:0xf bank_mask:0xf
	v_fmac_f32_dpp v33, v249, v26 row_newbcast:14 row_mask:0xf bank_mask:0xf
	s_waitcnt lgkmcnt(0)
; #define LAS __attribute__((address_space(3)))
; __device__ __forceinline__ void dn_prep_item(const Args& a, LAS unsigned char* lds, int item, int tid, int wave, int lane, int& cwh, int next_item) {
;     ...
;         { const LAS float* lrow = Lm + (lane & 15);
; #pragma unroll
;         for (int i = 1; i < 64; ++i) { float sa[4] = { x[i], 0.f, 0.f, 0.f };
;             int lr[4];
; #pragma unroll
;             for (int g = 0; g < (i + 15) / 16; ++g) lr[g] = __float_as_int(lrow[i * 68 + 16 * g]);
; #pragma unroll
;             for (int j = 0; j < i; ++j) { fmac_rowbcast_sel(sa[j & 3], lr[j >> 4], x[j], j); }
;             x[i] = (sa[0] + sa[1]) + (sa[2] + sa[3]); } }
	v_add_u32_e32 v254, 0x9800, v208
	ds_read2_b32 v[252:253], v254 offset0:200 offset1:216
	v_fmac_f32_dpp v34, v250, v71 row_newbcast:0 row_mask:0xf bank_mask:0xf
	v_mov_b32_e32 v35, v57
	v_fmac_f32_dpp v147, v249, v30 row_newbcast:15 row_mask:0xf bank_mask:0xf
	v_fmac_f32_dpp v35, v250, v235 row_newbcast:2 row_mask:0xf bank_mask:0xf
	v_fmac_f32_dpp v34, v250, v4 row_newbcast:4 row_mask:0xf bank_mask:0xf
	s_nop 0
	v_pk_add_f32 v[32:33], v[32:33], v[146:147]
	v_mov_b32_e32 v146, v57
	v_fmac_f32_dpp v146, v250, v234 row_newbcast:1 row_mask:0xf bank_mask:0xf
	v_mov_b32_e32 v147, v57
	v_fmac_f32_dpp v147, v250, v2 row_newbcast:3 row_mask:0xf bank_mask:0xf
	v_fmac_f32_dpp v146, v250, v6 row_newbcast:5 row_mask:0xf bank_mask:0xf
	v_fmac_f32_dpp v35, v250, v8 row_newbcast:6 row_mask:0xf bank_mask:0xf
	v_fmac_f32_dpp v34, v250, v12 row_newbcast:8 row_mask:0xf bank_mask:0xf
	v_pk_add_f32 v[32:33], v[32:33], v[32:33] op_sel:[0,1] op_sel_hi:[1,0]
	v_fmac_f32_dpp v147, v250, v10 row_newbcast:7 row_mask:0xf bank_mask:0xf
	v_fmac_f32_dpp v146, v250, v14 row_newbcast:9 row_mask:0xf bank_mask:0xf
	v_fmac_f32_dpp v35, v250, v18 row_newbcast:10 row_mask:0xf bank_mask:0xf
	v_fmac_f32_dpp v34, v250, v22 row_newbcast:12 row_mask:0xf bank_mask:0xf
	s_waitcnt lgkmcnt(0)
	v_add_u32_e32 v254, 0x9c00, v208
	ds_read2_b32 v[242:243], v254 offset0:12 offset1:28
	v_fmac_f32_dpp v38, v252, v71 row_newbcast:0 row_mask:0xf bank_mask:0xf
	v_mov_b32_e32 v39, v57
	v_fmac_f32_dpp v147, v250, v20 row_newbcast:11 row_mask:0xf bank_mask:0xf
	v_fmac_f32_dpp v146, v250, v24 row_newbcast:13 row_mask:0xf bank_mask:0xf
	v_fmac_f32_dpp v35, v250, v26 row_newbcast:14 row_mask:0xf bank_mask:0xf
	v_fmac_f32_dpp v34, v251, v32 row_newbcast:0 row_mask:0xf bank_mask:0xf
	v_fmac_f32_dpp v39, v252, v235 row_newbcast:2 row_mask:0xf bank_mask:0xf
	v_fmac_f32_dpp v38, v252, v4 row_newbcast:4 row_mask:0xf bank_mask:0xf
	s_nop 0
	v_fmac_f32_dpp v147, v250, v30 row_newbcast:15 row_mask:0xf bank_mask:0xf
	v_add_u32_e32 v1, 0x9c00, v208
	v_pk_add_f32 v[34:35], v[34:35], v[146:147]
	v_mov_b32_e32 v146, v57
	v_fmac_f32_dpp v146, v252, v234 row_newbcast:1 row_mask:0xf bank_mask:0xf
	v_mov_b32_e32 v147, v57
	v_fmac_f32_dpp v146, v252, v6 row_newbcast:5 row_mask:0xf bank_mask:0xf
	v_fmac_f32_dpp v147, v252, v2 row_newbcast:3 row_mask:0xf bank_mask:0xf
	v_fmac_f32_dpp v39, v252, v8 row_newbcast:6 row_mask:0xf bank_mask:0xf
	v_fmac_f32_dpp v38, v252, v12 row_newbcast:8 row_mask:0xf bank_mask:0xf
	v_pk_add_f32 v[34:35], v[34:35], v[34:35] op_sel:[0,1] op_sel_hi:[1,0]
	v_fmac_f32_dpp v146, v252, v14 row_newbcast:9 row_mask:0xf bank_mask:0xf
	v_fmac_f32_dpp v147, v252, v10 row_newbcast:7 row_mask:0xf bank_mask:0xf
	v_fmac_f32_dpp v39, v252, v18 row_newbcast:10 row_mask:0xf bank_mask:0xf
	v_fmac_f32_dpp v38, v252, v22 row_newbcast:12 row_mask:0xf bank_mask:0xf
	v_mov_b32_e32 v41, v57
	v_fmac_f32_dpp v146, v252, v24 row_newbcast:13 row_mask:0xf bank_mask:0xf
	v_fmac_f32_dpp v147, v252, v20 row_newbcast:11 row_mask:0xf bank_mask:0xf
	v_fmac_f32_dpp v39, v252, v26 row_newbcast:14 row_mask:0xf bank_mask:0xf
	v_fmac_f32_dpp v38, v253, v32 row_newbcast:0 row_mask:0xf bank_mask:0xf
	s_nop 0
	v_fmac_f32_dpp v146, v253, v34 row_newbcast:1 row_mask:0xf bank_mask:0xf
	v_fmac_f32_dpp v147, v252, v30 row_newbcast:15 row_mask:0xf bank_mask:0xf
	s_waitcnt lgkmcnt(0)
	v_add_u32_e32 v254, 0x9c00, v208
	ds_read2_b32 v[246:247], v254 offset0:80 offset1:96
	v_fmac_f32_dpp v40, v242, v71 row_newbcast:0 row_mask:0xf bank_mask:0xf
	v_fmac_f32_dpp v41, v242, v235 row_newbcast:2 row_mask:0xf bank_mask:0xf
	v_mov_b32_e32 v43, v57
	v_pk_add_f32 v[38:39], v[38:39], v[146:147]
	v_mov_b32_e32 v146, v57
	v_fmac_f32_dpp v146, v242, v234 row_newbcast:1 row_mask:0xf bank_mask:0xf
	v_mov_b32_e32 v147, v57
	v_fmac_f32_dpp v40, v242, v4 row_newbcast:4 row_mask:0xf bank_mask:0xf
	v_fmac_f32_dpp v146, v242, v6 row_newbcast:5 row_mask:0xf bank_mask:0xf
	v_fmac_f32_dpp v41, v242, v8 row_newbcast:6 row_mask:0xf bank_mask:0xf
	v_fmac_f32_dpp v147, v242, v2 row_newbcast:3 row_mask:0xf bank_mask:0xf
	v_pk_add_f32 v[38:39], v[38:39], v[38:39] op_sel:[0,1] op_sel_hi:[1,0]
	v_fmac_f32_dpp v40, v242, v12 row_newbcast:8 row_mask:0xf bank_mask:0xf
	v_fmac_f32_dpp v146, v242, v14 row_newbcast:9 row_mask:0xf bank_mask:0xf
	v_fmac_f32_dpp v41, v242, v18 row_newbcast:10 row_mask:0xf bank_mask:0xf
	v_fmac_f32_dpp v147, v242, v10 row_newbcast:7 row_mask:0xf bank_mask:0xf
	s_nop 0
	v_fmac_f32_dpp v40, v242, v22 row_newbcast:12 row_mask:0xf bank_mask:0xf
	v_fmac_f32_dpp v146, v242, v24 row_newbcast:13 row_mask:0xf bank_mask:0xf
	v_fmac_f32_dpp v41, v242, v26 row_newbcast:14 row_mask:0xf bank_mask:0xf
	v_fmac_f32_dpp v147, v242, v20 row_newbcast:11 row_mask:0xf bank_mask:0xf
	s_waitcnt lgkmcnt(0)
	v_add_u32_e32 v254, 0x9c00, v208
	ds_read2_b32 v[248:249], v254 offset0:148 offset1:164
	v_fmac_f32_dpp v42, v246, v71 row_newbcast:0 row_mask:0xf bank_mask:0xf
	v_fmac_f32_dpp v43, v246, v235 row_newbcast:2 row_mask:0xf bank_mask:0xf
	v_fmac_f32_dpp v40, v243, v32 row_newbcast:0 row_mask:0xf bank_mask:0xf
	v_fmac_f32_dpp v146, v243, v34 row_newbcast:1 row_mask:0xf bank_mask:0xf
	v_fmac_f32_dpp v41, v243, v38 row_newbcast:2 row_mask:0xf bank_mask:0xf
	v_fmac_f32_dpp v147, v242, v30 row_newbcast:15 row_mask:0xf bank_mask:0xf
	s_nop 0
	v_fmac_f32_dpp v42, v246, v4 row_newbcast:4 row_mask:0xf bank_mask:0xf
	v_fmac_f32_dpp v43, v246, v8 row_newbcast:6 row_mask:0xf bank_mask:0xf
	s_nop 0
	v_pk_add_f32 v[40:41], v[40:41], v[146:147]
	v_mov_b32_e32 v146, v57
	v_fmac_f32_dpp v146, v246, v234 row_newbcast:1 row_mask:0xf bank_mask:0xf
	v_mov_b32_e32 v147, v57
	v_fmac_f32_dpp v147, v246, v2 row_newbcast:3 row_mask:0xf bank_mask:0xf
	v_fmac_f32_dpp v146, v246, v6 row_newbcast:5 row_mask:0xf bank_mask:0xf
	v_fmac_f32_dpp v42, v246, v12 row_newbcast:8 row_mask:0xf bank_mask:0xf
	v_fmac_f32_dpp v43, v246, v18 row_newbcast:10 row_mask:0xf bank_mask:0xf
	v_pk_add_f32 v[40:41], v[40:41], v[40:41] op_sel:[0,1] op_sel_hi:[1,0]
	v_fmac_f32_dpp v147, v246, v10 row_newbcast:7 row_mask:0xf bank_mask:0xf
	v_fmac_f32_dpp v146, v246, v14 row_newbcast:9 row_mask:0xf bank_mask:0xf
	v_fmac_f32_dpp v42, v246, v22 row_newbcast:12 row_mask:0xf bank_mask:0xf
	v_fmac_f32_dpp v43, v246, v26 row_newbcast:14 row_mask:0xf bank_mask:0xf
	s_waitcnt lgkmcnt(0)
; #define LAS __attribute__((address_space(3)))
; __device__ __forceinline__ void dn_prep_item(const Args& a, LAS unsigned char* lds, int item, int tid, int wave, int lane, int& cwh, int next_item) {
;     ...
;         { const LAS float* lrow = Lm + (lane & 15);
; #pragma unroll
;         for (int i = 1; i < 64; ++i) { float sa[4] = { x[i], 0.f, 0.f, 0.f };
;             int lr[4];
; #pragma unroll
;             for (int g = 0; g < (i + 15) / 16; ++g) lr[g] = __float_as_int(lrow[i * 68 + 16 * g]);
; #pragma unroll
;             for (int j = 0; j < i; ++j) { fmac_rowbcast_sel(sa[j & 3], lr[j >> 4], x[j], j); }
;             x[i] = (sa[0] + sa[1]) + (sa[2] + sa[3]); } }
	v_add_u32_e32 v254, 0x9c00, v208
	ds_read2_b32 v[250:251], v254 offset0:216 offset1:232
	v_fmac_f32_dpp v46, v248, v71 row_newbcast:0 row_mask:0xf bank_mask:0xf
	v_mov_b32_e32 v47, v57
	v_fmac_f32_dpp v147, v246, v20 row_newbcast:11 row_mask:0xf bank_mask:0xf
	v_fmac_f32_dpp v146, v246, v24 row_newbcast:13 row_mask:0xf bank_mask:0xf
	v_fmac_f32_dpp v42, v247, v32 row_newbcast:0 row_mask:0xf bank_mask:0xf
	v_fmac_f32_dpp v43, v247, v38 row_newbcast:2 row_mask:0xf bank_mask:0xf
	v_fmac_f32_dpp v47, v248, v235 row_newbcast:2 row_mask:0xf bank_mask:0xf
	v_fmac_f32_dpp v46, v248, v4 row_newbcast:4 row_mask:0xf bank_mask:0xf
	s_nop 0
	v_fmac_f32_dpp v147, v246, v30 row_newbcast:15 row_mask:0xf bank_mask:0xf
	v_fmac_f32_dpp v146, v247, v34 row_newbcast:1 row_mask:0xf bank_mask:0xf
	v_mov_b32_e32 v73, v57
	v_fmac_f32_dpp v147, v247, v40 row_newbcast:3 row_mask:0xf bank_mask:0xf
	v_fmac_f32_dpp v47, v248, v8 row_newbcast:6 row_mask:0xf bank_mask:0xf
	v_fmac_f32_dpp v46, v248, v12 row_newbcast:8 row_mask:0xf bank_mask:0xf
	s_nop 0
	v_pk_add_f32 v[42:43], v[42:43], v[146:147]
	v_mov_b32_e32 v146, v57
	v_fmac_f32_dpp v146, v248, v234 row_newbcast:1 row_mask:0xf bank_mask:0xf
	v_mov_b32_e32 v147, v57
	v_fmac_f32_dpp v147, v248, v2 row_newbcast:3 row_mask:0xf bank_mask:0xf
	v_fmac_f32_dpp v146, v248, v6 row_newbcast:5 row_mask:0xf bank_mask:0xf
	v_fmac_f32_dpp v47, v248, v18 row_newbcast:10 row_mask:0xf bank_mask:0xf
	v_fmac_f32_dpp v46, v248, v22 row_newbcast:12 row_mask:0xf bank_mask:0xf
	v_pk_add_f32 v[42:43], v[42:43], v[42:43] op_sel:[0,1] op_sel_hi:[1,0]
	v_fmac_f32_dpp v147, v248, v10 row_newbcast:7 row_mask:0xf bank_mask:0xf
	v_fmac_f32_dpp v146, v248, v14 row_newbcast:9 row_mask:0xf bank_mask:0xf
	v_fmac_f32_dpp v47, v248, v26 row_newbcast:14 row_mask:0xf bank_mask:0xf
	v_fmac_f32_dpp v46, v249, v32 row_newbcast:0 row_mask:0xf bank_mask:0xf
	s_waitcnt lgkmcnt(0)
	v_add_u32_e32 v254, 0xa000, v208
	ds_read2_b32 v[252:253], v254 offset0:28 offset1:44
	v_fmac_f32_dpp v72, v250, v71 row_newbcast:0 row_mask:0xf bank_mask:0xf
	v_fmac_f32_dpp v73, v250, v235 row_newbcast:2 row_mask:0xf bank_mask:0xf
	v_fmac_f32_dpp v147, v248, v20 row_newbcast:11 row_mask:0xf bank_mask:0xf
	v_fmac_f32_dpp v146, v248, v24 row_newbcast:13 row_mask:0xf bank_mask:0xf
	v_fmac_f32_dpp v47, v249, v38 row_newbcast:2 row_mask:0xf bank_mask:0xf
	v_fmac_f32_dpp v46, v249, v42 row_newbcast:4 row_mask:0xf bank_mask:0xf
	s_nop 0
	v_fmac_f32_dpp v72, v250, v4 row_newbcast:4 row_mask:0xf bank_mask:0xf
	v_fmac_f32_dpp v73, v250, v8 row_newbcast:6 row_mask:0xf bank_mask:0xf
	v_fmac_f32_dpp v147, v248, v30 row_newbcast:15 row_mask:0xf bank_mask:0xf
	v_fmac_f32_dpp v146, v249, v34 row_newbcast:1 row_mask:0xf bank_mask:0xf
	v_add_u32_e32 v1, 0xa000, v208
	v_fmac_f32_dpp v147, v249, v40 row_newbcast:3 row_mask:0xf bank_mask:0xf
	v_fmac_f32_dpp v72, v250, v12 row_newbcast:8 row_mask:0xf bank_mask:0xf
	v_fmac_f32_dpp v73, v250, v18 row_newbcast:10 row_mask:0xf bank_mask:0xf
	v_mov_b32_e32 v75, v57
	v_pk_add_f32 v[46:47], v[46:47], v[146:147]
	v_mov_b32_e32 v146, v57
	v_fmac_f32_dpp v146, v250, v234 row_newbcast:1 row_mask:0xf bank_mask:0xf
	v_mov_b32_e32 v147, v57
	v_fmac_f32_dpp v146, v250, v6 row_newbcast:5 row_mask:0xf bank_mask:0xf
	v_fmac_f32_dpp v147, v250, v2 row_newbcast:3 row_mask:0xf bank_mask:0xf
	v_fmac_f32_dpp v72, v250, v22 row_newbcast:12 row_mask:0xf bank_mask:0xf
	v_fmac_f32_dpp v73, v250, v26 row_newbcast:14 row_mask:0xf bank_mask:0xf
	v_pk_add_f32 v[46:47], v[46:47], v[46:47] op_sel:[0,1] op_sel_hi:[1,0]
	v_fmac_f32_dpp v146, v250, v14 row_newbcast:9 row_mask:0xf bank_mask:0xf
	v_fmac_f32_dpp v147, v250, v10 row_newbcast:7 row_mask:0xf bank_mask:0xf
	v_fmac_f32_dpp v72, v251, v32 row_newbcast:0 row_mask:0xf bank_mask:0xf
	v_fmac_f32_dpp v73, v251, v38 row_newbcast:2 row_mask:0xf bank_mask:0xf
	s_nop 0
	v_fmac_f32_dpp v146, v250, v24 row_newbcast:13 row_mask:0xf bank_mask:0xf
	v_fmac_f32_dpp v147, v250, v20 row_newbcast:11 row_mask:0xf bank_mask:0xf
	v_fmac_f32_dpp v72, v251, v42 row_newbcast:4 row_mask:0xf bank_mask:0xf
	s_waitcnt lgkmcnt(0)
	v_add_u32_e32 v254, 0xa000, v208
	ds_read2_b32 v[242:243], v254 offset0:96 offset1:112
	v_fmac_f32_dpp v74, v252, v71 row_newbcast:0 row_mask:0xf bank_mask:0xf
	v_fmac_f32_dpp v75, v252, v235 row_newbcast:2 row_mask:0xf bank_mask:0xf
	v_mov_b32_e32 v79, v57
	v_fmac_f32_dpp v146, v251, v34 row_newbcast:1 row_mask:0xf bank_mask:0xf
	v_fmac_f32_dpp v147, v250, v30 row_newbcast:15 row_mask:0xf bank_mask:0xf
	v_fmac_f32_dpp v74, v252, v4 row_newbcast:4 row_mask:0xf bank_mask:0xf
	v_fmac_f32_dpp v75, v252, v8 row_newbcast:6 row_mask:0xf bank_mask:0xf
	v_mov_b32_e32 v81, v57
	v_fmac_f32_dpp v146, v251, v46 row_newbcast:5 row_mask:0xf bank_mask:0xf
	v_fmac_f32_dpp v147, v251, v40 row_newbcast:3 row_mask:0xf bank_mask:0xf
	v_fmac_f32_dpp v74, v252, v12 row_newbcast:8 row_mask:0xf bank_mask:0xf
	v_fmac_f32_dpp v75, v252, v18 row_newbcast:10 row_mask:0xf bank_mask:0xf
	s_nop 0
	v_pk_add_f32 v[72:73], v[72:73], v[146:147]
	v_mov_b32_e32 v146, v57
	v_fmac_f32_dpp v146, v252, v234 row_newbcast:1 row_mask:0xf bank_mask:0xf
	v_mov_b32_e32 v147, v57
	v_fmac_f32_dpp v146, v252, v6 row_newbcast:5 row_mask:0xf bank_mask:0xf
	v_fmac_f32_dpp v147, v252, v2 row_newbcast:3 row_mask:0xf bank_mask:0xf
	v_fmac_f32_dpp v74, v252, v22 row_newbcast:12 row_mask:0xf bank_mask:0xf
	v_fmac_f32_dpp v75, v252, v26 row_newbcast:14 row_mask:0xf bank_mask:0xf
	v_pk_add_f32 v[72:73], v[72:73], v[72:73] op_sel:[0,1] op_sel_hi:[1,0]
	v_fmac_f32_dpp v146, v252, v14 row_newbcast:9 row_mask:0xf bank_mask:0xf
	v_fmac_f32_dpp v147, v252, v10 row_newbcast:7 row_mask:0xf bank_mask:0xf
	v_fmac_f32_dpp v74, v253, v32 row_newbcast:0 row_mask:0xf bank_mask:0xf
	v_fmac_f32_dpp v75, v253, v38 row_newbcast:2 row_mask:0xf bank_mask:0xf
	s_waitcnt lgkmcnt(0)
; #define LAS __attribute__((address_space(3)))
; __device__ __forceinline__ void dn_prep_item(const Args& a, LAS unsigned char* lds, int item, int tid, int wave, int lane, int& cwh, int next_item) {
;     ...
;         { const LAS float* lrow = Lm + (lane & 15);
; #pragma unroll
;         for (int i = 1; i < 64; ++i) { float sa[4] = { x[i], 0.f, 0.f, 0.f };
;             int lr[4];
; #pragma unroll
;             for (int g = 0; g < (i + 15) / 16; ++g) lr[g] = __float_as_int(lrow[i * 68 + 16 * g]);
; #pragma unroll
;             for (int j = 0; j < i; ++j) { fmac_rowbcast_sel(sa[j & 3], lr[j >> 4], x[j], j); }
;             x[i] = (sa[0] + sa[1]) + (sa[2] + sa[3]); } }
	v_add_u32_e32 v254, 0xa000, v208
	ds_read2_b32 v[246:247], v254 offset0:164 offset1:180
	v_fmac_f32_dpp v78, v242, v71 row_newbcast:0 row_mask:0xf bank_mask:0xf
	v_fmac_f32_dpp v79, v242, v235 row_newbcast:2 row_mask:0xf bank_mask:0xf
	v_fmac_f32_dpp v146, v252, v24 row_newbcast:13 row_mask:0xf bank_mask:0xf
	v_fmac_f32_dpp v147, v252, v20 row_newbcast:11 row_mask:0xf bank_mask:0xf
	v_fmac_f32_dpp v74, v253, v42 row_newbcast:4 row_mask:0xf bank_mask:0xf
	v_fmac_f32_dpp v75, v253, v72 row_newbcast:6 row_mask:0xf bank_mask:0xf
	s_nop 0
	v_fmac_f32_dpp v78, v242, v4 row_newbcast:4 row_mask:0xf bank_mask:0xf
	v_fmac_f32_dpp v79, v242, v8 row_newbcast:6 row_mask:0xf bank_mask:0xf
	v_fmac_f32_dpp v146, v253, v34 row_newbcast:1 row_mask:0xf bank_mask:0xf
	v_fmac_f32_dpp v147, v252, v30 row_newbcast:15 row_mask:0xf bank_mask:0xf
	v_mov_b32_e32 v85, v57
	v_fmac_f32_dpp v146, v253, v46 row_newbcast:5 row_mask:0xf bank_mask:0xf
	v_fmac_f32_dpp v147, v253, v40 row_newbcast:3 row_mask:0xf bank_mask:0xf
	v_fmac_f32_dpp v78, v242, v12 row_newbcast:8 row_mask:0xf bank_mask:0xf
	v_fmac_f32_dpp v79, v242, v18 row_newbcast:10 row_mask:0xf bank_mask:0xf
	s_nop 0
	v_pk_add_f32 v[74:75], v[74:75], v[146:147]
	v_mov_b32_e32 v146, v57
	v_fmac_f32_dpp v146, v242, v234 row_newbcast:1 row_mask:0xf bank_mask:0xf
	v_mov_b32_e32 v147, v57
	v_fmac_f32_dpp v147, v242, v2 row_newbcast:3 row_mask:0xf bank_mask:0xf
	v_fmac_f32_dpp v146, v242, v6 row_newbcast:5 row_mask:0xf bank_mask:0xf
	v_fmac_f32_dpp v78, v242, v22 row_newbcast:12 row_mask:0xf bank_mask:0xf
	v_fmac_f32_dpp v79, v242, v26 row_newbcast:14 row_mask:0xf bank_mask:0xf
	v_pk_add_f32 v[74:75], v[74:75], v[74:75] op_sel:[0,1] op_sel_hi:[1,0]
	v_fmac_f32_dpp v147, v242, v10 row_newbcast:7 row_mask:0xf bank_mask:0xf
	v_fmac_f32_dpp v146, v242, v14 row_newbcast:9 row_mask:0xf bank_mask:0xf
	v_fmac_f32_dpp v78, v243, v32 row_newbcast:0 row_mask:0xf bank_mask:0xf
	v_fmac_f32_dpp v79, v243, v38 row_newbcast:2 row_mask:0xf bank_mask:0xf
	s_waitcnt lgkmcnt(0)
	v_add_u32_e32 v254, 0xa000, v208
	ds_read2_b32 v[248:249], v254 offset0:232 offset1:248
	v_fmac_f32_dpp v80, v246, v71 row_newbcast:0 row_mask:0xf bank_mask:0xf
	v_fmac_f32_dpp v81, v246, v235 row_newbcast:2 row_mask:0xf bank_mask:0xf
	v_fmac_f32_dpp v147, v242, v20 row_newbcast:11 row_mask:0xf bank_mask:0xf
	v_fmac_f32_dpp v146, v242, v24 row_newbcast:13 row_mask:0xf bank_mask:0xf
	v_fmac_f32_dpp v78, v243, v42 row_newbcast:4 row_mask:0xf bank_mask:0xf
	v_fmac_f32_dpp v79, v243, v72 row_newbcast:6 row_mask:0xf bank_mask:0xf
	s_nop 0
	v_fmac_f32_dpp v80, v246, v4 row_newbcast:4 row_mask:0xf bank_mask:0xf
	v_fmac_f32_dpp v81, v246, v8 row_newbcast:6 row_mask:0xf bank_mask:0xf
	v_fmac_f32_dpp v147, v242, v30 row_newbcast:15 row_mask:0xf bank_mask:0xf
	v_fmac_f32_dpp v146, v243, v34 row_newbcast:1 row_mask:0xf bank_mask:0xf
	v_mov_b32_e32 v87, v57
	v_fmac_f32_dpp v147, v243, v40 row_newbcast:3 row_mask:0xf bank_mask:0xf
	v_fmac_f32_dpp v146, v243, v46 row_newbcast:5 row_mask:0xf bank_mask:0xf
	v_fmac_f32_dpp v80, v246, v12 row_newbcast:8 row_mask:0xf bank_mask:0xf
	v_fmac_f32_dpp v81, v246, v18 row_newbcast:10 row_mask:0xf bank_mask:0xf
	v_mov_b32_e32 v91, v57
	v_fmac_f32_dpp v147, v243, v74 row_newbcast:7 row_mask:0xf bank_mask:0xf
	v_fmac_f32_dpp v80, v246, v22 row_newbcast:12 row_mask:0xf bank_mask:0xf
	v_fmac_f32_dpp v81, v246, v26 row_newbcast:14 row_mask:0xf bank_mask:0xf
	s_nop 0
	v_pk_add_f32 v[78:79], v[78:79], v[146:147]
	v_mov_b32_e32 v146, v57
	v_fmac_f32_dpp v146, v246, v234 row_newbcast:1 row_mask:0xf bank_mask:0xf
	v_mov_b32_e32 v147, v57
	v_fmac_f32_dpp v147, v246, v2 row_newbcast:3 row_mask:0xf bank_mask:0xf
	v_fmac_f32_dpp v146, v246, v6 row_newbcast:5 row_mask:0xf bank_mask:0xf
	v_fmac_f32_dpp v80, v247, v32 row_newbcast:0 row_mask:0xf bank_mask:0xf
	v_fmac_f32_dpp v81, v247, v38 row_newbcast:2 row_mask:0xf bank_mask:0xf
	v_pk_add_f32 v[78:79], v[78:79], v[78:79] op_sel:[0,1] op_sel_hi:[1,0]
	v_fmac_f32_dpp v147, v246, v10 row_newbcast:7 row_mask:0xf bank_mask:0xf
	v_fmac_f32_dpp v146, v246, v14 row_newbcast:9 row_mask:0xf bank_mask:0xf
	v_fmac_f32_dpp v80, v247, v42 row_newbcast:4 row_mask:0xf bank_mask:0xf
	v_fmac_f32_dpp v81, v247, v72 row_newbcast:6 row_mask:0xf bank_mask:0xf
	s_waitcnt lgkmcnt(0)
	v_add_u32_e32 v254, 0xa400, v208
	ds_read2_b32 v[250:251], v254 offset0:44 offset1:60
	v_fmac_f32_dpp v84, v248, v71 row_newbcast:0 row_mask:0xf bank_mask:0xf
	v_fmac_f32_dpp v85, v248, v235 row_newbcast:2 row_mask:0xf bank_mask:0xf
	v_fmac_f32_dpp v147, v246, v20 row_newbcast:11 row_mask:0xf bank_mask:0xf
	v_fmac_f32_dpp v146, v246, v24 row_newbcast:13 row_mask:0xf bank_mask:0xf
	v_fmac_f32_dpp v80, v247, v78 row_newbcast:8 row_mask:0xf bank_mask:0xf
	v_add_u32_e32 v1, 0xa400, v208
	v_fmac_f32_dpp v147, v246, v30 row_newbcast:15 row_mask:0xf bank_mask:0xf
	v_fmac_f32_dpp v146, v247, v34 row_newbcast:1 row_mask:0xf bank_mask:0xf
	v_fmac_f32_dpp v84, v248, v4 row_newbcast:4 row_mask:0xf bank_mask:0xf
	v_fmac_f32_dpp v85, v248, v8 row_newbcast:6 row_mask:0xf bank_mask:0xf
	v_mov_b32_e32 v93, v57
	v_fmac_f32_dpp v147, v247, v40 row_newbcast:3 row_mask:0xf bank_mask:0xf
	v_fmac_f32_dpp v146, v247, v46 row_newbcast:5 row_mask:0xf bank_mask:0xf
	v_fmac_f32_dpp v84, v248, v12 row_newbcast:8 row_mask:0xf bank_mask:0xf
	v_fmac_f32_dpp v85, v248, v18 row_newbcast:10 row_mask:0xf bank_mask:0xf
	v_mov_b32_e32 v97, v57
	v_fmac_f32_dpp v147, v247, v74 row_newbcast:7 row_mask:0xf bank_mask:0xf
	v_fmac_f32_dpp v84, v248, v22 row_newbcast:12 row_mask:0xf bank_mask:0xf
	v_fmac_f32_dpp v85, v248, v26 row_newbcast:14 row_mask:0xf bank_mask:0xf
	s_nop 0
	v_pk_add_f32 v[80:81], v[80:81], v[146:147]
	v_mov_b32_e32 v146, v57
	v_fmac_f32_dpp v146, v248, v234 row_newbcast:1 row_mask:0xf bank_mask:0xf
	v_mov_b32_e32 v147, v57
	v_fmac_f32_dpp v146, v248, v6 row_newbcast:5 row_mask:0xf bank_mask:0xf
	v_fmac_f32_dpp v147, v248, v2 row_newbcast:3 row_mask:0xf bank_mask:0xf
	v_fmac_f32_dpp v84, v249, v32 row_newbcast:0 row_mask:0xf bank_mask:0xf
	v_fmac_f32_dpp v85, v249, v38 row_newbcast:2 row_mask:0xf bank_mask:0xf
	v_pk_add_f32 v[80:81], v[80:81], v[80:81] op_sel:[0,1] op_sel_hi:[1,0]
	v_fmac_f32_dpp v146, v248, v14 row_newbcast:9 row_mask:0xf bank_mask:0xf
	v_fmac_f32_dpp v147, v248, v10 row_newbcast:7 row_mask:0xf bank_mask:0xf
	v_fmac_f32_dpp v84, v249, v42 row_newbcast:4 row_mask:0xf bank_mask:0xf
	v_fmac_f32_dpp v85, v249, v72 row_newbcast:6 row_mask:0xf bank_mask:0xf
	s_waitcnt lgkmcnt(0)
; #define LAS __attribute__((address_space(3)))
; __device__ __forceinline__ void dn_prep_item(const Args& a, LAS unsigned char* lds, int item, int tid, int wave, int lane, int& cwh, int next_item) {
;     ...
;         { const LAS float* lrow = Lm + (lane & 15);
; #pragma unroll
;         for (int i = 1; i < 64; ++i) { float sa[4] = { x[i], 0.f, 0.f, 0.f };
;             int lr[4];
; #pragma unroll
;             for (int g = 0; g < (i + 15) / 16; ++g) lr[g] = __float_as_int(lrow[i * 68 + 16 * g]);
; #pragma unroll
;             for (int j = 0; j < i; ++j) { fmac_rowbcast_sel(sa[j & 3], lr[j >> 4], x[j], j); }
;             x[i] = (sa[0] + sa[1]) + (sa[2] + sa[3]); } }
	v_add_u32_e32 v254, 0xa400, v208
	ds_read2_b32 v[252:253], v254 offset0:112 offset1:128
	v_fmac_f32_dpp v86, v250, v71 row_newbcast:0 row_mask:0xf bank_mask:0xf
	v_fmac_f32_dpp v87, v250, v235 row_newbcast:2 row_mask:0xf bank_mask:0xf
	v_fmac_f32_dpp v146, v248, v24 row_newbcast:13 row_mask:0xf bank_mask:0xf
	v_fmac_f32_dpp v147, v248, v20 row_newbcast:11 row_mask:0xf bank_mask:0xf
	v_fmac_f32_dpp v84, v249, v78 row_newbcast:8 row_mask:0xf bank_mask:0xf
	v_mov_b32_e32 v99, v57
	v_fmac_f32_dpp v146, v249, v34 row_newbcast:1 row_mask:0xf bank_mask:0xf
	v_fmac_f32_dpp v147, v248, v30 row_newbcast:15 row_mask:0xf bank_mask:0xf
	v_fmac_f32_dpp v86, v250, v4 row_newbcast:4 row_mask:0xf bank_mask:0xf
	v_fmac_f32_dpp v87, v250, v8 row_newbcast:6 row_mask:0xf bank_mask:0xf
	v_mov_b32_e32 v103, v57
	v_fmac_f32_dpp v146, v249, v46 row_newbcast:5 row_mask:0xf bank_mask:0xf
	v_fmac_f32_dpp v147, v249, v40 row_newbcast:3 row_mask:0xf bank_mask:0xf
	v_fmac_f32_dpp v86, v250, v12 row_newbcast:8 row_mask:0xf bank_mask:0xf
	v_fmac_f32_dpp v87, v250, v18 row_newbcast:10 row_mask:0xf bank_mask:0xf
	v_mov_b32_e32 v107, v57
	v_fmac_f32_dpp v146, v249, v80 row_newbcast:9 row_mask:0xf bank_mask:0xf
	v_fmac_f32_dpp v147, v249, v74 row_newbcast:7 row_mask:0xf bank_mask:0xf
	v_fmac_f32_dpp v86, v250, v22 row_newbcast:12 row_mask:0xf bank_mask:0xf
	v_fmac_f32_dpp v87, v250, v26 row_newbcast:14 row_mask:0xf bank_mask:0xf
	s_nop 0
	v_pk_add_f32 v[84:85], v[84:85], v[146:147]
	v_mov_b32_e32 v146, v57
	v_fmac_f32_dpp v146, v250, v234 row_newbcast:1 row_mask:0xf bank_mask:0xf
	v_mov_b32_e32 v147, v57
	v_fmac_f32_dpp v146, v250, v6 row_newbcast:5 row_mask:0xf bank_mask:0xf
	v_fmac_f32_dpp v147, v250, v2 row_newbcast:3 row_mask:0xf bank_mask:0xf
	v_fmac_f32_dpp v86, v251, v32 row_newbcast:0 row_mask:0xf bank_mask:0xf
	v_fmac_f32_dpp v87, v251, v38 row_newbcast:2 row_mask:0xf bank_mask:0xf
	v_pk_add_f32 v[84:85], v[84:85], v[84:85] op_sel:[0,1] op_sel_hi:[1,0]
	v_fmac_f32_dpp v146, v250, v14 row_newbcast:9 row_mask:0xf bank_mask:0xf
	v_fmac_f32_dpp v147, v250, v10 row_newbcast:7 row_mask:0xf bank_mask:0xf
	v_fmac_f32_dpp v86, v251, v42 row_newbcast:4 row_mask:0xf bank_mask:0xf
	v_fmac_f32_dpp v87, v251, v72 row_newbcast:6 row_mask:0xf bank_mask:0xf
	s_waitcnt lgkmcnt(0)
	v_add_u32_e32 v254, 0xa400, v208
	ds_read2_b32 v[242:243], v254 offset0:180 offset1:196
	v_fmac_f32_dpp v90, v252, v71 row_newbcast:0 row_mask:0xf bank_mask:0xf
	v_fmac_f32_dpp v91, v252, v235 row_newbcast:2 row_mask:0xf bank_mask:0xf
	v_fmac_f32_dpp v146, v250, v24 row_newbcast:13 row_mask:0xf bank_mask:0xf
	v_fmac_f32_dpp v147, v250, v20 row_newbcast:11 row_mask:0xf bank_mask:0xf
	v_fmac_f32_dpp v86, v251, v78 row_newbcast:8 row_mask:0xf bank_mask:0xf
	v_fmac_f32_dpp v87, v251, v84 row_newbcast:10 row_mask:0xf bank_mask:0xf
	s_nop 0
	v_fmac_f32_dpp v90, v252, v4 row_newbcast:4 row_mask:0xf bank_mask:0xf
	v_fmac_f32_dpp v91, v252, v8 row_newbcast:6 row_mask:0xf bank_mask:0xf
	v_fmac_f32_dpp v146, v251, v34 row_newbcast:1 row_mask:0xf bank_mask:0xf
	v_fmac_f32_dpp v147, v250, v30 row_newbcast:15 row_mask:0xf bank_mask:0xf
	v_mov_b32_e32 v109, v57
	v_fmac_f32_dpp v146, v251, v46 row_newbcast:5 row_mask:0xf bank_mask:0xf
	v_fmac_f32_dpp v147, v251, v40 row_newbcast:3 row_mask:0xf bank_mask:0xf
	v_fmac_f32_dpp v90, v252, v12 row_newbcast:8 row_mask:0xf bank_mask:0xf
	v_fmac_f32_dpp v91, v252, v18 row_newbcast:10 row_mask:0xf bank_mask:0xf
	v_mov_b32_e32 v113, v57
	v_fmac_f32_dpp v146, v251, v80 row_newbcast:9 row_mask:0xf bank_mask:0xf
	v_fmac_f32_dpp v147, v251, v74 row_newbcast:7 row_mask:0xf bank_mask:0xf
	v_fmac_f32_dpp v90, v252, v22 row_newbcast:12 row_mask:0xf bank_mask:0xf
	v_fmac_f32_dpp v91, v252, v26 row_newbcast:14 row_mask:0xf bank_mask:0xf
	s_nop 0
	v_pk_add_f32 v[86:87], v[86:87], v[146:147]
	v_mov_b32_e32 v146, v57
	v_fmac_f32_dpp v146, v252, v234 row_newbcast:1 row_mask:0xf bank_mask:0xf
	v_mov_b32_e32 v147, v57
	v_fmac_f32_dpp v147, v252, v2 row_newbcast:3 row_mask:0xf bank_mask:0xf
	v_fmac_f32_dpp v146, v252, v6 row_newbcast:5 row_mask:0xf bank_mask:0xf
	v_fmac_f32_dpp v90, v253, v32 row_newbcast:0 row_mask:0xf bank_mask:0xf
	v_fmac_f32_dpp v91, v253, v38 row_newbcast:2 row_mask:0xf bank_mask:0xf
	v_pk_add_f32 v[86:87], v[86:87], v[86:87] op_sel:[0,1] op_sel_hi:[1,0]
	v_fmac_f32_dpp v147, v252, v10 row_newbcast:7 row_mask:0xf bank_mask:0xf
	v_fmac_f32_dpp v146, v252, v14 row_newbcast:9 row_mask:0xf bank_mask:0xf
	v_fmac_f32_dpp v90, v253, v42 row_newbcast:4 row_mask:0xf bank_mask:0xf
	v_fmac_f32_dpp v91, v253, v72 row_newbcast:6 row_mask:0xf bank_mask:0xf
	s_waitcnt lgkmcnt(0)
; #define LAS __attribute__((address_space(3)))
; __device__ __forceinline__ void dn_prep_item(const Args& a, LAS unsigned char* lds, int item, int tid, int wave, int lane, int& cwh, int next_item) {
;     ...
;         { const LAS float* lrow = Lm + (lane & 15);
; #pragma unroll
;         for (int i = 1; i < 64; ++i) { float sa[4] = { x[i], 0.f, 0.f, 0.f };
;             int lr[4];
; #pragma unroll
;             for (int g = 0; g < (i + 15) / 16; ++g) lr[g] = __float_as_int(lrow[i * 68 + 16 * g]);
; #pragma unroll
;             for (int j = 0; j < i; ++j) { fmac_rowbcast_sel(sa[j & 3], lr[j >> 4], x[j], j); }
;             x[i] = (sa[0] + sa[1]) + (sa[2] + sa[3]); } }
	v_add_u32_e32 v254, 0xa600, v208
	ds_read2_b32 v[246:247], v254 offset0:120 offset1:136
	v_fmac_f32_dpp v92, v242, v71 row_newbcast:0 row_mask:0xf bank_mask:0xf
	v_fmac_f32_dpp v93, v242, v235 row_newbcast:2 row_mask:0xf bank_mask:0xf
	v_fmac_f32_dpp v147, v252, v20 row_newbcast:11 row_mask:0xf bank_mask:0xf
	v_fmac_f32_dpp v146, v252, v24 row_newbcast:13 row_mask:0xf bank_mask:0xf
	v_fmac_f32_dpp v90, v253, v78 row_newbcast:8 row_mask:0xf bank_mask:0xf
	v_fmac_f32_dpp v91, v253, v84 row_newbcast:10 row_mask:0xf bank_mask:0xf
	s_nop 0
	v_fmac_f32_dpp v92, v242, v4 row_newbcast:4 row_mask:0xf bank_mask:0xf
	v_fmac_f32_dpp v93, v242, v8 row_newbcast:6 row_mask:0xf bank_mask:0xf
	v_fmac_f32_dpp v147, v252, v30 row_newbcast:15 row_mask:0xf bank_mask:0xf
	v_fmac_f32_dpp v146, v253, v34 row_newbcast:1 row_mask:0xf bank_mask:0xf
	v_add_u32_e32 v1, 0xa600, v208
	v_fmac_f32_dpp v147, v253, v40 row_newbcast:3 row_mask:0xf bank_mask:0xf
	v_fmac_f32_dpp v146, v253, v46 row_newbcast:5 row_mask:0xf bank_mask:0xf
	v_fmac_f32_dpp v92, v242, v12 row_newbcast:8 row_mask:0xf bank_mask:0xf
	v_fmac_f32_dpp v93, v242, v18 row_newbcast:10 row_mask:0xf bank_mask:0xf
	v_mov_b32_e32 v117, v57
	v_fmac_f32_dpp v147, v253, v74 row_newbcast:7 row_mask:0xf bank_mask:0xf
	v_fmac_f32_dpp v146, v253, v80 row_newbcast:9 row_mask:0xf bank_mask:0xf
	v_fmac_f32_dpp v92, v242, v22 row_newbcast:12 row_mask:0xf bank_mask:0xf
	v_fmac_f32_dpp v93, v242, v26 row_newbcast:14 row_mask:0xf bank_mask:0xf
	v_mov_b32_e32 v119, v57
	v_fmac_f32_dpp v147, v253, v86 row_newbcast:11 row_mask:0xf bank_mask:0xf
	v_fmac_f32_dpp v92, v243, v32 row_newbcast:0 row_mask:0xf bank_mask:0xf
	v_fmac_f32_dpp v93, v243, v38 row_newbcast:2 row_mask:0xf bank_mask:0xf
	s_nop 0
	v_pk_add_f32 v[90:91], v[90:91], v[146:147]
	v_mov_b32_e32 v146, v57
	v_fmac_f32_dpp v146, v242, v234 row_newbcast:1 row_mask:0xf bank_mask:0xf
	v_mov_b32_e32 v147, v57
	v_fmac_f32_dpp v147, v242, v2 row_newbcast:3 row_mask:0xf bank_mask:0xf
	v_fmac_f32_dpp v146, v242, v6 row_newbcast:5 row_mask:0xf bank_mask:0xf
	v_fmac_f32_dpp v92, v243, v42 row_newbcast:4 row_mask:0xf bank_mask:0xf
	v_fmac_f32_dpp v93, v243, v72 row_newbcast:6 row_mask:0xf bank_mask:0xf
	v_pk_add_f32 v[90:91], v[90:91], v[90:91] op_sel:[0,1] op_sel_hi:[1,0]
	v_fmac_f32_dpp v147, v242, v10 row_newbcast:7 row_mask:0xf bank_mask:0xf
	v_fmac_f32_dpp v146, v242, v14 row_newbcast:9 row_mask:0xf bank_mask:0xf
	v_fmac_f32_dpp v92, v243, v78 row_newbcast:8 row_mask:0xf bank_mask:0xf
	v_fmac_f32_dpp v93, v243, v84 row_newbcast:10 row_mask:0xf bank_mask:0xf
	s_waitcnt lgkmcnt(0)
	v_add_u32_e32 v254, 0xa800, v208
	ds_read2_b32 v[248:249], v254 offset0:60 offset1:76
	v_fmac_f32_dpp v96, v246, v71 row_newbcast:0 row_mask:0xf bank_mask:0xf
	v_fmac_f32_dpp v97, v246, v235 row_newbcast:2 row_mask:0xf bank_mask:0xf
	v_fmac_f32_dpp v147, v242, v20 row_newbcast:11 row_mask:0xf bank_mask:0xf
	v_fmac_f32_dpp v146, v242, v24 row_newbcast:13 row_mask:0xf bank_mask:0xf
	v_fmac_f32_dpp v92, v243, v90 row_newbcast:12 row_mask:0xf bank_mask:0xf
	v_add_u32_e32 v1, 0xa800, v208
	v_fmac_f32_dpp v147, v242, v30 row_newbcast:15 row_mask:0xf bank_mask:0xf
	v_fmac_f32_dpp v146, v243, v34 row_newbcast:1 row_mask:0xf bank_mask:0xf
	v_fmac_f32_dpp v96, v246, v4 row_newbcast:4 row_mask:0xf bank_mask:0xf
	v_fmac_f32_dpp v97, v246, v8 row_newbcast:6 row_mask:0xf bank_mask:0xf
	v_mov_b32_e32 v123, v57
	v_fmac_f32_dpp v147, v243, v40 row_newbcast:3 row_mask:0xf bank_mask:0xf
	v_fmac_f32_dpp v146, v243, v46 row_newbcast:5 row_mask:0xf bank_mask:0xf
	v_fmac_f32_dpp v96, v246, v12 row_newbcast:8 row_mask:0xf bank_mask:0xf
	v_fmac_f32_dpp v97, v246, v18 row_newbcast:10 row_mask:0xf bank_mask:0xf
	v_mov_b32_e32 v127, v57
	v_fmac_f32_dpp v147, v243, v74 row_newbcast:7 row_mask:0xf bank_mask:0xf
	v_fmac_f32_dpp v146, v243, v80 row_newbcast:9 row_mask:0xf bank_mask:0xf
	v_fmac_f32_dpp v96, v246, v22 row_newbcast:12 row_mask:0xf bank_mask:0xf
	v_fmac_f32_dpp v97, v246, v26 row_newbcast:14 row_mask:0xf bank_mask:0xf
	v_mov_b32_e32 v131, v57
	v_fmac_f32_dpp v147, v243, v86 row_newbcast:11 row_mask:0xf bank_mask:0xf
	v_fmac_f32_dpp v96, v247, v32 row_newbcast:0 row_mask:0xf bank_mask:0xf
	v_fmac_f32_dpp v97, v247, v38 row_newbcast:2 row_mask:0xf bank_mask:0xf
	s_nop 0
	v_pk_add_f32 v[92:93], v[92:93], v[146:147]
	v_mov_b32_e32 v146, v57
	v_fmac_f32_dpp v146, v246, v234 row_newbcast:1 row_mask:0xf bank_mask:0xf
	v_mov_b32_e32 v147, v57
	v_fmac_f32_dpp v146, v246, v6 row_newbcast:5 row_mask:0xf bank_mask:0xf
	v_fmac_f32_dpp v147, v246, v2 row_newbcast:3 row_mask:0xf bank_mask:0xf
	v_fmac_f32_dpp v96, v247, v42 row_newbcast:4 row_mask:0xf bank_mask:0xf
	v_fmac_f32_dpp v97, v247, v72 row_newbcast:6 row_mask:0xf bank_mask:0xf
	v_pk_add_f32 v[92:93], v[92:93], v[92:93] op_sel:[0,1] op_sel_hi:[1,0]
	v_fmac_f32_dpp v146, v246, v14 row_newbcast:9 row_mask:0xf bank_mask:0xf
	v_fmac_f32_dpp v147, v246, v10 row_newbcast:7 row_mask:0xf bank_mask:0xf
	v_fmac_f32_dpp v96, v247, v78 row_newbcast:8 row_mask:0xf bank_mask:0xf
	v_fmac_f32_dpp v97, v247, v84 row_newbcast:10 row_mask:0xf bank_mask:0xf
	s_waitcnt lgkmcnt(0)
; #define LAS __attribute__((address_space(3)))
; __device__ __forceinline__ void dn_prep_item(const Args& a, LAS unsigned char* lds, int item, int tid, int wave, int lane, int& cwh, int next_item) {
;     ...
;         { const LAS float* lrow = Lm + (lane & 15);
; #pragma unroll
;         for (int i = 1; i < 64; ++i) { float sa[4] = { x[i], 0.f, 0.f, 0.f };
;             int lr[4];
; #pragma unroll
;             for (int g = 0; g < (i + 15) / 16; ++g) lr[g] = __float_as_int(lrow[i * 68 + 16 * g]);
; #pragma unroll
;             for (int j = 0; j < i; ++j) { fmac_rowbcast_sel(sa[j & 3], lr[j >> 4], x[j], j); }
;             x[i] = (sa[0] + sa[1]) + (sa[2] + sa[3]); } }
	v_add_u32_e32 v254, 0xa800, v208
	ds_read2_b32 v[250:251], v254 offset0:128 offset1:144
	v_fmac_f32_dpp v98, v248, v71 row_newbcast:0 row_mask:0xf bank_mask:0xf
	v_fmac_f32_dpp v99, v248, v235 row_newbcast:2 row_mask:0xf bank_mask:0xf
	v_fmac_f32_dpp v146, v246, v24 row_newbcast:13 row_mask:0xf bank_mask:0xf
	v_fmac_f32_dpp v147, v246, v20 row_newbcast:11 row_mask:0xf bank_mask:0xf
	v_fmac_f32_dpp v96, v247, v90 row_newbcast:12 row_mask:0xf bank_mask:0xf
	v_mov_b32_e32 v135, v57
	v_fmac_f32_dpp v146, v247, v34 row_newbcast:1 row_mask:0xf bank_mask:0xf
	v_fmac_f32_dpp v147, v246, v30 row_newbcast:15 row_mask:0xf bank_mask:0xf
	v_fmac_f32_dpp v98, v248, v4 row_newbcast:4 row_mask:0xf bank_mask:0xf
	v_fmac_f32_dpp v99, v248, v8 row_newbcast:6 row_mask:0xf bank_mask:0xf
	v_mov_b32_e32 v139, v57
	v_fmac_f32_dpp v146, v247, v46 row_newbcast:5 row_mask:0xf bank_mask:0xf
	v_fmac_f32_dpp v147, v247, v40 row_newbcast:3 row_mask:0xf bank_mask:0xf
	v_fmac_f32_dpp v98, v248, v12 row_newbcast:8 row_mask:0xf bank_mask:0xf
	v_fmac_f32_dpp v99, v248, v18 row_newbcast:10 row_mask:0xf bank_mask:0xf
	v_mov_b32_e32 v143, v57
	v_fmac_f32_dpp v146, v247, v80 row_newbcast:9 row_mask:0xf bank_mask:0xf
	v_fmac_f32_dpp v147, v247, v74 row_newbcast:7 row_mask:0xf bank_mask:0xf
	v_fmac_f32_dpp v98, v248, v22 row_newbcast:12 row_mask:0xf bank_mask:0xf
	v_fmac_f32_dpp v99, v248, v26 row_newbcast:14 row_mask:0xf bank_mask:0xf
	v_mov_b32_e32 v145, v57
	v_fmac_f32_dpp v146, v247, v92 row_newbcast:13 row_mask:0xf bank_mask:0xf
	v_fmac_f32_dpp v147, v247, v86 row_newbcast:11 row_mask:0xf bank_mask:0xf
	v_fmac_f32_dpp v98, v249, v32 row_newbcast:0 row_mask:0xf bank_mask:0xf
	v_fmac_f32_dpp v99, v249, v38 row_newbcast:2 row_mask:0xf bank_mask:0xf
	s_nop 0
	v_pk_add_f32 v[96:97], v[96:97], v[146:147]
	v_mov_b32_e32 v146, v57
	v_fmac_f32_dpp v146, v248, v234 row_newbcast:1 row_mask:0xf bank_mask:0xf
	v_mov_b32_e32 v147, v57
	v_fmac_f32_dpp v147, v248, v2 row_newbcast:3 row_mask:0xf bank_mask:0xf
	v_fmac_f32_dpp v146, v248, v6 row_newbcast:5 row_mask:0xf bank_mask:0xf
	v_fmac_f32_dpp v98, v249, v42 row_newbcast:4 row_mask:0xf bank_mask:0xf
	v_fmac_f32_dpp v99, v249, v72 row_newbcast:6 row_mask:0xf bank_mask:0xf
	v_pk_add_f32 v[96:97], v[96:97], v[96:97] op_sel:[0,1] op_sel_hi:[1,0]
	v_fmac_f32_dpp v147, v248, v10 row_newbcast:7 row_mask:0xf bank_mask:0xf
	v_fmac_f32_dpp v146, v248, v14 row_newbcast:9 row_mask:0xf bank_mask:0xf
	v_fmac_f32_dpp v98, v249, v78 row_newbcast:8 row_mask:0xf bank_mask:0xf
	v_fmac_f32_dpp v99, v249, v84 row_newbcast:10 row_mask:0xf bank_mask:0xf
	s_waitcnt lgkmcnt(0)
	v_add_u32_e32 v254, 0xa800, v208
	ds_read2_b32 v[252:253], v254 offset0:196 offset1:212
	v_fmac_f32_dpp v102, v250, v71 row_newbcast:0 row_mask:0xf bank_mask:0xf
	v_fmac_f32_dpp v103, v250, v235 row_newbcast:2 row_mask:0xf bank_mask:0xf
	v_fmac_f32_dpp v147, v248, v20 row_newbcast:11 row_mask:0xf bank_mask:0xf
	v_fmac_f32_dpp v146, v248, v24 row_newbcast:13 row_mask:0xf bank_mask:0xf
	v_fmac_f32_dpp v98, v249, v90 row_newbcast:12 row_mask:0xf bank_mask:0xf
	v_fmac_f32_dpp v99, v249, v96 row_newbcast:14 row_mask:0xf bank_mask:0xf
	s_nop 0
	v_fmac_f32_dpp v102, v250, v4 row_newbcast:4 row_mask:0xf bank_mask:0xf
	v_fmac_f32_dpp v103, v250, v8 row_newbcast:6 row_mask:0xf bank_mask:0xf
	v_fmac_f32_dpp v147, v248, v30 row_newbcast:15 row_mask:0xf bank_mask:0xf
	v_fmac_f32_dpp v146, v249, v34 row_newbcast:1 row_mask:0xf bank_mask:0xf
	v_mov_b32_e32 v238, v57
	v_fmac_f32_dpp v147, v249, v40 row_newbcast:3 row_mask:0xf bank_mask:0xf
	v_fmac_f32_dpp v146, v249, v46 row_newbcast:5 row_mask:0xf bank_mask:0xf
	v_fmac_f32_dpp v102, v250, v12 row_newbcast:8 row_mask:0xf bank_mask:0xf
	v_fmac_f32_dpp v103, v250, v18 row_newbcast:10 row_mask:0xf bank_mask:0xf
	v_mov_b32_e32 v141, v57
	v_fmac_f32_dpp v147, v249, v74 row_newbcast:7 row_mask:0xf bank_mask:0xf
	v_fmac_f32_dpp v146, v249, v80 row_newbcast:9 row_mask:0xf bank_mask:0xf
	v_fmac_f32_dpp v102, v250, v22 row_newbcast:12 row_mask:0xf bank_mask:0xf
	v_fmac_f32_dpp v103, v250, v26 row_newbcast:14 row_mask:0xf bank_mask:0xf
	v_mov_b32_e32 v137, v57
	v_fmac_f32_dpp v147, v249, v86 row_newbcast:11 row_mask:0xf bank_mask:0xf
	v_fmac_f32_dpp v146, v249, v92 row_newbcast:13 row_mask:0xf bank_mask:0xf
	v_fmac_f32_dpp v102, v251, v32 row_newbcast:0 row_mask:0xf bank_mask:0xf
	v_fmac_f32_dpp v103, v251, v38 row_newbcast:2 row_mask:0xf bank_mask:0xf
	v_mov_b32_e32 v239, v57
	v_pk_add_f32 v[98:99], v[98:99], v[146:147]
	v_mov_b32_e32 v146, v57
	v_mov_b32_e32 v147, v57
	v_fmac_f32_dpp v146, v250, v234 row_newbcast:1 row_mask:0xf bank_mask:0xf
	v_fmac_f32_dpp v147, v250, v2 row_newbcast:3 row_mask:0xf bank_mask:0xf
	v_fmac_f32_dpp v102, v251, v42 row_newbcast:4 row_mask:0xf bank_mask:0xf
	v_fmac_f32_dpp v103, v251, v72 row_newbcast:6 row_mask:0xf bank_mask:0xf
	v_pk_add_f32 v[98:99], v[98:99], v[98:99] op_sel:[0,1] op_sel_hi:[1,0]
	v_fmac_f32_dpp v146, v250, v6 row_newbcast:5 row_mask:0xf bank_mask:0xf
	v_fmac_f32_dpp v147, v250, v10 row_newbcast:7 row_mask:0xf bank_mask:0xf
	v_fmac_f32_dpp v102, v251, v78 row_newbcast:8 row_mask:0xf bank_mask:0xf
	v_fmac_f32_dpp v103, v251, v84 row_newbcast:10 row_mask:0xf bank_mask:0xf
	v_mov_b32_e32 v133, v57
	v_fmac_f32_dpp v146, v250, v14 row_newbcast:9 row_mask:0xf bank_mask:0xf
	v_fmac_f32_dpp v147, v250, v20 row_newbcast:11 row_mask:0xf bank_mask:0xf
	v_fmac_f32_dpp v102, v251, v90 row_newbcast:12 row_mask:0xf bank_mask:0xf
	v_fmac_f32_dpp v103, v251, v96 row_newbcast:14 row_mask:0xf bank_mask:0xf
	v_mov_b32_e32 v129, v57
	v_fmac_f32_dpp v146, v250, v24 row_newbcast:13 row_mask:0xf bank_mask:0xf
	v_fmac_f32_dpp v147, v250, v30 row_newbcast:15 row_mask:0xf bank_mask:0xf
	v_mov_b32_e32 v125, v57
	v_fmac_f32_dpp v146, v251, v34 row_newbcast:1 row_mask:0xf bank_mask:0xf
	v_fmac_f32_dpp v147, v251, v40 row_newbcast:3 row_mask:0xf bank_mask:0xf
	v_mov_b32_e32 v121, v57
	v_fmac_f32_dpp v146, v251, v46 row_newbcast:5 row_mask:0xf bank_mask:0xf
	v_fmac_f32_dpp v147, v251, v74 row_newbcast:7 row_mask:0xf bank_mask:0xf
	v_mov_b32_e32 v115, v57
	v_fmac_f32_dpp v146, v251, v80 row_newbcast:9 row_mask:0xf bank_mask:0xf
	v_fmac_f32_dpp v147, v251, v86 row_newbcast:11 row_mask:0xf bank_mask:0xf
	v_mov_b32_e32 v111, v57
	v_fmac_f32_dpp v146, v251, v92 row_newbcast:13 row_mask:0xf bank_mask:0xf
	v_fmac_f32_dpp v147, v251, v98 row_newbcast:15 row_mask:0xf bank_mask:0xf
	s_nop 0
	s_waitcnt lgkmcnt(0)
; #define LAS __attribute__((address_space(3)))
; __device__ __forceinline__ void dn_prep_item(const Args& a, LAS unsigned char* lds, int item, int tid, int wave, int lane, int& cwh, int next_item) {
;     ...
;         { const LAS float* lrow = Lm + (lane & 15);
; #pragma unroll
;         for (int i = 1; i < 64; ++i) { float sa[4] = { x[i], 0.f, 0.f, 0.f };
;             int lr[4];
; #pragma unroll
;             for (int g = 0; g < (i + 15) / 16; ++g) lr[g] = __float_as_int(lrow[i * 68 + 16 * g]);
; #pragma unroll
;             for (int j = 0; j < i; ++j) { fmac_rowbcast_sel(sa[j & 3], lr[j >> 4], x[j], j); }
;             x[i] = (sa[0] + sa[1]) + (sa[2] + sa[3]); } }
	v_add_u32_e32 v254, 0xaa00, v208
	ds_read2_b32 v[242:243], v254 offset0:100 offset1:136
	v_fmac_f32_dpp v106, v252, v71 row_newbcast:0 row_mask:0xf bank_mask:0xf
	v_fmac_f32_dpp v238, v252, v234 row_newbcast:1 row_mask:0xf bank_mask:0xf
	v_fmac_f32_dpp v107, v252, v235 row_newbcast:2 row_mask:0xf bank_mask:0xf
	v_fmac_f32_dpp v239, v252, v2 row_newbcast:3 row_mask:0xf bank_mask:0xf
	v_pk_add_f32 v[102:103], v[102:103], v[146:147]
	v_fmac_f32_dpp v106, v252, v4 row_newbcast:4 row_mask:0xf bank_mask:0xf
	v_fmac_f32_dpp v238, v252, v6 row_newbcast:5 row_mask:0xf bank_mask:0xf
	v_fmac_f32_dpp v107, v252, v8 row_newbcast:6 row_mask:0xf bank_mask:0xf
	v_fmac_f32_dpp v239, v252, v10 row_newbcast:7 row_mask:0xf bank_mask:0xf
	v_add_u32_e32 v1, 0xaa00, v208
	v_fmac_f32_dpp v106, v252, v12 row_newbcast:8 row_mask:0xf bank_mask:0xf
	v_fmac_f32_dpp v238, v252, v14 row_newbcast:9 row_mask:0xf bank_mask:0xf
	v_fmac_f32_dpp v107, v252, v18 row_newbcast:10 row_mask:0xf bank_mask:0xf
	v_fmac_f32_dpp v239, v252, v20 row_newbcast:11 row_mask:0xf bank_mask:0xf
	v_pk_add_f32 v[102:103], v[102:103], v[102:103] op_sel:[0,1] op_sel_hi:[1,0]
	v_fmac_f32_dpp v106, v252, v22 row_newbcast:12 row_mask:0xf bank_mask:0xf
	v_fmac_f32_dpp v238, v252, v24 row_newbcast:13 row_mask:0xf bank_mask:0xf
	v_fmac_f32_dpp v107, v252, v26 row_newbcast:14 row_mask:0xf bank_mask:0xf
	v_fmac_f32_dpp v239, v252, v30 row_newbcast:15 row_mask:0xf bank_mask:0xf
	s_nop 0
	v_fmac_f32_dpp v106, v253, v32 row_newbcast:0 row_mask:0xf bank_mask:0xf
	v_fmac_f32_dpp v238, v253, v34 row_newbcast:1 row_mask:0xf bank_mask:0xf
	v_fmac_f32_dpp v107, v253, v38 row_newbcast:2 row_mask:0xf bank_mask:0xf
	v_fmac_f32_dpp v239, v253, v40 row_newbcast:3 row_mask:0xf bank_mask:0xf
	s_waitcnt lgkmcnt(0)
	v_add_u32_e32 v254, 0xac00, v208
	ds_read2_b32 v[246:247], v254 offset0:24 offset1:40
	v_fmac_f32_dpp v108, v243, v71 row_newbcast:0 row_mask:0xf bank_mask:0xf
	v_fmac_f32_dpp v109, v243, v235 row_newbcast:2 row_mask:0xf bank_mask:0xf
	v_fmac_f32_dpp v106, v253, v42 row_newbcast:4 row_mask:0xf bank_mask:0xf
	v_fmac_f32_dpp v238, v253, v46 row_newbcast:5 row_mask:0xf bank_mask:0xf
	v_fmac_f32_dpp v107, v253, v72 row_newbcast:6 row_mask:0xf bank_mask:0xf
	v_fmac_f32_dpp v239, v253, v74 row_newbcast:7 row_mask:0xf bank_mask:0xf
	s_nop 0
	v_fmac_f32_dpp v108, v243, v4 row_newbcast:4 row_mask:0xf bank_mask:0xf
	v_fmac_f32_dpp v109, v243, v8 row_newbcast:6 row_mask:0xf bank_mask:0xf
	v_fmac_f32_dpp v106, v253, v78 row_newbcast:8 row_mask:0xf bank_mask:0xf
	v_fmac_f32_dpp v238, v253, v80 row_newbcast:9 row_mask:0xf bank_mask:0xf
	v_fmac_f32_dpp v107, v253, v84 row_newbcast:10 row_mask:0xf bank_mask:0xf
	v_fmac_f32_dpp v239, v253, v86 row_newbcast:11 row_mask:0xf bank_mask:0xf
	s_nop 0
	v_fmac_f32_dpp v108, v243, v12 row_newbcast:8 row_mask:0xf bank_mask:0xf
	v_add_u32_e32 v1, 0xac00, v208
	v_fmac_f32_dpp v106, v253, v90 row_newbcast:12 row_mask:0xf bank_mask:0xf
	v_fmac_f32_dpp v238, v253, v92 row_newbcast:13 row_mask:0xf bank_mask:0xf
	v_fmac_f32_dpp v107, v253, v96 row_newbcast:14 row_mask:0xf bank_mask:0xf
	v_fmac_f32_dpp v239, v253, v98 row_newbcast:15 row_mask:0xf bank_mask:0xf
	v_fmac_f32_dpp v109, v243, v18 row_newbcast:10 row_mask:0xf bank_mask:0xf
	v_fmac_f32_dpp v108, v243, v22 row_newbcast:12 row_mask:0xf bank_mask:0xf
	s_nop 0
	v_fmac_f32_dpp v106, v242, v102 row_newbcast:0 row_mask:0xf bank_mask:0xf
	s_nop 0
	v_pk_add_f32 v[106:107], v[106:107], v[238:239]
	v_mov_b32_e32 v238, v57
	v_fmac_f32_dpp v238, v243, v234 row_newbcast:1 row_mask:0xf bank_mask:0xf
	v_mov_b32_e32 v239, v57
	v_fmac_f32_dpp v238, v243, v6 row_newbcast:5 row_mask:0xf bank_mask:0xf
	v_fmac_f32_dpp v239, v243, v2 row_newbcast:3 row_mask:0xf bank_mask:0xf
	v_fmac_f32_dpp v109, v243, v26 row_newbcast:14 row_mask:0xf bank_mask:0xf
	s_waitcnt lgkmcnt(0)
	v_add_u32_e32 v254, 0xac00, v208
	ds_read2_b32 v[248:249], v254 offset0:76 offset1:92
	v_fmac_f32_dpp v108, v246, v32 row_newbcast:0 row_mask:0xf bank_mask:0xf
	v_pk_add_f32 v[106:107], v[106:107], v[106:107] op_sel:[0,1] op_sel_hi:[1,0]
	v_fmac_f32_dpp v238, v243, v14 row_newbcast:9 row_mask:0xf bank_mask:0xf
	v_fmac_f32_dpp v239, v243, v10 row_newbcast:7 row_mask:0xf bank_mask:0xf
	v_fmac_f32_dpp v109, v246, v38 row_newbcast:2 row_mask:0xf bank_mask:0xf
	v_fmac_f32_dpp v108, v246, v42 row_newbcast:4 row_mask:0xf bank_mask:0xf
	v_mov_b32_e32 v105, v57
	v_fmac_f32_dpp v238, v243, v24 row_newbcast:13 row_mask:0xf bank_mask:0xf
	v_fmac_f32_dpp v239, v243, v20 row_newbcast:11 row_mask:0xf bank_mask:0xf
	v_fmac_f32_dpp v109, v246, v72 row_newbcast:6 row_mask:0xf bank_mask:0xf
	v_fmac_f32_dpp v108, v246, v78 row_newbcast:8 row_mask:0xf bank_mask:0xf
	v_mov_b32_e32 v101, v57
	v_fmac_f32_dpp v238, v246, v34 row_newbcast:1 row_mask:0xf bank_mask:0xf
	v_fmac_f32_dpp v239, v243, v30 row_newbcast:15 row_mask:0xf bank_mask:0xf
	v_fmac_f32_dpp v109, v246, v84 row_newbcast:10 row_mask:0xf bank_mask:0xf
	v_fmac_f32_dpp v108, v246, v90 row_newbcast:12 row_mask:0xf bank_mask:0xf
	s_nop 0
	v_fmac_f32_dpp v238, v246, v46 row_newbcast:5 row_mask:0xf bank_mask:0xf
	v_fmac_f32_dpp v239, v246, v40 row_newbcast:3 row_mask:0xf bank_mask:0xf
	v_fmac_f32_dpp v109, v246, v96 row_newbcast:14 row_mask:0xf bank_mask:0xf
	v_fmac_f32_dpp v108, v247, v102 row_newbcast:0 row_mask:0xf bank_mask:0xf
	s_waitcnt lgkmcnt(0)
; #define LAS __attribute__((address_space(3)))
; __device__ __forceinline__ void dn_prep_item(const Args& a, LAS unsigned char* lds, int item, int tid, int wave, int lane, int& cwh, int next_item) {
;     ...
;         { const LAS float* lrow = Lm + (lane & 15);
; #pragma unroll
;         for (int i = 1; i < 64; ++i) { float sa[4] = { x[i], 0.f, 0.f, 0.f };
;             int lr[4];
; #pragma unroll
;             for (int g = 0; g < (i + 15) / 16; ++g) lr[g] = __float_as_int(lrow[i * 68 + 16 * g]);
; #pragma unroll
;             for (int j = 0; j < i; ++j) { fmac_rowbcast_sel(sa[j & 3], lr[j >> 4], x[j], j); }
;             x[i] = (sa[0] + sa[1]) + (sa[2] + sa[3]); } }
	v_add_u32_e32 v254, 0xac00, v208
	ds_read2_b32 v[250:251], v254 offset0:108 offset1:144
	v_fmac_f32_dpp v112, v248, v71 row_newbcast:0 row_mask:0xf bank_mask:0xf
	v_fmac_f32_dpp v113, v248, v235 row_newbcast:2 row_mask:0xf bank_mask:0xf
	v_fmac_f32_dpp v238, v246, v80 row_newbcast:9 row_mask:0xf bank_mask:0xf
	v_fmac_f32_dpp v239, v246, v74 row_newbcast:7 row_mask:0xf bank_mask:0xf
	v_mov_b32_e32 v95, v57
	v_fmac_f32_dpp v238, v246, v92 row_newbcast:13 row_mask:0xf bank_mask:0xf
	v_fmac_f32_dpp v239, v246, v86 row_newbcast:11 row_mask:0xf bank_mask:0xf
	v_fmac_f32_dpp v112, v248, v4 row_newbcast:4 row_mask:0xf bank_mask:0xf
	v_fmac_f32_dpp v113, v248, v8 row_newbcast:6 row_mask:0xf bank_mask:0xf
	v_mov_b32_e32 v89, v57
	v_fmac_f32_dpp v238, v247, v106 row_newbcast:1 row_mask:0xf bank_mask:0xf
	v_fmac_f32_dpp v239, v246, v98 row_newbcast:15 row_mask:0xf bank_mask:0xf
	v_fmac_f32_dpp v112, v248, v12 row_newbcast:8 row_mask:0xf bank_mask:0xf
	v_fmac_f32_dpp v113, v248, v18 row_newbcast:10 row_mask:0xf bank_mask:0xf
	s_nop 0
	v_pk_add_f32 v[108:109], v[108:109], v[238:239]
	v_mov_b32_e32 v238, v57
	v_fmac_f32_dpp v238, v248, v234 row_newbcast:1 row_mask:0xf bank_mask:0xf
	v_mov_b32_e32 v239, v57
	v_fmac_f32_dpp v238, v248, v6 row_newbcast:5 row_mask:0xf bank_mask:0xf
	v_fmac_f32_dpp v239, v248, v2 row_newbcast:3 row_mask:0xf bank_mask:0xf
	v_fmac_f32_dpp v112, v248, v22 row_newbcast:12 row_mask:0xf bank_mask:0xf
	v_fmac_f32_dpp v113, v248, v26 row_newbcast:14 row_mask:0xf bank_mask:0xf
	v_pk_add_f32 v[108:109], v[108:109], v[108:109] op_sel:[0,1] op_sel_hi:[1,0]
	v_fmac_f32_dpp v238, v248, v14 row_newbcast:9 row_mask:0xf bank_mask:0xf
	v_fmac_f32_dpp v239, v248, v10 row_newbcast:7 row_mask:0xf bank_mask:0xf
	v_fmac_f32_dpp v112, v249, v32 row_newbcast:0 row_mask:0xf bank_mask:0xf
	v_fmac_f32_dpp v113, v249, v38 row_newbcast:2 row_mask:0xf bank_mask:0xf
	s_waitcnt lgkmcnt(0)
	v_add_u32_e32 v254, 0xac00, v208
	ds_read2_b32 v[252:253], v254 offset0:160 offset1:176
	v_fmac_f32_dpp v116, v251, v71 row_newbcast:0 row_mask:0xf bank_mask:0xf
	v_fmac_f32_dpp v117, v251, v235 row_newbcast:2 row_mask:0xf bank_mask:0xf
	v_fmac_f32_dpp v238, v248, v24 row_newbcast:13 row_mask:0xf bank_mask:0xf
	v_fmac_f32_dpp v239, v248, v20 row_newbcast:11 row_mask:0xf bank_mask:0xf
	v_fmac_f32_dpp v112, v249, v42 row_newbcast:4 row_mask:0xf bank_mask:0xf
	v_fmac_f32_dpp v113, v249, v72 row_newbcast:6 row_mask:0xf bank_mask:0xf
	s_nop 0
	v_fmac_f32_dpp v116, v251, v4 row_newbcast:4 row_mask:0xf bank_mask:0xf
	v_fmac_f32_dpp v117, v251, v8 row_newbcast:6 row_mask:0xf bank_mask:0xf
	v_fmac_f32_dpp v238, v249, v34 row_newbcast:1 row_mask:0xf bank_mask:0xf
	v_fmac_f32_dpp v239, v248, v30 row_newbcast:15 row_mask:0xf bank_mask:0xf
	v_fmac_f32_dpp v112, v249, v78 row_newbcast:8 row_mask:0xf bank_mask:0xf
	v_fmac_f32_dpp v113, v249, v84 row_newbcast:10 row_mask:0xf bank_mask:0xf
	s_nop 0
	v_fmac_f32_dpp v116, v251, v12 row_newbcast:8 row_mask:0xf bank_mask:0xf
	v_fmac_f32_dpp v117, v251, v18 row_newbcast:10 row_mask:0xf bank_mask:0xf
	v_fmac_f32_dpp v238, v249, v46 row_newbcast:5 row_mask:0xf bank_mask:0xf
	v_fmac_f32_dpp v239, v249, v40 row_newbcast:3 row_mask:0xf bank_mask:0xf
	v_fmac_f32_dpp v112, v249, v90 row_newbcast:12 row_mask:0xf bank_mask:0xf
	v_fmac_f32_dpp v113, v249, v96 row_newbcast:14 row_mask:0xf bank_mask:0xf
	s_nop 0
	v_fmac_f32_dpp v116, v251, v22 row_newbcast:12 row_mask:0xf bank_mask:0xf
	v_fmac_f32_dpp v117, v251, v26 row_newbcast:14 row_mask:0xf bank_mask:0xf
	v_fmac_f32_dpp v238, v249, v80 row_newbcast:9 row_mask:0xf bank_mask:0xf
	v_fmac_f32_dpp v239, v249, v74 row_newbcast:7 row_mask:0xf bank_mask:0xf
	v_fmac_f32_dpp v112, v250, v102 row_newbcast:0 row_mask:0xf bank_mask:0xf
	v_fmac_f32_dpp v113, v250, v108 row_newbcast:2 row_mask:0xf bank_mask:0xf
	v_mov_b32_e32 v83, v57
	v_fmac_f32_dpp v238, v249, v92 row_newbcast:13 row_mask:0xf bank_mask:0xf
	v_fmac_f32_dpp v239, v249, v86 row_newbcast:11 row_mask:0xf bank_mask:0xf
	v_mov_b32_e32 v77, v57
	v_fmac_f32_dpp v238, v250, v106 row_newbcast:1 row_mask:0xf bank_mask:0xf
	v_fmac_f32_dpp v239, v249, v98 row_newbcast:15 row_mask:0xf bank_mask:0xf
	s_nop 0
	v_pk_add_f32 v[112:113], v[112:113], v[238:239]
	v_mov_b32_e32 v238, v57
	v_fmac_f32_dpp v238, v251, v234 row_newbcast:1 row_mask:0xf bank_mask:0xf
	v_mov_b32_e32 v239, v57
	v_fmac_f32_dpp v239, v251, v2 row_newbcast:3 row_mask:0xf bank_mask:0xf
	v_fmac_f32_dpp v238, v251, v6 row_newbcast:5 row_mask:0xf bank_mask:0xf
	s_waitcnt lgkmcnt(0)
; #define LAS __attribute__((address_space(3)))
; __device__ __forceinline__ void dn_prep_item(const Args& a, LAS unsigned char* lds, int item, int tid, int wave, int lane, int& cwh, int next_item) {
;     ...
;         { const LAS float* lrow = Lm + (lane & 15);
; #pragma unroll
;         for (int i = 1; i < 64; ++i) { float sa[4] = { x[i], 0.f, 0.f, 0.f };
;             int lr[4];
; #pragma unroll
;             for (int g = 0; g < (i + 15) / 16; ++g) lr[g] = __float_as_int(lrow[i * 68 + 16 * g]);
; #pragma unroll
;             for (int j = 0; j < i; ++j) { fmac_rowbcast_sel(sa[j & 3], lr[j >> 4], x[j], j); }
;             x[i] = (sa[0] + sa[1]) + (sa[2] + sa[3]); } }
	v_add_u32_e32 v254, 0xac00, v208
	ds_read2_b32 v[242:243], v254 offset0:212 offset1:228
	v_fmac_f32_dpp v116, v252, v32 row_newbcast:0 row_mask:0xf bank_mask:0xf
	v_fmac_f32_dpp v117, v252, v38 row_newbcast:2 row_mask:0xf bank_mask:0xf
	v_pk_add_f32 v[112:113], v[112:113], v[112:113] op_sel:[0,1] op_sel_hi:[1,0]
	v_fmac_f32_dpp v239, v251, v10 row_newbcast:7 row_mask:0xf bank_mask:0xf
	v_fmac_f32_dpp v238, v251, v14 row_newbcast:9 row_mask:0xf bank_mask:0xf
	v_fmac_f32_dpp v116, v252, v42 row_newbcast:4 row_mask:0xf bank_mask:0xf
	v_fmac_f32_dpp v117, v252, v72 row_newbcast:6 row_mask:0xf bank_mask:0xf
	v_mov_b32_e32 v45, v57
	v_fmac_f32_dpp v239, v251, v20 row_newbcast:11 row_mask:0xf bank_mask:0xf
	v_fmac_f32_dpp v238, v251, v24 row_newbcast:13 row_mask:0xf bank_mask:0xf
	v_fmac_f32_dpp v116, v252, v78 row_newbcast:8 row_mask:0xf bank_mask:0xf
	v_fmac_f32_dpp v117, v252, v84 row_newbcast:10 row_mask:0xf bank_mask:0xf
	v_mov_b32_e32 v37, v57
	v_fmac_f32_dpp v239, v251, v30 row_newbcast:15 row_mask:0xf bank_mask:0xf
	v_fmac_f32_dpp v238, v252, v34 row_newbcast:1 row_mask:0xf bank_mask:0xf
	v_fmac_f32_dpp v116, v252, v90 row_newbcast:12 row_mask:0xf bank_mask:0xf
	v_fmac_f32_dpp v117, v252, v96 row_newbcast:14 row_mask:0xf bank_mask:0xf
	v_mul_f32_e32 v16, v240, v0
	v_fmac_f32_dpp v239, v252, v40 row_newbcast:3 row_mask:0xf bank_mask:0xf
	v_fmac_f32_dpp v238, v252, v46 row_newbcast:5 row_mask:0xf bank_mask:0xf
	v_fmac_f32_dpp v116, v253, v102 row_newbcast:0 row_mask:0xf bank_mask:0xf
	v_fmac_f32_dpp v117, v253, v108 row_newbcast:2 row_mask:0xf bank_mask:0xf
	v_lshlrev_b32_e32 v0, 16, v17
	v_fmac_f32_dpp v239, v252, v74 row_newbcast:7 row_mask:0xf bank_mask:0xf
	v_fmac_f32_dpp v238, v252, v80 row_newbcast:9 row_mask:0xf bank_mask:0xf
	v_mul_f32_e32 v0, v241, v0
	v_fmac_f32_dpp v239, v252, v86 row_newbcast:11 row_mask:0xf bank_mask:0xf
	v_fmac_f32_dpp v238, v252, v92 row_newbcast:13 row_mask:0xf bank_mask:0xf
	v_mov_b32_e32 v29, v57
	v_fmac_f32_dpp v239, v252, v98 row_newbcast:15 row_mask:0xf bank_mask:0xf
	v_fmac_f32_dpp v238, v253, v106 row_newbcast:1 row_mask:0xf bank_mask:0xf
	v_mov_b32_e32 v17, v57
	v_fmac_f32_dpp v239, v253, v112 row_newbcast:3 row_mask:0xf bank_mask:0xf
	s_nop 0
	v_pk_add_f32 v[116:117], v[116:117], v[238:239]
	s_waitcnt lgkmcnt(0)
	v_add_u32_e32 v254, 0xae00, v208
	ds_read2_b32 v[246:247], v254 offset0:116 offset1:152
	v_fmac_f32_dpp v118, v242, v71 row_newbcast:0 row_mask:0xf bank_mask:0xf
	v_mov_b32_e32 v238, v57
	v_fmac_f32_dpp v238, v242, v234 row_newbcast:1 row_mask:0xf bank_mask:0xf
	v_fmac_f32_dpp v119, v242, v235 row_newbcast:2 row_mask:0xf bank_mask:0xf
	v_mov_b32_e32 v239, v57
	v_fmac_f32_dpp v118, v242, v4 row_newbcast:4 row_mask:0xf bank_mask:0xf
	v_fmac_f32_dpp v239, v242, v2 row_newbcast:3 row_mask:0xf bank_mask:0xf
	v_fmac_f32_dpp v238, v242, v6 row_newbcast:5 row_mask:0xf bank_mask:0xf
	v_fmac_f32_dpp v119, v242, v8 row_newbcast:6 row_mask:0xf bank_mask:0xf
	v_add_u32_e32 v1, 0xae00, v208
	v_fmac_f32_dpp v118, v242, v12 row_newbcast:8 row_mask:0xf bank_mask:0xf
	v_fmac_f32_dpp v239, v242, v10 row_newbcast:7 row_mask:0xf bank_mask:0xf
	v_fmac_f32_dpp v238, v242, v14 row_newbcast:9 row_mask:0xf bank_mask:0xf
	v_fmac_f32_dpp v119, v242, v18 row_newbcast:10 row_mask:0xf bank_mask:0xf
	s_nop 0
	v_fmac_f32_dpp v118, v242, v22 row_newbcast:12 row_mask:0xf bank_mask:0xf
	v_fmac_f32_dpp v239, v242, v20 row_newbcast:11 row_mask:0xf bank_mask:0xf
	v_fmac_f32_dpp v238, v242, v24 row_newbcast:13 row_mask:0xf bank_mask:0xf
	v_fmac_f32_dpp v119, v242, v26 row_newbcast:14 row_mask:0xf bank_mask:0xf
	v_pk_add_f32 v[116:117], v[116:117], v[116:117] op_sel:[0,1] op_sel_hi:[1,0]
	v_fmac_f32_dpp v118, v243, v32 row_newbcast:0 row_mask:0xf bank_mask:0xf
	v_fmac_f32_dpp v239, v242, v30 row_newbcast:15 row_mask:0xf bank_mask:0xf
	v_fmac_f32_dpp v238, v243, v34 row_newbcast:1 row_mask:0xf bank_mask:0xf
	v_fmac_f32_dpp v119, v243, v38 row_newbcast:2 row_mask:0xf bank_mask:0xf
	s_waitcnt lgkmcnt(0)
	v_add_u32_e32 v254, 0xb000, v208
	ds_read2_b32 v[248:249], v254 offset0:40 offset1:56
	v_fmac_f32_dpp v122, v247, v71 row_newbcast:0 row_mask:0xf bank_mask:0xf
	v_fmac_f32_dpp v123, v247, v235 row_newbcast:2 row_mask:0xf bank_mask:0xf
	v_fmac_f32_dpp v118, v243, v42 row_newbcast:4 row_mask:0xf bank_mask:0xf
	v_fmac_f32_dpp v239, v243, v40 row_newbcast:3 row_mask:0xf bank_mask:0xf
	v_fmac_f32_dpp v238, v243, v46 row_newbcast:5 row_mask:0xf bank_mask:0xf
	v_fmac_f32_dpp v119, v243, v72 row_newbcast:6 row_mask:0xf bank_mask:0xf
	s_nop 0
	v_fmac_f32_dpp v122, v247, v4 row_newbcast:4 row_mask:0xf bank_mask:0xf
	v_fmac_f32_dpp v123, v247, v8 row_newbcast:6 row_mask:0xf bank_mask:0xf
	v_fmac_f32_dpp v118, v243, v78 row_newbcast:8 row_mask:0xf bank_mask:0xf
	v_fmac_f32_dpp v239, v243, v74 row_newbcast:7 row_mask:0xf bank_mask:0xf
	v_fmac_f32_dpp v238, v243, v80 row_newbcast:9 row_mask:0xf bank_mask:0xf
	v_fmac_f32_dpp v119, v243, v84 row_newbcast:10 row_mask:0xf bank_mask:0xf
	s_nop 0
	v_fmac_f32_dpp v122, v247, v12 row_newbcast:8 row_mask:0xf bank_mask:0xf
	v_add_u32_e32 v1, 0xb000, v208
	v_fmac_f32_dpp v118, v243, v90 row_newbcast:12 row_mask:0xf bank_mask:0xf
	v_fmac_f32_dpp v239, v243, v86 row_newbcast:11 row_mask:0xf bank_mask:0xf
	v_fmac_f32_dpp v238, v243, v92 row_newbcast:13 row_mask:0xf bank_mask:0xf
	v_fmac_f32_dpp v119, v243, v96 row_newbcast:14 row_mask:0xf bank_mask:0xf
	v_fmac_f32_dpp v123, v247, v18 row_newbcast:10 row_mask:0xf bank_mask:0xf
	v_fmac_f32_dpp v122, v247, v22 row_newbcast:12 row_mask:0xf bank_mask:0xf
	s_nop 0
	v_fmac_f32_dpp v118, v246, v102 row_newbcast:0 row_mask:0xf bank_mask:0xf
	v_fmac_f32_dpp v239, v243, v98 row_newbcast:15 row_mask:0xf bank_mask:0xf
	v_fmac_f32_dpp v238, v246, v106 row_newbcast:1 row_mask:0xf bank_mask:0xf
	v_fmac_f32_dpp v119, v246, v108 row_newbcast:2 row_mask:0xf bank_mask:0xf
	s_nop 0
	v_fmac_f32_dpp v118, v246, v116 row_newbcast:4 row_mask:0xf bank_mask:0xf
	v_fmac_f32_dpp v239, v246, v112 row_newbcast:3 row_mask:0xf bank_mask:0xf
	v_fmac_f32_dpp v123, v247, v26 row_newbcast:14 row_mask:0xf bank_mask:0xf
	s_waitcnt lgkmcnt(0)
; #define LAS __attribute__((address_space(3)))
; __device__ __forceinline__ void dn_prep_item(const Args& a, LAS unsigned char* lds, int item, int tid, int wave, int lane, int& cwh, int next_item) {
;     ...
;         { const LAS float* lrow = Lm + (lane & 15);
; #pragma unroll
;         for (int i = 1; i < 64; ++i) { float sa[4] = { x[i], 0.f, 0.f, 0.f };
;             int lr[4];
; #pragma unroll
;             for (int g = 0; g < (i + 15) / 16; ++g) lr[g] = __float_as_int(lrow[i * 68 + 16 * g]);
; #pragma unroll
;             for (int j = 0; j < i; ++j) { fmac_rowbcast_sel(sa[j & 3], lr[j >> 4], x[j], j); }
;             x[i] = (sa[0] + sa[1]) + (sa[2] + sa[3]); } }
	v_add_u32_e32 v254, 0xb000, v208
	ds_read2_b32 v[250:251], v254 offset0:92 offset1:108
	v_fmac_f32_dpp v122, v248, v32 row_newbcast:0 row_mask:0xf bank_mask:0xf
	v_cvt_pk_bf16_f32 v3, v8, v10
	v_pk_add_f32 v[118:119], v[118:119], v[238:239]
	v_mov_b32_e32 v238, v57
	v_fmac_f32_dpp v238, v247, v234 row_newbcast:1 row_mask:0xf bank_mask:0xf
	v_mov_b32_e32 v239, v57
	v_fmac_f32_dpp v238, v247, v6 row_newbcast:5 row_mask:0xf bank_mask:0xf
	v_fmac_f32_dpp v239, v247, v2 row_newbcast:3 row_mask:0xf bank_mask:0xf
	v_fmac_f32_dpp v123, v248, v38 row_newbcast:2 row_mask:0xf bank_mask:0xf
	v_fmac_f32_dpp v122, v248, v42 row_newbcast:4 row_mask:0xf bank_mask:0xf
	v_pk_add_f32 v[118:119], v[118:119], v[118:119] op_sel:[0,1] op_sel_hi:[1,0]
	v_fmac_f32_dpp v238, v247, v14 row_newbcast:9 row_mask:0xf bank_mask:0xf
	v_fmac_f32_dpp v239, v247, v10 row_newbcast:7 row_mask:0xf bank_mask:0xf
	v_fmac_f32_dpp v123, v248, v72 row_newbcast:6 row_mask:0xf bank_mask:0xf
	v_fmac_f32_dpp v122, v248, v78 row_newbcast:8 row_mask:0xf bank_mask:0xf
	s_nop 0
	v_fmac_f32_dpp v238, v247, v24 row_newbcast:13 row_mask:0xf bank_mask:0xf
	v_fmac_f32_dpp v239, v247, v20 row_newbcast:11 row_mask:0xf bank_mask:0xf
	v_fmac_f32_dpp v123, v248, v84 row_newbcast:10 row_mask:0xf bank_mask:0xf
	v_fmac_f32_dpp v122, v248, v90 row_newbcast:12 row_mask:0xf bank_mask:0xf
	s_nop 0
	v_fmac_f32_dpp v238, v248, v34 row_newbcast:1 row_mask:0xf bank_mask:0xf
	v_fmac_f32_dpp v239, v247, v30 row_newbcast:15 row_mask:0xf bank_mask:0xf
	v_fmac_f32_dpp v123, v248, v96 row_newbcast:14 row_mask:0xf bank_mask:0xf
	v_fmac_f32_dpp v122, v249, v102 row_newbcast:0 row_mask:0xf bank_mask:0xf
	s_nop 0
	v_fmac_f32_dpp v238, v248, v46 row_newbcast:5 row_mask:0xf bank_mask:0xf
	v_fmac_f32_dpp v239, v248, v40 row_newbcast:3 row_mask:0xf bank_mask:0xf
	v_fmac_f32_dpp v123, v249, v108 row_newbcast:2 row_mask:0xf bank_mask:0xf
	v_fmac_f32_dpp v122, v249, v116 row_newbcast:4 row_mask:0xf bank_mask:0xf
	s_waitcnt lgkmcnt(0)
	v_add_u32_e32 v254, 0xb000, v208
	ds_read2_b32 v[252:253], v254 offset0:124 offset1:160
	v_fmac_f32_dpp v126, v250, v71 row_newbcast:0 row_mask:0xf bank_mask:0xf
	v_fmac_f32_dpp v127, v250, v235 row_newbcast:2 row_mask:0xf bank_mask:0xf
	v_fmac_f32_dpp v238, v248, v80 row_newbcast:9 row_mask:0xf bank_mask:0xf
	v_fmac_f32_dpp v239, v248, v74 row_newbcast:7 row_mask:0xf bank_mask:0xf
	s_nop 0
	v_fmac_f32_dpp v238, v248, v92 row_newbcast:13 row_mask:0xf bank_mask:0xf
	v_fmac_f32_dpp v239, v248, v86 row_newbcast:11 row_mask:0xf bank_mask:0xf
	v_fmac_f32_dpp v126, v250, v4 row_newbcast:4 row_mask:0xf bank_mask:0xf
	v_fmac_f32_dpp v127, v250, v8 row_newbcast:6 row_mask:0xf bank_mask:0xf
	s_nop 0
	v_fmac_f32_dpp v238, v249, v106 row_newbcast:1 row_mask:0xf bank_mask:0xf
	v_fmac_f32_dpp v239, v248, v98 row_newbcast:15 row_mask:0xf bank_mask:0xf
	v_fmac_f32_dpp v126, v250, v12 row_newbcast:8 row_mask:0xf bank_mask:0xf
	v_fmac_f32_dpp v127, v250, v18 row_newbcast:10 row_mask:0xf bank_mask:0xf
	s_nop 0
	v_fmac_f32_dpp v238, v249, v118 row_newbcast:5 row_mask:0xf bank_mask:0xf
	v_fmac_f32_dpp v239, v249, v112 row_newbcast:3 row_mask:0xf bank_mask:0xf
	v_fmac_f32_dpp v126, v250, v22 row_newbcast:12 row_mask:0xf bank_mask:0xf
	v_fmac_f32_dpp v127, v250, v26 row_newbcast:14 row_mask:0xf bank_mask:0xf
	s_nop 0
	v_pk_add_f32 v[122:123], v[122:123], v[238:239]
	v_mov_b32_e32 v238, v57
	v_fmac_f32_dpp v238, v250, v234 row_newbcast:1 row_mask:0xf bank_mask:0xf
	v_mov_b32_e32 v239, v57
	v_fmac_f32_dpp v238, v250, v6 row_newbcast:5 row_mask:0xf bank_mask:0xf
	v_fmac_f32_dpp v239, v250, v2 row_newbcast:3 row_mask:0xf bank_mask:0xf
	v_fmac_f32_dpp v126, v251, v32 row_newbcast:0 row_mask:0xf bank_mask:0xf
	v_fmac_f32_dpp v127, v251, v38 row_newbcast:2 row_mask:0xf bank_mask:0xf
	v_pk_add_f32 v[122:123], v[122:123], v[122:123] op_sel:[0,1] op_sel_hi:[1,0]
	v_fmac_f32_dpp v238, v250, v14 row_newbcast:9 row_mask:0xf bank_mask:0xf
	v_fmac_f32_dpp v239, v250, v10 row_newbcast:7 row_mask:0xf bank_mask:0xf
	v_fmac_f32_dpp v126, v251, v42 row_newbcast:4 row_mask:0xf bank_mask:0xf
	v_fmac_f32_dpp v127, v251, v72 row_newbcast:6 row_mask:0xf bank_mask:0xf
	s_waitcnt lgkmcnt(0)
	v_add_u32_e32 v254, 0xb000, v208
	ds_read2_b32 v[242:243], v254 offset0:176 offset1:192
	v_fmac_f32_dpp v130, v253, v71 row_newbcast:0 row_mask:0xf bank_mask:0xf
	v_fmac_f32_dpp v131, v253, v235 row_newbcast:2 row_mask:0xf bank_mask:0xf
	v_fmac_f32_dpp v238, v250, v24 row_newbcast:13 row_mask:0xf bank_mask:0xf
	v_fmac_f32_dpp v239, v250, v20 row_newbcast:11 row_mask:0xf bank_mask:0xf
	v_fmac_f32_dpp v126, v251, v78 row_newbcast:8 row_mask:0xf bank_mask:0xf
	v_fmac_f32_dpp v127, v251, v84 row_newbcast:10 row_mask:0xf bank_mask:0xf
	s_nop 0
	v_fmac_f32_dpp v130, v253, v4 row_newbcast:4 row_mask:0xf bank_mask:0xf
	v_fmac_f32_dpp v131, v253, v8 row_newbcast:6 row_mask:0xf bank_mask:0xf
	v_fmac_f32_dpp v238, v251, v34 row_newbcast:1 row_mask:0xf bank_mask:0xf
	v_fmac_f32_dpp v239, v250, v30 row_newbcast:15 row_mask:0xf bank_mask:0xf
	v_fmac_f32_dpp v126, v251, v90 row_newbcast:12 row_mask:0xf bank_mask:0xf
	v_fmac_f32_dpp v127, v251, v96 row_newbcast:14 row_mask:0xf bank_mask:0xf
	s_nop 0
	v_fmac_f32_dpp v130, v253, v12 row_newbcast:8 row_mask:0xf bank_mask:0xf
	v_fmac_f32_dpp v131, v253, v18 row_newbcast:10 row_mask:0xf bank_mask:0xf
	v_fmac_f32_dpp v238, v251, v46 row_newbcast:5 row_mask:0xf bank_mask:0xf
	v_fmac_f32_dpp v239, v251, v40 row_newbcast:3 row_mask:0xf bank_mask:0xf
	v_fmac_f32_dpp v126, v252, v102 row_newbcast:0 row_mask:0xf bank_mask:0xf
	v_fmac_f32_dpp v127, v252, v108 row_newbcast:2 row_mask:0xf bank_mask:0xf
	s_nop 0
	v_fmac_f32_dpp v130, v253, v22 row_newbcast:12 row_mask:0xf bank_mask:0xf
	v_fmac_f32_dpp v131, v253, v26 row_newbcast:14 row_mask:0xf bank_mask:0xf
	v_fmac_f32_dpp v238, v251, v80 row_newbcast:9 row_mask:0xf bank_mask:0xf
	v_fmac_f32_dpp v239, v251, v74 row_newbcast:7 row_mask:0xf bank_mask:0xf
	v_fmac_f32_dpp v126, v252, v116 row_newbcast:4 row_mask:0xf bank_mask:0xf
	v_fmac_f32_dpp v127, v252, v122 row_newbcast:6 row_mask:0xf bank_mask:0xf
	s_nop 0
	v_fmac_f32_dpp v238, v251, v92 row_newbcast:13 row_mask:0xf bank_mask:0xf
	v_fmac_f32_dpp v239, v251, v86 row_newbcast:11 row_mask:0xf bank_mask:0xf
	s_nop 0
	v_fmac_f32_dpp v238, v252, v106 row_newbcast:1 row_mask:0xf bank_mask:0xf
	v_fmac_f32_dpp v239, v251, v98 row_newbcast:15 row_mask:0xf bank_mask:0xf
	s_nop 0
	v_fmac_f32_dpp v238, v252, v118 row_newbcast:5 row_mask:0xf bank_mask:0xf
	v_fmac_f32_dpp v239, v252, v112 row_newbcast:3 row_mask:0xf bank_mask:0xf
	s_waitcnt lgkmcnt(0)
; #define LAS __attribute__((address_space(3)))
; __device__ __forceinline__ void dn_prep_item(const Args& a, LAS unsigned char* lds, int item, int tid, int wave, int lane, int& cwh, int next_item) {
;     ...
;         { const LAS float* lrow = Lm + (lane & 15);
; #pragma unroll
;         for (int i = 1; i < 64; ++i) { float sa[4] = { x[i], 0.f, 0.f, 0.f };
;             int lr[4];
; #pragma unroll
;             for (int g = 0; g < (i + 15) / 16; ++g) lr[g] = __float_as_int(lrow[i * 68 + 16 * g]);
; #pragma unroll
;             for (int j = 0; j < i; ++j) { fmac_rowbcast_sel(sa[j & 3], lr[j >> 4], x[j], j); }
;             x[i] = (sa[0] + sa[1]) + (sa[2] + sa[3]); } }
	v_add_u32_e32 v254, 0xb000, v208
	ds_read2_b32 v[246:247], v254 offset0:228 offset1:244
	v_fmac_f32_dpp v130, v242, v32 row_newbcast:0 row_mask:0xf bank_mask:0xf
	v_fmac_f32_dpp v131, v242, v38 row_newbcast:2 row_mask:0xf bank_mask:0xf
	v_pk_add_f32 v[126:127], v[126:127], v[238:239]
	v_mov_b32_e32 v238, v57
	v_fmac_f32_dpp v238, v253, v234 row_newbcast:1 row_mask:0xf bank_mask:0xf
	v_mov_b32_e32 v239, v57
	v_fmac_f32_dpp v239, v253, v2 row_newbcast:3 row_mask:0xf bank_mask:0xf
	v_fmac_f32_dpp v238, v253, v6 row_newbcast:5 row_mask:0xf bank_mask:0xf
	v_fmac_f32_dpp v130, v242, v42 row_newbcast:4 row_mask:0xf bank_mask:0xf
	v_fmac_f32_dpp v131, v242, v72 row_newbcast:6 row_mask:0xf bank_mask:0xf
	v_pk_add_f32 v[126:127], v[126:127], v[126:127] op_sel:[0,1] op_sel_hi:[1,0]
	v_fmac_f32_dpp v239, v253, v10 row_newbcast:7 row_mask:0xf bank_mask:0xf
	v_fmac_f32_dpp v238, v253, v14 row_newbcast:9 row_mask:0xf bank_mask:0xf
	v_fmac_f32_dpp v130, v242, v78 row_newbcast:8 row_mask:0xf bank_mask:0xf
	v_fmac_f32_dpp v131, v242, v84 row_newbcast:10 row_mask:0xf bank_mask:0xf
	s_nop 0
	v_fmac_f32_dpp v239, v253, v20 row_newbcast:11 row_mask:0xf bank_mask:0xf
	v_fmac_f32_dpp v238, v253, v24 row_newbcast:13 row_mask:0xf bank_mask:0xf
	v_fmac_f32_dpp v130, v242, v90 row_newbcast:12 row_mask:0xf bank_mask:0xf
	v_fmac_f32_dpp v131, v242, v96 row_newbcast:14 row_mask:0xf bank_mask:0xf
	s_nop 0
	v_fmac_f32_dpp v239, v253, v30 row_newbcast:15 row_mask:0xf bank_mask:0xf
	v_fmac_f32_dpp v238, v242, v34 row_newbcast:1 row_mask:0xf bank_mask:0xf
	v_fmac_f32_dpp v130, v243, v102 row_newbcast:0 row_mask:0xf bank_mask:0xf
	v_fmac_f32_dpp v131, v243, v108 row_newbcast:2 row_mask:0xf bank_mask:0xf
	s_nop 0
	v_fmac_f32_dpp v239, v242, v40 row_newbcast:3 row_mask:0xf bank_mask:0xf
	v_fmac_f32_dpp v238, v242, v46 row_newbcast:5 row_mask:0xf bank_mask:0xf
	v_fmac_f32_dpp v130, v243, v116 row_newbcast:4 row_mask:0xf bank_mask:0xf
	v_fmac_f32_dpp v131, v243, v122 row_newbcast:6 row_mask:0xf bank_mask:0xf
	s_waitcnt lgkmcnt(0)
	v_add_u32_e32 v254, 0xb400, v208
	ds_read2_b32 v[248:249], v254 offset0:4 offset1:40
	v_fmac_f32_dpp v134, v246, v71 row_newbcast:0 row_mask:0xf bank_mask:0xf
	v_fmac_f32_dpp v135, v246, v235 row_newbcast:2 row_mask:0xf bank_mask:0xf
	v_fmac_f32_dpp v239, v242, v74 row_newbcast:7 row_mask:0xf bank_mask:0xf
	v_fmac_f32_dpp v238, v242, v80 row_newbcast:9 row_mask:0xf bank_mask:0xf
	v_add_u32_e32 v1, 0xb400, v208
	v_fmac_f32_dpp v239, v242, v86 row_newbcast:11 row_mask:0xf bank_mask:0xf
	v_fmac_f32_dpp v238, v242, v92 row_newbcast:13 row_mask:0xf bank_mask:0xf
	v_fmac_f32_dpp v134, v246, v4 row_newbcast:4 row_mask:0xf bank_mask:0xf
	v_fmac_f32_dpp v135, v246, v8 row_newbcast:6 row_mask:0xf bank_mask:0xf
	s_nop 0
	v_fmac_f32_dpp v239, v242, v98 row_newbcast:15 row_mask:0xf bank_mask:0xf
	v_fmac_f32_dpp v238, v243, v106 row_newbcast:1 row_mask:0xf bank_mask:0xf
	v_fmac_f32_dpp v134, v246, v12 row_newbcast:8 row_mask:0xf bank_mask:0xf
	v_fmac_f32_dpp v135, v246, v18 row_newbcast:10 row_mask:0xf bank_mask:0xf
	s_nop 0
	v_fmac_f32_dpp v239, v243, v112 row_newbcast:3 row_mask:0xf bank_mask:0xf
	v_fmac_f32_dpp v238, v243, v118 row_newbcast:5 row_mask:0xf bank_mask:0xf
	v_fmac_f32_dpp v134, v246, v22 row_newbcast:12 row_mask:0xf bank_mask:0xf
	v_fmac_f32_dpp v135, v246, v26 row_newbcast:14 row_mask:0xf bank_mask:0xf
	s_nop 0
	v_fmac_f32_dpp v239, v243, v126 row_newbcast:7 row_mask:0xf bank_mask:0xf
	v_fmac_f32_dpp v134, v247, v32 row_newbcast:0 row_mask:0xf bank_mask:0xf
	v_fmac_f32_dpp v135, v247, v38 row_newbcast:2 row_mask:0xf bank_mask:0xf
	s_nop 0
	v_pk_add_f32 v[130:131], v[130:131], v[238:239]
	v_mov_b32_e32 v238, v57
	v_fmac_f32_dpp v238, v246, v234 row_newbcast:1 row_mask:0xf bank_mask:0xf
	v_mov_b32_e32 v239, v57
	v_fmac_f32_dpp v239, v246, v2 row_newbcast:3 row_mask:0xf bank_mask:0xf
	v_fmac_f32_dpp v238, v246, v6 row_newbcast:5 row_mask:0xf bank_mask:0xf
	v_fmac_f32_dpp v134, v247, v42 row_newbcast:4 row_mask:0xf bank_mask:0xf
	v_fmac_f32_dpp v135, v247, v72 row_newbcast:6 row_mask:0xf bank_mask:0xf
	v_pk_add_f32 v[130:131], v[130:131], v[130:131] op_sel:[0,1] op_sel_hi:[1,0]
	v_fmac_f32_dpp v239, v246, v10 row_newbcast:7 row_mask:0xf bank_mask:0xf
	v_fmac_f32_dpp v238, v246, v14 row_newbcast:9 row_mask:0xf bank_mask:0xf
	v_fmac_f32_dpp v134, v247, v78 row_newbcast:8 row_mask:0xf bank_mask:0xf
	v_fmac_f32_dpp v135, v247, v84 row_newbcast:10 row_mask:0xf bank_mask:0xf
	s_waitcnt lgkmcnt(0)
	v_add_u32_e32 v254, 0xb400, v208
	ds_read2_b32 v[250:251], v254 offset0:56 offset1:72
	v_fmac_f32_dpp v138, v249, v71 row_newbcast:0 row_mask:0xf bank_mask:0xf
	v_fmac_f32_dpp v139, v249, v235 row_newbcast:2 row_mask:0xf bank_mask:0xf
	v_fmac_f32_dpp v239, v246, v20 row_newbcast:11 row_mask:0xf bank_mask:0xf
	v_fmac_f32_dpp v238, v246, v24 row_newbcast:13 row_mask:0xf bank_mask:0xf
	v_fmac_f32_dpp v134, v247, v90 row_newbcast:12 row_mask:0xf bank_mask:0xf
	v_fmac_f32_dpp v135, v247, v96 row_newbcast:14 row_mask:0xf bank_mask:0xf
	s_nop 0
	v_fmac_f32_dpp v138, v249, v4 row_newbcast:4 row_mask:0xf bank_mask:0xf
	v_fmac_f32_dpp v139, v249, v8 row_newbcast:6 row_mask:0xf bank_mask:0xf
	v_fmac_f32_dpp v239, v246, v30 row_newbcast:15 row_mask:0xf bank_mask:0xf
	v_fmac_f32_dpp v238, v247, v34 row_newbcast:1 row_mask:0xf bank_mask:0xf
	v_fmac_f32_dpp v134, v248, v102 row_newbcast:0 row_mask:0xf bank_mask:0xf
	v_fmac_f32_dpp v135, v248, v108 row_newbcast:2 row_mask:0xf bank_mask:0xf
	s_nop 0
	v_fmac_f32_dpp v138, v249, v12 row_newbcast:8 row_mask:0xf bank_mask:0xf
	v_fmac_f32_dpp v139, v249, v18 row_newbcast:10 row_mask:0xf bank_mask:0xf
	v_fmac_f32_dpp v239, v247, v40 row_newbcast:3 row_mask:0xf bank_mask:0xf
	v_fmac_f32_dpp v238, v247, v46 row_newbcast:5 row_mask:0xf bank_mask:0xf
	v_fmac_f32_dpp v134, v248, v116 row_newbcast:4 row_mask:0xf bank_mask:0xf
	v_fmac_f32_dpp v135, v248, v122 row_newbcast:6 row_mask:0xf bank_mask:0xf
	s_nop 0
	v_fmac_f32_dpp v138, v249, v22 row_newbcast:12 row_mask:0xf bank_mask:0xf
	v_fmac_f32_dpp v139, v249, v26 row_newbcast:14 row_mask:0xf bank_mask:0xf
	v_fmac_f32_dpp v239, v247, v74 row_newbcast:7 row_mask:0xf bank_mask:0xf
	v_fmac_f32_dpp v238, v247, v80 row_newbcast:9 row_mask:0xf bank_mask:0xf
	v_fmac_f32_dpp v134, v248, v130 row_newbcast:8 row_mask:0xf bank_mask:0xf
	s_nop 0
	v_fmac_f32_dpp v239, v247, v86 row_newbcast:11 row_mask:0xf bank_mask:0xf
	v_fmac_f32_dpp v238, v247, v92 row_newbcast:13 row_mask:0xf bank_mask:0xf
	s_nop 0
	v_fmac_f32_dpp v239, v247, v98 row_newbcast:15 row_mask:0xf bank_mask:0xf
	v_fmac_f32_dpp v238, v248, v106 row_newbcast:1 row_mask:0xf bank_mask:0xf
	s_nop 0
	v_fmac_f32_dpp v239, v248, v112 row_newbcast:3 row_mask:0xf bank_mask:0xf
	v_fmac_f32_dpp v238, v248, v118 row_newbcast:5 row_mask:0xf bank_mask:0xf
	s_waitcnt lgkmcnt(0)
; #define LAS __attribute__((address_space(3)))
; __device__ __forceinline__ void dn_prep_item(const Args& a, LAS unsigned char* lds, int item, int tid, int wave, int lane, int& cwh, int next_item) {
;     ...
;         { const LAS float* lrow = Lm + (lane & 15);
; #pragma unroll
;         for (int i = 1; i < 64; ++i) { float sa[4] = { x[i], 0.f, 0.f, 0.f };
;             int lr[4];
; #pragma unroll
;             for (int g = 0; g < (i + 15) / 16; ++g) lr[g] = __float_as_int(lrow[i * 68 + 16 * g]);
; #pragma unroll
;             for (int j = 0; j < i; ++j) { fmac_rowbcast_sel(sa[j & 3], lr[j >> 4], x[j], j); }
;             x[i] = (sa[0] + sa[1]) + (sa[2] + sa[3]); } }
	v_add_u32_e32 v254, 0xb400, v208
	ds_read2_b32 v[252:253], v254 offset0:108 offset1:124
	v_fmac_f32_dpp v138, v250, v32 row_newbcast:0 row_mask:0xf bank_mask:0xf
	v_fmac_f32_dpp v139, v250, v38 row_newbcast:2 row_mask:0xf bank_mask:0xf
	v_fmac_f32_dpp v239, v248, v126 row_newbcast:7 row_mask:0xf bank_mask:0xf
	s_nop 0
	v_fmac_f32_dpp v138, v250, v42 row_newbcast:4 row_mask:0xf bank_mask:0xf
	v_fmac_f32_dpp v139, v250, v72 row_newbcast:6 row_mask:0xf bank_mask:0xf
	v_pk_add_f32 v[134:135], v[134:135], v[238:239]
	v_mov_b32_e32 v238, v57
	v_fmac_f32_dpp v238, v249, v234 row_newbcast:1 row_mask:0xf bank_mask:0xf
	v_mov_b32_e32 v239, v57
	v_fmac_f32_dpp v238, v249, v6 row_newbcast:5 row_mask:0xf bank_mask:0xf
	v_fmac_f32_dpp v239, v249, v2 row_newbcast:3 row_mask:0xf bank_mask:0xf
	v_fmac_f32_dpp v138, v250, v78 row_newbcast:8 row_mask:0xf bank_mask:0xf
	v_fmac_f32_dpp v139, v250, v84 row_newbcast:10 row_mask:0xf bank_mask:0xf
	v_pk_add_f32 v[134:135], v[134:135], v[134:135] op_sel:[0,1] op_sel_hi:[1,0]
	v_fmac_f32_dpp v238, v249, v14 row_newbcast:9 row_mask:0xf bank_mask:0xf
	v_fmac_f32_dpp v239, v249, v10 row_newbcast:7 row_mask:0xf bank_mask:0xf
	v_fmac_f32_dpp v138, v250, v90 row_newbcast:12 row_mask:0xf bank_mask:0xf
	v_fmac_f32_dpp v139, v250, v96 row_newbcast:14 row_mask:0xf bank_mask:0xf
	s_nop 0
	v_fmac_f32_dpp v238, v249, v24 row_newbcast:13 row_mask:0xf bank_mask:0xf
	v_fmac_f32_dpp v239, v249, v20 row_newbcast:11 row_mask:0xf bank_mask:0xf
	v_fmac_f32_dpp v138, v251, v102 row_newbcast:0 row_mask:0xf bank_mask:0xf
	v_fmac_f32_dpp v139, v251, v108 row_newbcast:2 row_mask:0xf bank_mask:0xf
	s_nop 0
	v_fmac_f32_dpp v238, v250, v34 row_newbcast:1 row_mask:0xf bank_mask:0xf
	v_fmac_f32_dpp v239, v249, v30 row_newbcast:15 row_mask:0xf bank_mask:0xf
	v_fmac_f32_dpp v138, v251, v116 row_newbcast:4 row_mask:0xf bank_mask:0xf
	v_fmac_f32_dpp v139, v251, v122 row_newbcast:6 row_mask:0xf bank_mask:0xf
	s_nop 0
	v_fmac_f32_dpp v238, v250, v46 row_newbcast:5 row_mask:0xf bank_mask:0xf
	v_fmac_f32_dpp v239, v250, v40 row_newbcast:3 row_mask:0xf bank_mask:0xf
	v_fmac_f32_dpp v138, v251, v130 row_newbcast:8 row_mask:0xf bank_mask:0xf
	s_waitcnt lgkmcnt(0)
	v_add_u32_e32 v254, 0xb400, v208
	ds_read2_b32 v[242:243], v254 offset0:140 offset1:176
	v_fmac_f32_dpp v142, v252, v71 row_newbcast:0 row_mask:0xf bank_mask:0xf
	v_fmac_f32_dpp v143, v252, v235 row_newbcast:2 row_mask:0xf bank_mask:0xf
	v_fmac_f32_dpp v238, v250, v80 row_newbcast:9 row_mask:0xf bank_mask:0xf
	v_fmac_f32_dpp v239, v250, v74 row_newbcast:7 row_mask:0xf bank_mask:0xf
	s_nop 0
	v_fmac_f32_dpp v142, v252, v4 row_newbcast:4 row_mask:0xf bank_mask:0xf
	v_fmac_f32_dpp v143, v252, v8 row_newbcast:6 row_mask:0xf bank_mask:0xf
	v_fmac_f32_dpp v238, v250, v92 row_newbcast:13 row_mask:0xf bank_mask:0xf
	v_fmac_f32_dpp v239, v250, v86 row_newbcast:11 row_mask:0xf bank_mask:0xf
	s_nop 0
	v_fmac_f32_dpp v142, v252, v12 row_newbcast:8 row_mask:0xf bank_mask:0xf
	v_fmac_f32_dpp v143, v252, v18 row_newbcast:10 row_mask:0xf bank_mask:0xf
	v_fmac_f32_dpp v238, v251, v106 row_newbcast:1 row_mask:0xf bank_mask:0xf
	v_fmac_f32_dpp v239, v250, v98 row_newbcast:15 row_mask:0xf bank_mask:0xf
	s_nop 0
	v_fmac_f32_dpp v142, v252, v22 row_newbcast:12 row_mask:0xf bank_mask:0xf
	v_fmac_f32_dpp v143, v252, v26 row_newbcast:14 row_mask:0xf bank_mask:0xf
	v_fmac_f32_dpp v238, v251, v118 row_newbcast:5 row_mask:0xf bank_mask:0xf
	v_fmac_f32_dpp v239, v251, v112 row_newbcast:3 row_mask:0xf bank_mask:0xf
	s_nop 0
	v_fmac_f32_dpp v142, v253, v32 row_newbcast:0 row_mask:0xf bank_mask:0xf
	v_fmac_f32_dpp v143, v253, v38 row_newbcast:2 row_mask:0xf bank_mask:0xf
	v_fmac_f32_dpp v238, v251, v134 row_newbcast:9 row_mask:0xf bank_mask:0xf
	v_fmac_f32_dpp v239, v251, v126 row_newbcast:7 row_mask:0xf bank_mask:0xf
	s_nop 0
	v_fmac_f32_dpp v142, v253, v42 row_newbcast:4 row_mask:0xf bank_mask:0xf
	v_fmac_f32_dpp v143, v253, v72 row_newbcast:6 row_mask:0xf bank_mask:0xf
	s_nop 0
	v_pk_add_f32 v[138:139], v[138:139], v[238:239]
	v_mov_b32_e32 v238, v57
	v_fmac_f32_dpp v238, v252, v234 row_newbcast:1 row_mask:0xf bank_mask:0xf
	v_mov_b32_e32 v239, v57
	v_fmac_f32_dpp v238, v252, v6 row_newbcast:5 row_mask:0xf bank_mask:0xf
	v_fmac_f32_dpp v239, v252, v2 row_newbcast:3 row_mask:0xf bank_mask:0xf
	v_fmac_f32_dpp v142, v253, v78 row_newbcast:8 row_mask:0xf bank_mask:0xf
	v_fmac_f32_dpp v143, v253, v84 row_newbcast:10 row_mask:0xf bank_mask:0xf
	v_pk_add_f32 v[138:139], v[138:139], v[138:139] op_sel:[0,1] op_sel_hi:[1,0]
	v_fmac_f32_dpp v238, v252, v14 row_newbcast:9 row_mask:0xf bank_mask:0xf
	v_fmac_f32_dpp v239, v252, v10 row_newbcast:7 row_mask:0xf bank_mask:0xf
	v_fmac_f32_dpp v142, v253, v90 row_newbcast:12 row_mask:0xf bank_mask:0xf
	v_fmac_f32_dpp v143, v253, v96 row_newbcast:14 row_mask:0xf bank_mask:0xf
	s_waitcnt lgkmcnt(0)
; #define LAS __attribute__((address_space(3)))
; __device__ __forceinline__ void dn_prep_item(const Args& a, LAS unsigned char* lds, int item, int tid, int wave, int lane, int& cwh, int next_item) {
;     ...
;         { const LAS float* lrow = Lm + (lane & 15);
; #pragma unroll
;         for (int i = 1; i < 64; ++i) { float sa[4] = { x[i], 0.f, 0.f, 0.f };
;             int lr[4];
; #pragma unroll
;             for (int g = 0; g < (i + 15) / 16; ++g) lr[g] = __float_as_int(lrow[i * 68 + 16 * g]);
; #pragma unroll
;             for (int j = 0; j < i; ++j) { fmac_rowbcast_sel(sa[j & 3], lr[j >> 4], x[j], j); }
;             x[i] = (sa[0] + sa[1]) + (sa[2] + sa[3]); } }
	v_add_u32_e32 v254, 0xb400, v208
	ds_read2_b32 v[246:247], v254 offset0:192 offset1:208
	v_fmac_f32_dpp v144, v243, v71 row_newbcast:0 row_mask:0xf bank_mask:0xf
	v_fmac_f32_dpp v145, v243, v235 row_newbcast:2 row_mask:0xf bank_mask:0xf
	v_fmac_f32_dpp v238, v252, v24 row_newbcast:13 row_mask:0xf bank_mask:0xf
	v_fmac_f32_dpp v239, v252, v20 row_newbcast:11 row_mask:0xf bank_mask:0xf
	v_fmac_f32_dpp v142, v242, v102 row_newbcast:0 row_mask:0xf bank_mask:0xf
	v_fmac_f32_dpp v143, v242, v108 row_newbcast:2 row_mask:0xf bank_mask:0xf
	s_nop 0
	v_fmac_f32_dpp v144, v243, v4 row_newbcast:4 row_mask:0xf bank_mask:0xf
	v_fmac_f32_dpp v145, v243, v8 row_newbcast:6 row_mask:0xf bank_mask:0xf
	v_fmac_f32_dpp v238, v253, v34 row_newbcast:1 row_mask:0xf bank_mask:0xf
	v_fmac_f32_dpp v239, v252, v30 row_newbcast:15 row_mask:0xf bank_mask:0xf
	v_fmac_f32_dpp v142, v242, v116 row_newbcast:4 row_mask:0xf bank_mask:0xf
	v_fmac_f32_dpp v143, v242, v122 row_newbcast:6 row_mask:0xf bank_mask:0xf
	s_nop 0
	v_fmac_f32_dpp v144, v243, v12 row_newbcast:8 row_mask:0xf bank_mask:0xf
	v_fmac_f32_dpp v145, v243, v18 row_newbcast:10 row_mask:0xf bank_mask:0xf
	v_fmac_f32_dpp v238, v253, v46 row_newbcast:5 row_mask:0xf bank_mask:0xf
	v_fmac_f32_dpp v239, v253, v40 row_newbcast:3 row_mask:0xf bank_mask:0xf
	v_fmac_f32_dpp v142, v242, v130 row_newbcast:8 row_mask:0xf bank_mask:0xf
	v_fmac_f32_dpp v143, v242, v138 row_newbcast:10 row_mask:0xf bank_mask:0xf
	s_nop 0
	v_fmac_f32_dpp v144, v243, v22 row_newbcast:12 row_mask:0xf bank_mask:0xf
	v_fmac_f32_dpp v145, v243, v26 row_newbcast:14 row_mask:0xf bank_mask:0xf
	v_fmac_f32_dpp v238, v253, v80 row_newbcast:9 row_mask:0xf bank_mask:0xf
	v_fmac_f32_dpp v239, v253, v74 row_newbcast:7 row_mask:0xf bank_mask:0xf
	s_nop 0
	v_fmac_f32_dpp v238, v253, v92 row_newbcast:13 row_mask:0xf bank_mask:0xf
	v_fmac_f32_dpp v239, v253, v86 row_newbcast:11 row_mask:0xf bank_mask:0xf
	s_nop 0
	v_fmac_f32_dpp v238, v242, v106 row_newbcast:1 row_mask:0xf bank_mask:0xf
	v_fmac_f32_dpp v239, v253, v98 row_newbcast:15 row_mask:0xf bank_mask:0xf
	s_nop 0
	v_fmac_f32_dpp v238, v242, v118 row_newbcast:5 row_mask:0xf bank_mask:0xf
	v_fmac_f32_dpp v239, v242, v112 row_newbcast:3 row_mask:0xf bank_mask:0xf
	s_waitcnt lgkmcnt(0)
	v_add_u32_e32 v254, 0xb600, v208
	ds_read2_b32 v[248:249], v254 offset0:116 offset1:132
	v_fmac_f32_dpp v144, v246, v32 row_newbcast:0 row_mask:0xf bank_mask:0xf
	v_fmac_f32_dpp v145, v246, v38 row_newbcast:2 row_mask:0xf bank_mask:0xf
	v_add_u32_e32 v1, 0xb600, v208
	v_fmac_f32_dpp v238, v242, v134 row_newbcast:9 row_mask:0xf bank_mask:0xf
	v_fmac_f32_dpp v239, v242, v126 row_newbcast:7 row_mask:0xf bank_mask:0xf
	v_fmac_f32_dpp v144, v246, v42 row_newbcast:4 row_mask:0xf bank_mask:0xf
	v_fmac_f32_dpp v145, v246, v72 row_newbcast:6 row_mask:0xf bank_mask:0xf
	s_nop 0
	v_pk_add_f32 v[142:143], v[142:143], v[238:239]
	v_mov_b32_e32 v238, v57
	v_fmac_f32_dpp v238, v243, v234 row_newbcast:1 row_mask:0xf bank_mask:0xf
	v_mov_b32_e32 v239, v57
	v_fmac_f32_dpp v239, v243, v2 row_newbcast:3 row_mask:0xf bank_mask:0xf
	v_fmac_f32_dpp v238, v243, v6 row_newbcast:5 row_mask:0xf bank_mask:0xf
	v_fmac_f32_dpp v144, v246, v78 row_newbcast:8 row_mask:0xf bank_mask:0xf
	v_fmac_f32_dpp v145, v246, v84 row_newbcast:10 row_mask:0xf bank_mask:0xf
	v_pk_add_f32 v[142:143], v[142:143], v[142:143] op_sel:[0,1] op_sel_hi:[1,0]
	v_fmac_f32_dpp v239, v243, v10 row_newbcast:7 row_mask:0xf bank_mask:0xf
	v_fmac_f32_dpp v238, v243, v14 row_newbcast:9 row_mask:0xf bank_mask:0xf
	v_fmac_f32_dpp v144, v246, v90 row_newbcast:12 row_mask:0xf bank_mask:0xf
	v_fmac_f32_dpp v145, v246, v96 row_newbcast:14 row_mask:0xf bank_mask:0xf
	s_nop 0
	v_fmac_f32_dpp v239, v243, v20 row_newbcast:11 row_mask:0xf bank_mask:0xf
	v_fmac_f32_dpp v238, v243, v24 row_newbcast:13 row_mask:0xf bank_mask:0xf
	v_fmac_f32_dpp v144, v247, v102 row_newbcast:0 row_mask:0xf bank_mask:0xf
	v_fmac_f32_dpp v145, v247, v108 row_newbcast:2 row_mask:0xf bank_mask:0xf
	s_nop 0
	v_fmac_f32_dpp v239, v243, v30 row_newbcast:15 row_mask:0xf bank_mask:0xf
	v_fmac_f32_dpp v238, v246, v34 row_newbcast:1 row_mask:0xf bank_mask:0xf
	v_fmac_f32_dpp v144, v247, v116 row_newbcast:4 row_mask:0xf bank_mask:0xf
	v_fmac_f32_dpp v145, v247, v122 row_newbcast:6 row_mask:0xf bank_mask:0xf
	s_nop 0
	v_fmac_f32_dpp v239, v246, v40 row_newbcast:3 row_mask:0xf bank_mask:0xf
	v_fmac_f32_dpp v238, v246, v46 row_newbcast:5 row_mask:0xf bank_mask:0xf
	v_fmac_f32_dpp v144, v247, v130 row_newbcast:8 row_mask:0xf bank_mask:0xf
	v_fmac_f32_dpp v145, v247, v138 row_newbcast:10 row_mask:0xf bank_mask:0xf
	s_waitcnt lgkmcnt(0)
; #define LAS __attribute__((address_space(3)))
; __device__ __forceinline__ void dn_prep_item(const Args& a, LAS unsigned char* lds, int item, int tid, int wave, int lane, int& cwh, int next_item) {
;     ...
;         { const LAS float* lrow = Lm + (lane & 15);
; #pragma unroll
;         for (int i = 1; i < 64; ++i) { float sa[4] = { x[i], 0.f, 0.f, 0.f };
;             int lr[4];
; #pragma unroll
;             for (int g = 0; g < (i + 15) / 16; ++g) lr[g] = __float_as_int(lrow[i * 68 + 16 * g]);
; #pragma unroll
;             for (int j = 0; j < i; ++j) { fmac_rowbcast_sel(sa[j & 3], lr[j >> 4], x[j], j); }
;             x[i] = (sa[0] + sa[1]) + (sa[2] + sa[3]); } }
	v_add_u32_e32 v254, 0xb800, v208
	ds_read2_b32 v[250:251], v254 offset0:20 offset1:56
	v_fmac_f32_dpp v140, v248, v71 row_newbcast:0 row_mask:0xf bank_mask:0xf
	v_fmac_f32_dpp v141, v248, v235 row_newbcast:2 row_mask:0xf bank_mask:0xf
	v_fmac_f32_dpp v239, v246, v74 row_newbcast:7 row_mask:0xf bank_mask:0xf
	v_fmac_f32_dpp v238, v246, v80 row_newbcast:9 row_mask:0xf bank_mask:0xf
	v_add_u32_e32 v1, 0xb800, v208
	v_fmac_f32_dpp v239, v246, v86 row_newbcast:11 row_mask:0xf bank_mask:0xf
	v_fmac_f32_dpp v238, v246, v92 row_newbcast:13 row_mask:0xf bank_mask:0xf
	v_fmac_f32_dpp v140, v248, v4 row_newbcast:4 row_mask:0xf bank_mask:0xf
	v_fmac_f32_dpp v141, v248, v8 row_newbcast:6 row_mask:0xf bank_mask:0xf
	s_nop 0
	v_fmac_f32_dpp v239, v246, v98 row_newbcast:15 row_mask:0xf bank_mask:0xf
	v_fmac_f32_dpp v238, v247, v106 row_newbcast:1 row_mask:0xf bank_mask:0xf
	v_fmac_f32_dpp v140, v248, v12 row_newbcast:8 row_mask:0xf bank_mask:0xf
	v_fmac_f32_dpp v141, v248, v18 row_newbcast:10 row_mask:0xf bank_mask:0xf
	s_nop 0
	v_fmac_f32_dpp v239, v247, v112 row_newbcast:3 row_mask:0xf bank_mask:0xf
	v_fmac_f32_dpp v238, v247, v118 row_newbcast:5 row_mask:0xf bank_mask:0xf
	v_fmac_f32_dpp v140, v248, v22 row_newbcast:12 row_mask:0xf bank_mask:0xf
	v_fmac_f32_dpp v141, v248, v26 row_newbcast:14 row_mask:0xf bank_mask:0xf
	s_nop 0
	v_fmac_f32_dpp v239, v247, v126 row_newbcast:7 row_mask:0xf bank_mask:0xf
	v_fmac_f32_dpp v238, v247, v134 row_newbcast:9 row_mask:0xf bank_mask:0xf
	v_fmac_f32_dpp v140, v249, v32 row_newbcast:0 row_mask:0xf bank_mask:0xf
	v_fmac_f32_dpp v141, v249, v38 row_newbcast:2 row_mask:0xf bank_mask:0xf
	s_nop 0
	v_fmac_f32_dpp v239, v247, v142 row_newbcast:11 row_mask:0xf bank_mask:0xf
	v_fmac_f32_dpp v140, v249, v42 row_newbcast:4 row_mask:0xf bank_mask:0xf
	v_fmac_f32_dpp v141, v249, v72 row_newbcast:6 row_mask:0xf bank_mask:0xf
	s_nop 0
	v_pk_add_f32 v[144:145], v[144:145], v[238:239]
	v_mov_b32_e32 v238, v57
	v_fmac_f32_dpp v238, v248, v234 row_newbcast:1 row_mask:0xf bank_mask:0xf
	v_mov_b32_e32 v239, v57
	v_fmac_f32_dpp v239, v248, v2 row_newbcast:3 row_mask:0xf bank_mask:0xf
	v_fmac_f32_dpp v238, v248, v6 row_newbcast:5 row_mask:0xf bank_mask:0xf
	v_fmac_f32_dpp v140, v249, v78 row_newbcast:8 row_mask:0xf bank_mask:0xf
	v_fmac_f32_dpp v141, v249, v84 row_newbcast:10 row_mask:0xf bank_mask:0xf
	v_pk_add_f32 v[144:145], v[144:145], v[144:145] op_sel:[0,1] op_sel_hi:[1,0]
	v_fmac_f32_dpp v239, v248, v10 row_newbcast:7 row_mask:0xf bank_mask:0xf
	v_fmac_f32_dpp v238, v248, v14 row_newbcast:9 row_mask:0xf bank_mask:0xf
	v_fmac_f32_dpp v140, v249, v90 row_newbcast:12 row_mask:0xf bank_mask:0xf
	v_fmac_f32_dpp v141, v249, v96 row_newbcast:14 row_mask:0xf bank_mask:0xf
	s_waitcnt lgkmcnt(0)
	v_add_u32_e32 v254, 0xb800, v208
	ds_read2_b32 v[252:253], v254 offset0:72 offset1:88
	v_fmac_f32_dpp v136, v251, v71 row_newbcast:0 row_mask:0xf bank_mask:0xf
	v_fmac_f32_dpp v137, v251, v235 row_newbcast:2 row_mask:0xf bank_mask:0xf
	v_fmac_f32_dpp v239, v248, v20 row_newbcast:11 row_mask:0xf bank_mask:0xf
	v_fmac_f32_dpp v238, v248, v24 row_newbcast:13 row_mask:0xf bank_mask:0xf
	v_fmac_f32_dpp v140, v250, v102 row_newbcast:0 row_mask:0xf bank_mask:0xf
	v_fmac_f32_dpp v141, v250, v108 row_newbcast:2 row_mask:0xf bank_mask:0xf
	s_nop 0
	v_fmac_f32_dpp v136, v251, v4 row_newbcast:4 row_mask:0xf bank_mask:0xf
	v_fmac_f32_dpp v137, v251, v8 row_newbcast:6 row_mask:0xf bank_mask:0xf
	v_fmac_f32_dpp v239, v248, v30 row_newbcast:15 row_mask:0xf bank_mask:0xf
	v_fmac_f32_dpp v238, v249, v34 row_newbcast:1 row_mask:0xf bank_mask:0xf
	v_fmac_f32_dpp v140, v250, v116 row_newbcast:4 row_mask:0xf bank_mask:0xf
	v_fmac_f32_dpp v141, v250, v122 row_newbcast:6 row_mask:0xf bank_mask:0xf
	s_nop 0
	v_fmac_f32_dpp v136, v251, v12 row_newbcast:8 row_mask:0xf bank_mask:0xf
	v_fmac_f32_dpp v137, v251, v18 row_newbcast:10 row_mask:0xf bank_mask:0xf
	v_fmac_f32_dpp v239, v249, v40 row_newbcast:3 row_mask:0xf bank_mask:0xf
	v_fmac_f32_dpp v238, v249, v46 row_newbcast:5 row_mask:0xf bank_mask:0xf
	v_fmac_f32_dpp v140, v250, v130 row_newbcast:8 row_mask:0xf bank_mask:0xf
	v_fmac_f32_dpp v141, v250, v138 row_newbcast:10 row_mask:0xf bank_mask:0xf
	s_nop 0
	v_fmac_f32_dpp v136, v251, v22 row_newbcast:12 row_mask:0xf bank_mask:0xf
	v_fmac_f32_dpp v137, v251, v26 row_newbcast:14 row_mask:0xf bank_mask:0xf
	v_fmac_f32_dpp v239, v249, v74 row_newbcast:7 row_mask:0xf bank_mask:0xf
	v_fmac_f32_dpp v238, v249, v80 row_newbcast:9 row_mask:0xf bank_mask:0xf
	v_fmac_f32_dpp v140, v250, v144 row_newbcast:12 row_mask:0xf bank_mask:0xf
	s_nop 0
	v_fmac_f32_dpp v239, v249, v86 row_newbcast:11 row_mask:0xf bank_mask:0xf
	v_fmac_f32_dpp v238, v249, v92 row_newbcast:13 row_mask:0xf bank_mask:0xf
	s_nop 0
	v_fmac_f32_dpp v239, v249, v98 row_newbcast:15 row_mask:0xf bank_mask:0xf
	v_fmac_f32_dpp v238, v250, v106 row_newbcast:1 row_mask:0xf bank_mask:0xf
	s_nop 0
	v_fmac_f32_dpp v239, v250, v112 row_newbcast:3 row_mask:0xf bank_mask:0xf
	v_fmac_f32_dpp v238, v250, v118 row_newbcast:5 row_mask:0xf bank_mask:0xf
	s_waitcnt lgkmcnt(0)
; #define LAS __attribute__((address_space(3)))
; __device__ __forceinline__ void dn_prep_item(const Args& a, LAS unsigned char* lds, int item, int tid, int wave, int lane, int& cwh, int next_item) {
;     ...
;         { const LAS float* lrow = Lm + (lane & 15);
; #pragma unroll
;         for (int i = 1; i < 64; ++i) { float sa[4] = { x[i], 0.f, 0.f, 0.f };
;             int lr[4];
; #pragma unroll
;             for (int g = 0; g < (i + 15) / 16; ++g) lr[g] = __float_as_int(lrow[i * 68 + 16 * g]);
; #pragma unroll
;             for (int j = 0; j < i; ++j) { fmac_rowbcast_sel(sa[j & 3], lr[j >> 4], x[j], j); }
;             x[i] = (sa[0] + sa[1]) + (sa[2] + sa[3]); } }
	v_add_u32_e32 v254, 0xb800, v208
	ds_read2_b32 v[242:243], v254 offset0:124 offset1:140
	v_fmac_f32_dpp v136, v252, v32 row_newbcast:0 row_mask:0xf bank_mask:0xf
	v_fmac_f32_dpp v137, v252, v38 row_newbcast:2 row_mask:0xf bank_mask:0xf
	v_fmac_f32_dpp v239, v250, v126 row_newbcast:7 row_mask:0xf bank_mask:0xf
	v_fmac_f32_dpp v238, v250, v134 row_newbcast:9 row_mask:0xf bank_mask:0xf
	s_nop 0
	v_fmac_f32_dpp v136, v252, v42 row_newbcast:4 row_mask:0xf bank_mask:0xf
	v_fmac_f32_dpp v137, v252, v72 row_newbcast:6 row_mask:0xf bank_mask:0xf
	v_fmac_f32_dpp v239, v250, v142 row_newbcast:11 row_mask:0xf bank_mask:0xf
	s_nop 0
	v_fmac_f32_dpp v136, v252, v78 row_newbcast:8 row_mask:0xf bank_mask:0xf
	v_fmac_f32_dpp v137, v252, v84 row_newbcast:10 row_mask:0xf bank_mask:0xf
	v_pk_add_f32 v[140:141], v[140:141], v[238:239]
	v_mov_b32_e32 v238, v57
	v_fmac_f32_dpp v238, v251, v234 row_newbcast:1 row_mask:0xf bank_mask:0xf
	v_mov_b32_e32 v239, v57
	v_fmac_f32_dpp v238, v251, v6 row_newbcast:5 row_mask:0xf bank_mask:0xf
	v_fmac_f32_dpp v239, v251, v2 row_newbcast:3 row_mask:0xf bank_mask:0xf
	v_fmac_f32_dpp v136, v252, v90 row_newbcast:12 row_mask:0xf bank_mask:0xf
	v_fmac_f32_dpp v137, v252, v96 row_newbcast:14 row_mask:0xf bank_mask:0xf
	v_pk_add_f32 v[140:141], v[140:141], v[140:141] op_sel:[0,1] op_sel_hi:[1,0]
	v_fmac_f32_dpp v238, v251, v14 row_newbcast:9 row_mask:0xf bank_mask:0xf
	v_fmac_f32_dpp v239, v251, v10 row_newbcast:7 row_mask:0xf bank_mask:0xf
	v_fmac_f32_dpp v136, v253, v102 row_newbcast:0 row_mask:0xf bank_mask:0xf
	v_fmac_f32_dpp v137, v253, v108 row_newbcast:2 row_mask:0xf bank_mask:0xf
	s_nop 0
	v_fmac_f32_dpp v238, v251, v24 row_newbcast:13 row_mask:0xf bank_mask:0xf
	v_fmac_f32_dpp v239, v251, v20 row_newbcast:11 row_mask:0xf bank_mask:0xf
	v_fmac_f32_dpp v136, v253, v116 row_newbcast:4 row_mask:0xf bank_mask:0xf
	v_fmac_f32_dpp v137, v253, v122 row_newbcast:6 row_mask:0xf bank_mask:0xf
	s_nop 0
	v_fmac_f32_dpp v238, v252, v34 row_newbcast:1 row_mask:0xf bank_mask:0xf
	v_fmac_f32_dpp v239, v251, v30 row_newbcast:15 row_mask:0xf bank_mask:0xf
	v_fmac_f32_dpp v136, v253, v130 row_newbcast:8 row_mask:0xf bank_mask:0xf
	v_fmac_f32_dpp v137, v253, v138 row_newbcast:10 row_mask:0xf bank_mask:0xf
	s_nop 0
	v_fmac_f32_dpp v238, v252, v46 row_newbcast:5 row_mask:0xf bank_mask:0xf
	v_fmac_f32_dpp v239, v252, v40 row_newbcast:3 row_mask:0xf bank_mask:0xf
	v_fmac_f32_dpp v136, v253, v144 row_newbcast:12 row_mask:0xf bank_mask:0xf
	s_waitcnt lgkmcnt(0)
	v_add_u32_e32 v254, 0xb800, v208
	ds_read2_b32 v[246:247], v254 offset0:156 offset1:192
	v_fmac_f32_dpp v132, v242, v71 row_newbcast:0 row_mask:0xf bank_mask:0xf
	v_fmac_f32_dpp v133, v242, v235 row_newbcast:2 row_mask:0xf bank_mask:0xf
	v_fmac_f32_dpp v238, v252, v80 row_newbcast:9 row_mask:0xf bank_mask:0xf
	v_fmac_f32_dpp v239, v252, v74 row_newbcast:7 row_mask:0xf bank_mask:0xf
	s_nop 0
	v_fmac_f32_dpp v132, v242, v4 row_newbcast:4 row_mask:0xf bank_mask:0xf
	v_fmac_f32_dpp v133, v242, v8 row_newbcast:6 row_mask:0xf bank_mask:0xf
	v_fmac_f32_dpp v238, v252, v92 row_newbcast:13 row_mask:0xf bank_mask:0xf
	v_fmac_f32_dpp v239, v252, v86 row_newbcast:11 row_mask:0xf bank_mask:0xf
	s_nop 0
	v_fmac_f32_dpp v132, v242, v12 row_newbcast:8 row_mask:0xf bank_mask:0xf
	v_fmac_f32_dpp v133, v242, v18 row_newbcast:10 row_mask:0xf bank_mask:0xf
	v_fmac_f32_dpp v238, v253, v106 row_newbcast:1 row_mask:0xf bank_mask:0xf
	v_fmac_f32_dpp v239, v252, v98 row_newbcast:15 row_mask:0xf bank_mask:0xf
	s_nop 0
	v_fmac_f32_dpp v132, v242, v22 row_newbcast:12 row_mask:0xf bank_mask:0xf
	v_fmac_f32_dpp v133, v242, v26 row_newbcast:14 row_mask:0xf bank_mask:0xf
	v_fmac_f32_dpp v238, v253, v118 row_newbcast:5 row_mask:0xf bank_mask:0xf
	v_fmac_f32_dpp v239, v253, v112 row_newbcast:3 row_mask:0xf bank_mask:0xf
	s_nop 0
	v_fmac_f32_dpp v132, v243, v32 row_newbcast:0 row_mask:0xf bank_mask:0xf
	v_fmac_f32_dpp v133, v243, v38 row_newbcast:2 row_mask:0xf bank_mask:0xf
	v_fmac_f32_dpp v238, v253, v134 row_newbcast:9 row_mask:0xf bank_mask:0xf
	v_fmac_f32_dpp v239, v253, v126 row_newbcast:7 row_mask:0xf bank_mask:0xf
	s_nop 0
	v_fmac_f32_dpp v132, v243, v42 row_newbcast:4 row_mask:0xf bank_mask:0xf
	v_fmac_f32_dpp v133, v243, v72 row_newbcast:6 row_mask:0xf bank_mask:0xf
	v_fmac_f32_dpp v238, v253, v140 row_newbcast:13 row_mask:0xf bank_mask:0xf
	v_fmac_f32_dpp v239, v253, v142 row_newbcast:11 row_mask:0xf bank_mask:0xf
	s_nop 0
	v_fmac_f32_dpp v132, v243, v78 row_newbcast:8 row_mask:0xf bank_mask:0xf
	v_fmac_f32_dpp v133, v243, v84 row_newbcast:10 row_mask:0xf bank_mask:0xf
	s_nop 0
	v_pk_add_f32 v[136:137], v[136:137], v[238:239]
	v_mov_b32_e32 v238, v57
	v_fmac_f32_dpp v238, v242, v234 row_newbcast:1 row_mask:0xf bank_mask:0xf
	v_mov_b32_e32 v239, v57
	v_fmac_f32_dpp v238, v242, v6 row_newbcast:5 row_mask:0xf bank_mask:0xf
	v_fmac_f32_dpp v239, v242, v2 row_newbcast:3 row_mask:0xf bank_mask:0xf
	v_fmac_f32_dpp v132, v243, v90 row_newbcast:12 row_mask:0xf bank_mask:0xf
	v_fmac_f32_dpp v133, v243, v96 row_newbcast:14 row_mask:0xf bank_mask:0xf
	v_pk_add_f32 v[136:137], v[136:137], v[136:137] op_sel:[0,1] op_sel_hi:[1,0]
	v_fmac_f32_dpp v238, v242, v14 row_newbcast:9 row_mask:0xf bank_mask:0xf
	v_fmac_f32_dpp v239, v242, v10 row_newbcast:7 row_mask:0xf bank_mask:0xf
	s_waitcnt lgkmcnt(0)
; #define LAS __attribute__((address_space(3)))
; __device__ __forceinline__ void dn_prep_item(const Args& a, LAS unsigned char* lds, int item, int tid, int wave, int lane, int& cwh, int next_item) {
;     ...
;         { const LAS float* lrow = Lm + (lane & 15);
; #pragma unroll
;         for (int i = 1; i < 64; ++i) { float sa[4] = { x[i], 0.f, 0.f, 0.f };
;             int lr[4];
; #pragma unroll
;             for (int g = 0; g < (i + 15) / 16; ++g) lr[g] = __float_as_int(lrow[i * 68 + 16 * g]);
; #pragma unroll
;             for (int j = 0; j < i; ++j) { fmac_rowbcast_sel(sa[j & 3], lr[j >> 4], x[j], j); }
;             x[i] = (sa[0] + sa[1]) + (sa[2] + sa[3]); } }
	v_add_u32_e32 v254, 0xb800, v208
	ds_read2_b32 v[248:249], v254 offset0:208 offset1:224
	v_fmac_f32_dpp v132, v246, v102 row_newbcast:0 row_mask:0xf bank_mask:0xf
	v_fmac_f32_dpp v133, v246, v108 row_newbcast:2 row_mask:0xf bank_mask:0xf
	v_fmac_f32_dpp v128, v247, v71 row_newbcast:0 row_mask:0xf bank_mask:0xf
	v_fmac_f32_dpp v129, v247, v235 row_newbcast:2 row_mask:0xf bank_mask:0xf
	v_fmac_f32_dpp v238, v242, v24 row_newbcast:13 row_mask:0xf bank_mask:0xf
	v_fmac_f32_dpp v239, v242, v20 row_newbcast:11 row_mask:0xf bank_mask:0xf
	s_nop 0
	v_fmac_f32_dpp v132, v246, v116 row_newbcast:4 row_mask:0xf bank_mask:0xf
	v_fmac_f32_dpp v133, v246, v122 row_newbcast:6 row_mask:0xf bank_mask:0xf
	v_fmac_f32_dpp v128, v247, v4 row_newbcast:4 row_mask:0xf bank_mask:0xf
	v_fmac_f32_dpp v129, v247, v8 row_newbcast:6 row_mask:0xf bank_mask:0xf
	v_fmac_f32_dpp v238, v243, v34 row_newbcast:1 row_mask:0xf bank_mask:0xf
	v_fmac_f32_dpp v239, v242, v30 row_newbcast:15 row_mask:0xf bank_mask:0xf
	s_nop 0
	v_fmac_f32_dpp v132, v246, v130 row_newbcast:8 row_mask:0xf bank_mask:0xf
	v_fmac_f32_dpp v133, v246, v138 row_newbcast:10 row_mask:0xf bank_mask:0xf
	v_fmac_f32_dpp v128, v247, v12 row_newbcast:8 row_mask:0xf bank_mask:0xf
	v_fmac_f32_dpp v129, v247, v18 row_newbcast:10 row_mask:0xf bank_mask:0xf
	v_fmac_f32_dpp v238, v243, v46 row_newbcast:5 row_mask:0xf bank_mask:0xf
	v_fmac_f32_dpp v239, v243, v40 row_newbcast:3 row_mask:0xf bank_mask:0xf
	s_nop 0
	v_fmac_f32_dpp v132, v246, v144 row_newbcast:12 row_mask:0xf bank_mask:0xf
	v_fmac_f32_dpp v133, v246, v136 row_newbcast:14 row_mask:0xf bank_mask:0xf
	v_fmac_f32_dpp v128, v247, v22 row_newbcast:12 row_mask:0xf bank_mask:0xf
	v_fmac_f32_dpp v129, v247, v26 row_newbcast:14 row_mask:0xf bank_mask:0xf
	v_fmac_f32_dpp v238, v243, v80 row_newbcast:9 row_mask:0xf bank_mask:0xf
	v_fmac_f32_dpp v239, v243, v74 row_newbcast:7 row_mask:0xf bank_mask:0xf
	s_nop 0
	v_fmac_f32_dpp v238, v243, v92 row_newbcast:13 row_mask:0xf bank_mask:0xf
	v_fmac_f32_dpp v239, v243, v86 row_newbcast:11 row_mask:0xf bank_mask:0xf
	s_nop 0
	v_fmac_f32_dpp v238, v246, v106 row_newbcast:1 row_mask:0xf bank_mask:0xf
	v_fmac_f32_dpp v239, v243, v98 row_newbcast:15 row_mask:0xf bank_mask:0xf
	s_nop 0
	v_fmac_f32_dpp v238, v246, v118 row_newbcast:5 row_mask:0xf bank_mask:0xf
	v_fmac_f32_dpp v239, v246, v112 row_newbcast:3 row_mask:0xf bank_mask:0xf
	s_waitcnt lgkmcnt(0)
	v_add_u32_e32 v254, 0xbc00, v208
	ds_read2_b32 v[250:251], v254 offset0:4 offset1:20
	v_fmac_f32_dpp v128, v248, v32 row_newbcast:0 row_mask:0xf bank_mask:0xf
	v_fmac_f32_dpp v129, v248, v38 row_newbcast:2 row_mask:0xf bank_mask:0xf
	v_add_u32_e32 v1, 0xbc00, v208
	v_fmac_f32_dpp v238, v246, v134 row_newbcast:9 row_mask:0xf bank_mask:0xf
	v_fmac_f32_dpp v239, v246, v126 row_newbcast:7 row_mask:0xf bank_mask:0xf
	v_fmac_f32_dpp v128, v248, v42 row_newbcast:4 row_mask:0xf bank_mask:0xf
	v_fmac_f32_dpp v129, v248, v72 row_newbcast:6 row_mask:0xf bank_mask:0xf
	s_nop 0
	v_fmac_f32_dpp v238, v246, v140 row_newbcast:13 row_mask:0xf bank_mask:0xf
	v_fmac_f32_dpp v239, v246, v142 row_newbcast:11 row_mask:0xf bank_mask:0xf
	v_fmac_f32_dpp v128, v248, v78 row_newbcast:8 row_mask:0xf bank_mask:0xf
	v_fmac_f32_dpp v129, v248, v84 row_newbcast:10 row_mask:0xf bank_mask:0xf
	s_nop 0
	v_pk_add_f32 v[132:133], v[132:133], v[238:239]
	v_mov_b32_e32 v238, v57
	v_fmac_f32_dpp v238, v247, v234 row_newbcast:1 row_mask:0xf bank_mask:0xf
	v_mov_b32_e32 v239, v57
	v_fmac_f32_dpp v239, v247, v2 row_newbcast:3 row_mask:0xf bank_mask:0xf
	v_fmac_f32_dpp v238, v247, v6 row_newbcast:5 row_mask:0xf bank_mask:0xf
	v_fmac_f32_dpp v128, v248, v90 row_newbcast:12 row_mask:0xf bank_mask:0xf
	v_fmac_f32_dpp v129, v248, v96 row_newbcast:14 row_mask:0xf bank_mask:0xf
	v_pk_add_f32 v[132:133], v[132:133], v[132:133] op_sel:[0,1] op_sel_hi:[1,0]
	v_fmac_f32_dpp v239, v247, v10 row_newbcast:7 row_mask:0xf bank_mask:0xf
	v_fmac_f32_dpp v238, v247, v14 row_newbcast:9 row_mask:0xf bank_mask:0xf
	v_fmac_f32_dpp v128, v249, v102 row_newbcast:0 row_mask:0xf bank_mask:0xf
	v_fmac_f32_dpp v129, v249, v108 row_newbcast:2 row_mask:0xf bank_mask:0xf
	s_nop 0
	v_fmac_f32_dpp v239, v247, v20 row_newbcast:11 row_mask:0xf bank_mask:0xf
	v_fmac_f32_dpp v238, v247, v24 row_newbcast:13 row_mask:0xf bank_mask:0xf
	v_fmac_f32_dpp v128, v249, v116 row_newbcast:4 row_mask:0xf bank_mask:0xf
	v_fmac_f32_dpp v129, v249, v122 row_newbcast:6 row_mask:0xf bank_mask:0xf
	s_nop 0
	v_fmac_f32_dpp v239, v247, v30 row_newbcast:15 row_mask:0xf bank_mask:0xf
	v_fmac_f32_dpp v238, v248, v34 row_newbcast:1 row_mask:0xf bank_mask:0xf
	v_fmac_f32_dpp v128, v249, v130 row_newbcast:8 row_mask:0xf bank_mask:0xf
	v_fmac_f32_dpp v129, v249, v138 row_newbcast:10 row_mask:0xf bank_mask:0xf
	s_nop 0
	v_fmac_f32_dpp v239, v248, v40 row_newbcast:3 row_mask:0xf bank_mask:0xf
	v_fmac_f32_dpp v238, v248, v46 row_newbcast:5 row_mask:0xf bank_mask:0xf
	v_fmac_f32_dpp v128, v249, v144 row_newbcast:12 row_mask:0xf bank_mask:0xf
	v_fmac_f32_dpp v129, v249, v136 row_newbcast:14 row_mask:0xf bank_mask:0xf
	s_waitcnt lgkmcnt(0)
; #define LAS __attribute__((address_space(3)))
; __device__ __forceinline__ void dn_prep_item(const Args& a, LAS unsigned char* lds, int item, int tid, int wave, int lane, int& cwh, int next_item) {
;     ...
;         { const LAS float* lrow = Lm + (lane & 15);
; #pragma unroll
;         for (int i = 1; i < 64; ++i) { float sa[4] = { x[i], 0.f, 0.f, 0.f };
;             int lr[4];
; #pragma unroll
;             for (int g = 0; g < (i + 15) / 16; ++g) lr[g] = __float_as_int(lrow[i * 68 + 16 * g]);
; #pragma unroll
;             for (int j = 0; j < i; ++j) { fmac_rowbcast_sel(sa[j & 3], lr[j >> 4], x[j], j); }
;             x[i] = (sa[0] + sa[1]) + (sa[2] + sa[3]); } }
	v_add_u32_e32 v254, 0xbc00, v208
	ds_read2_b32 v[252:253], v254 offset0:36 offset1:52
	v_fmac_f32_dpp v124, v250, v71 row_newbcast:0 row_mask:0xf bank_mask:0xf
	v_fmac_f32_dpp v125, v250, v235 row_newbcast:2 row_mask:0xf bank_mask:0xf
	v_fmac_f32_dpp v239, v248, v74 row_newbcast:7 row_mask:0xf bank_mask:0xf
	v_fmac_f32_dpp v238, v248, v80 row_newbcast:9 row_mask:0xf bank_mask:0xf
	s_nop 0
	v_fmac_f32_dpp v239, v248, v86 row_newbcast:11 row_mask:0xf bank_mask:0xf
	v_fmac_f32_dpp v238, v248, v92 row_newbcast:13 row_mask:0xf bank_mask:0xf
	v_fmac_f32_dpp v124, v250, v4 row_newbcast:4 row_mask:0xf bank_mask:0xf
	v_fmac_f32_dpp v125, v250, v8 row_newbcast:6 row_mask:0xf bank_mask:0xf
	s_nop 0
	v_fmac_f32_dpp v239, v248, v98 row_newbcast:15 row_mask:0xf bank_mask:0xf
	v_fmac_f32_dpp v238, v249, v106 row_newbcast:1 row_mask:0xf bank_mask:0xf
	v_fmac_f32_dpp v124, v250, v12 row_newbcast:8 row_mask:0xf bank_mask:0xf
	v_fmac_f32_dpp v125, v250, v18 row_newbcast:10 row_mask:0xf bank_mask:0xf
	s_nop 0
	v_fmac_f32_dpp v239, v249, v112 row_newbcast:3 row_mask:0xf bank_mask:0xf
	v_fmac_f32_dpp v238, v249, v118 row_newbcast:5 row_mask:0xf bank_mask:0xf
	v_fmac_f32_dpp v124, v250, v22 row_newbcast:12 row_mask:0xf bank_mask:0xf
	v_fmac_f32_dpp v125, v250, v26 row_newbcast:14 row_mask:0xf bank_mask:0xf
	s_nop 0
	v_fmac_f32_dpp v239, v249, v126 row_newbcast:7 row_mask:0xf bank_mask:0xf
	v_fmac_f32_dpp v238, v249, v134 row_newbcast:9 row_mask:0xf bank_mask:0xf
	v_fmac_f32_dpp v124, v251, v32 row_newbcast:0 row_mask:0xf bank_mask:0xf
	v_fmac_f32_dpp v125, v251, v38 row_newbcast:2 row_mask:0xf bank_mask:0xf
	s_nop 0
	v_fmac_f32_dpp v239, v249, v142 row_newbcast:11 row_mask:0xf bank_mask:0xf
	v_fmac_f32_dpp v238, v249, v140 row_newbcast:13 row_mask:0xf bank_mask:0xf
	v_fmac_f32_dpp v124, v251, v42 row_newbcast:4 row_mask:0xf bank_mask:0xf
	v_fmac_f32_dpp v125, v251, v72 row_newbcast:6 row_mask:0xf bank_mask:0xf
	s_nop 0
	v_fmac_f32_dpp v239, v249, v132 row_newbcast:15 row_mask:0xf bank_mask:0xf
	v_fmac_f32_dpp v124, v251, v78 row_newbcast:8 row_mask:0xf bank_mask:0xf
	v_fmac_f32_dpp v125, v251, v84 row_newbcast:10 row_mask:0xf bank_mask:0xf
	s_nop 0
	v_pk_add_f32 v[128:129], v[128:129], v[238:239]
	v_mov_b32_e32 v238, v57
	v_fmac_f32_dpp v238, v250, v234 row_newbcast:1 row_mask:0xf bank_mask:0xf
	v_mov_b32_e32 v239, v57
	v_fmac_f32_dpp v239, v250, v2 row_newbcast:3 row_mask:0xf bank_mask:0xf
	v_fmac_f32_dpp v238, v250, v6 row_newbcast:5 row_mask:0xf bank_mask:0xf
	v_fmac_f32_dpp v124, v251, v90 row_newbcast:12 row_mask:0xf bank_mask:0xf
	v_fmac_f32_dpp v125, v251, v96 row_newbcast:14 row_mask:0xf bank_mask:0xf
	v_pk_add_f32 v[128:129], v[128:129], v[128:129] op_sel:[0,1] op_sel_hi:[1,0]
	v_fmac_f32_dpp v239, v250, v10 row_newbcast:7 row_mask:0xf bank_mask:0xf
	v_fmac_f32_dpp v238, v250, v14 row_newbcast:9 row_mask:0xf bank_mask:0xf
	s_waitcnt lgkmcnt(0)
	v_add_u32_e32 v254, 0xbc00, v208
	ds_read2_b32 v[242:243], v254 offset0:72 offset1:88
	v_fmac_f32_dpp v124, v252, v102 row_newbcast:0 row_mask:0xf bank_mask:0xf
	v_fmac_f32_dpp v125, v252, v108 row_newbcast:2 row_mask:0xf bank_mask:0xf
	v_fmac_f32_dpp v239, v250, v20 row_newbcast:11 row_mask:0xf bank_mask:0xf
	v_fmac_f32_dpp v238, v250, v24 row_newbcast:13 row_mask:0xf bank_mask:0xf
	s_nop 0
	v_fmac_f32_dpp v124, v252, v116 row_newbcast:4 row_mask:0xf bank_mask:0xf
	v_fmac_f32_dpp v125, v252, v122 row_newbcast:6 row_mask:0xf bank_mask:0xf
	v_fmac_f32_dpp v239, v250, v30 row_newbcast:15 row_mask:0xf bank_mask:0xf
	v_fmac_f32_dpp v238, v251, v34 row_newbcast:1 row_mask:0xf bank_mask:0xf
	s_nop 0
	v_fmac_f32_dpp v124, v252, v130 row_newbcast:8 row_mask:0xf bank_mask:0xf
	v_fmac_f32_dpp v125, v252, v138 row_newbcast:10 row_mask:0xf bank_mask:0xf
	v_fmac_f32_dpp v239, v251, v40 row_newbcast:3 row_mask:0xf bank_mask:0xf
	v_fmac_f32_dpp v238, v251, v46 row_newbcast:5 row_mask:0xf bank_mask:0xf
	s_nop 0
	v_fmac_f32_dpp v124, v252, v144 row_newbcast:12 row_mask:0xf bank_mask:0xf
	v_fmac_f32_dpp v125, v252, v136 row_newbcast:14 row_mask:0xf bank_mask:0xf
	v_fmac_f32_dpp v239, v251, v74 row_newbcast:7 row_mask:0xf bank_mask:0xf
	v_fmac_f32_dpp v238, v251, v80 row_newbcast:9 row_mask:0xf bank_mask:0xf
	s_nop 0
	v_fmac_f32_dpp v124, v253, v128 row_newbcast:0 row_mask:0xf bank_mask:0xf
	v_fmac_f32_dpp v239, v251, v86 row_newbcast:11 row_mask:0xf bank_mask:0xf
	v_fmac_f32_dpp v238, v251, v92 row_newbcast:13 row_mask:0xf bank_mask:0xf
	s_nop 0
	v_fmac_f32_dpp v239, v251, v98 row_newbcast:15 row_mask:0xf bank_mask:0xf
	v_fmac_f32_dpp v238, v252, v106 row_newbcast:1 row_mask:0xf bank_mask:0xf
	s_nop 0
	v_fmac_f32_dpp v239, v252, v112 row_newbcast:3 row_mask:0xf bank_mask:0xf
	v_fmac_f32_dpp v238, v252, v118 row_newbcast:5 row_mask:0xf bank_mask:0xf
	s_waitcnt lgkmcnt(0)
; #define LAS __attribute__((address_space(3)))
; __device__ __forceinline__ void dn_prep_item(const Args& a, LAS unsigned char* lds, int item, int tid, int wave, int lane, int& cwh, int next_item) {
;     ...
;         { const LAS float* lrow = Lm + (lane & 15);
; #pragma unroll
;         for (int i = 1; i < 64; ++i) { float sa[4] = { x[i], 0.f, 0.f, 0.f };
;             int lr[4];
; #pragma unroll
;             for (int g = 0; g < (i + 15) / 16; ++g) lr[g] = __float_as_int(lrow[i * 68 + 16 * g]);
; #pragma unroll
;             for (int j = 0; j < i; ++j) { fmac_rowbcast_sel(sa[j & 3], lr[j >> 4], x[j], j); }
;             x[i] = (sa[0] + sa[1]) + (sa[2] + sa[3]); } }
	v_add_u32_e32 v254, 0xbc00, v208
	ds_read2_b32 v[246:247], v254 offset0:104 offset1:120
	v_fmac_f32_dpp v120, v242, v71 row_newbcast:0 row_mask:0xf bank_mask:0xf
	v_fmac_f32_dpp v121, v242, v235 row_newbcast:2 row_mask:0xf bank_mask:0xf
	v_fmac_f32_dpp v239, v252, v126 row_newbcast:7 row_mask:0xf bank_mask:0xf
	v_fmac_f32_dpp v238, v252, v134 row_newbcast:9 row_mask:0xf bank_mask:0xf
	s_nop 0
	v_fmac_f32_dpp v120, v242, v4 row_newbcast:4 row_mask:0xf bank_mask:0xf
	v_fmac_f32_dpp v121, v242, v8 row_newbcast:6 row_mask:0xf bank_mask:0xf
	v_fmac_f32_dpp v239, v252, v142 row_newbcast:11 row_mask:0xf bank_mask:0xf
	v_fmac_f32_dpp v238, v252, v140 row_newbcast:13 row_mask:0xf bank_mask:0xf
	s_nop 0
	v_fmac_f32_dpp v120, v242, v12 row_newbcast:8 row_mask:0xf bank_mask:0xf
	v_fmac_f32_dpp v121, v242, v18 row_newbcast:10 row_mask:0xf bank_mask:0xf
	v_fmac_f32_dpp v239, v252, v132 row_newbcast:15 row_mask:0xf bank_mask:0xf
	s_nop 0
	v_fmac_f32_dpp v120, v242, v22 row_newbcast:12 row_mask:0xf bank_mask:0xf
	v_fmac_f32_dpp v121, v242, v26 row_newbcast:14 row_mask:0xf bank_mask:0xf
	s_nop 0
	v_pk_add_f32 v[124:125], v[124:125], v[238:239]
	v_mov_b32_e32 v238, v57
	v_fmac_f32_dpp v238, v242, v234 row_newbcast:1 row_mask:0xf bank_mask:0xf
	v_mov_b32_e32 v239, v57
	v_fmac_f32_dpp v238, v242, v6 row_newbcast:5 row_mask:0xf bank_mask:0xf
	v_fmac_f32_dpp v239, v242, v2 row_newbcast:3 row_mask:0xf bank_mask:0xf
	v_fmac_f32_dpp v120, v243, v32 row_newbcast:0 row_mask:0xf bank_mask:0xf
	v_fmac_f32_dpp v121, v243, v38 row_newbcast:2 row_mask:0xf bank_mask:0xf
	v_pk_add_f32 v[124:125], v[124:125], v[124:125] op_sel:[0,1] op_sel_hi:[1,0]
	v_fmac_f32_dpp v238, v242, v14 row_newbcast:9 row_mask:0xf bank_mask:0xf
	v_fmac_f32_dpp v239, v242, v10 row_newbcast:7 row_mask:0xf bank_mask:0xf
	v_fmac_f32_dpp v120, v243, v42 row_newbcast:4 row_mask:0xf bank_mask:0xf
	v_fmac_f32_dpp v121, v243, v72 row_newbcast:6 row_mask:0xf bank_mask:0xf
	s_nop 0
	v_fmac_f32_dpp v238, v242, v24 row_newbcast:13 row_mask:0xf bank_mask:0xf
	v_fmac_f32_dpp v239, v242, v20 row_newbcast:11 row_mask:0xf bank_mask:0xf
	v_fmac_f32_dpp v120, v243, v78 row_newbcast:8 row_mask:0xf bank_mask:0xf
	v_fmac_f32_dpp v121, v243, v84 row_newbcast:10 row_mask:0xf bank_mask:0xf
	s_nop 0
	v_fmac_f32_dpp v238, v243, v34 row_newbcast:1 row_mask:0xf bank_mask:0xf
	v_fmac_f32_dpp v239, v242, v30 row_newbcast:15 row_mask:0xf bank_mask:0xf
	v_fmac_f32_dpp v120, v243, v90 row_newbcast:12 row_mask:0xf bank_mask:0xf
	v_fmac_f32_dpp v121, v243, v96 row_newbcast:14 row_mask:0xf bank_mask:0xf
	s_nop 0
	v_fmac_f32_dpp v238, v243, v46 row_newbcast:5 row_mask:0xf bank_mask:0xf
	v_fmac_f32_dpp v239, v243, v40 row_newbcast:3 row_mask:0xf bank_mask:0xf
	s_waitcnt lgkmcnt(0)
	v_add_u32_e32 v254, 0xbc00, v208
	ds_read2_b32 v[248:249], v254 offset0:140 offset1:156
	v_fmac_f32_dpp v120, v246, v102 row_newbcast:0 row_mask:0xf bank_mask:0xf
	v_fmac_f32_dpp v121, v246, v108 row_newbcast:2 row_mask:0xf bank_mask:0xf
	v_fmac_f32_dpp v238, v243, v80 row_newbcast:9 row_mask:0xf bank_mask:0xf
	v_fmac_f32_dpp v239, v243, v74 row_newbcast:7 row_mask:0xf bank_mask:0xf
	s_nop 0
	v_fmac_f32_dpp v120, v246, v116 row_newbcast:4 row_mask:0xf bank_mask:0xf
	v_fmac_f32_dpp v121, v246, v122 row_newbcast:6 row_mask:0xf bank_mask:0xf
	v_fmac_f32_dpp v238, v243, v92 row_newbcast:13 row_mask:0xf bank_mask:0xf
	v_fmac_f32_dpp v239, v243, v86 row_newbcast:11 row_mask:0xf bank_mask:0xf
	s_nop 0
	v_fmac_f32_dpp v120, v246, v130 row_newbcast:8 row_mask:0xf bank_mask:0xf
	v_fmac_f32_dpp v121, v246, v138 row_newbcast:10 row_mask:0xf bank_mask:0xf
	v_fmac_f32_dpp v238, v246, v106 row_newbcast:1 row_mask:0xf bank_mask:0xf
	v_fmac_f32_dpp v239, v243, v98 row_newbcast:15 row_mask:0xf bank_mask:0xf
	s_nop 0
	v_fmac_f32_dpp v120, v246, v144 row_newbcast:12 row_mask:0xf bank_mask:0xf
	v_fmac_f32_dpp v121, v246, v136 row_newbcast:14 row_mask:0xf bank_mask:0xf
	s_nop 0
	v_fmac_f32_dpp v238, v246, v118 row_newbcast:5 row_mask:0xf bank_mask:0xf
	v_fmac_f32_dpp v239, v246, v112 row_newbcast:3 row_mask:0xf bank_mask:0xf
	v_fmac_f32_dpp v120, v247, v128 row_newbcast:0 row_mask:0xf bank_mask:0xf
	s_waitcnt lgkmcnt(0)
	v_add_u32_e32 v254, 0xbc00, v208
	ds_read2_b32 v[250:251], v254 offset0:172 offset1:188
	v_fmac_f32_dpp v114, v248, v71 row_newbcast:0 row_mask:0xf bank_mask:0xf
	v_fmac_f32_dpp v115, v248, v235 row_newbcast:2 row_mask:0xf bank_mask:0xf
	v_fmac_f32_dpp v238, v246, v134 row_newbcast:9 row_mask:0xf bank_mask:0xf
	v_fmac_f32_dpp v239, v246, v126 row_newbcast:7 row_mask:0xf bank_mask:0xf
	s_nop 0
	v_fmac_f32_dpp v114, v248, v4 row_newbcast:4 row_mask:0xf bank_mask:0xf
	v_fmac_f32_dpp v115, v248, v8 row_newbcast:6 row_mask:0xf bank_mask:0xf
	v_fmac_f32_dpp v238, v246, v140 row_newbcast:13 row_mask:0xf bank_mask:0xf
	v_fmac_f32_dpp v239, v246, v142 row_newbcast:11 row_mask:0xf bank_mask:0xf
	s_nop 0
	v_fmac_f32_dpp v114, v248, v12 row_newbcast:8 row_mask:0xf bank_mask:0xf
	v_fmac_f32_dpp v115, v248, v18 row_newbcast:10 row_mask:0xf bank_mask:0xf
	v_fmac_f32_dpp v238, v247, v124 row_newbcast:1 row_mask:0xf bank_mask:0xf
	v_fmac_f32_dpp v239, v246, v132 row_newbcast:15 row_mask:0xf bank_mask:0xf
	s_nop 0
	v_fmac_f32_dpp v114, v248, v22 row_newbcast:12 row_mask:0xf bank_mask:0xf
	v_fmac_f32_dpp v115, v248, v26 row_newbcast:14 row_mask:0xf bank_mask:0xf
	s_nop 0
	v_pk_add_f32 v[120:121], v[120:121], v[238:239]
	v_mov_b32_e32 v238, v57
	v_fmac_f32_dpp v238, v248, v234 row_newbcast:1 row_mask:0xf bank_mask:0xf
	v_mov_b32_e32 v239, v57
	v_fmac_f32_dpp v238, v248, v6 row_newbcast:5 row_mask:0xf bank_mask:0xf
	v_fmac_f32_dpp v239, v248, v2 row_newbcast:3 row_mask:0xf bank_mask:0xf
	v_fmac_f32_dpp v114, v249, v32 row_newbcast:0 row_mask:0xf bank_mask:0xf
	v_fmac_f32_dpp v115, v249, v38 row_newbcast:2 row_mask:0xf bank_mask:0xf
	v_pk_add_f32 v[120:121], v[120:121], v[120:121] op_sel:[0,1] op_sel_hi:[1,0]
	v_fmac_f32_dpp v238, v248, v14 row_newbcast:9 row_mask:0xf bank_mask:0xf
	v_fmac_f32_dpp v239, v248, v10 row_newbcast:7 row_mask:0xf bank_mask:0xf
	v_fmac_f32_dpp v114, v249, v42 row_newbcast:4 row_mask:0xf bank_mask:0xf
	v_fmac_f32_dpp v115, v249, v72 row_newbcast:6 row_mask:0xf bank_mask:0xf
	s_nop 0
	v_fmac_f32_dpp v238, v248, v24 row_newbcast:13 row_mask:0xf bank_mask:0xf
	v_fmac_f32_dpp v239, v248, v20 row_newbcast:11 row_mask:0xf bank_mask:0xf
	v_fmac_f32_dpp v114, v249, v78 row_newbcast:8 row_mask:0xf bank_mask:0xf
	v_fmac_f32_dpp v115, v249, v84 row_newbcast:10 row_mask:0xf bank_mask:0xf
	s_nop 0
	v_fmac_f32_dpp v238, v249, v34 row_newbcast:1 row_mask:0xf bank_mask:0xf
	v_fmac_f32_dpp v239, v248, v30 row_newbcast:15 row_mask:0xf bank_mask:0xf
	v_fmac_f32_dpp v114, v249, v90 row_newbcast:12 row_mask:0xf bank_mask:0xf
	v_fmac_f32_dpp v115, v249, v96 row_newbcast:14 row_mask:0xf bank_mask:0xf
	s_nop 0
	v_fmac_f32_dpp v238, v249, v46 row_newbcast:5 row_mask:0xf bank_mask:0xf
	v_fmac_f32_dpp v239, v249, v40 row_newbcast:3 row_mask:0xf bank_mask:0xf
	s_waitcnt lgkmcnt(0)
; #define LAS __attribute__((address_space(3)))
; __device__ __forceinline__ void dn_prep_item(const Args& a, LAS unsigned char* lds, int item, int tid, int wave, int lane, int& cwh, int next_item) {
;     ...
;         { const LAS float* lrow = Lm + (lane & 15);
; #pragma unroll
;         for (int i = 1; i < 64; ++i) { float sa[4] = { x[i], 0.f, 0.f, 0.f };
;             int lr[4];
; #pragma unroll
;             for (int g = 0; g < (i + 15) / 16; ++g) lr[g] = __float_as_int(lrow[i * 68 + 16 * g]);
; #pragma unroll
;             for (int j = 0; j < i; ++j) { fmac_rowbcast_sel(sa[j & 3], lr[j >> 4], x[j], j); }
;             x[i] = (sa[0] + sa[1]) + (sa[2] + sa[3]); } }
	v_add_u32_e32 v254, 0xbc00, v208
	ds_read2_b32 v[252:253], v254 offset0:208 offset1:224
	v_fmac_f32_dpp v114, v250, v102 row_newbcast:0 row_mask:0xf bank_mask:0xf
	v_fmac_f32_dpp v115, v250, v108 row_newbcast:2 row_mask:0xf bank_mask:0xf
	v_fmac_f32_dpp v238, v249, v80 row_newbcast:9 row_mask:0xf bank_mask:0xf
	v_fmac_f32_dpp v239, v249, v74 row_newbcast:7 row_mask:0xf bank_mask:0xf
	s_nop 0
	v_fmac_f32_dpp v114, v250, v116 row_newbcast:4 row_mask:0xf bank_mask:0xf
	v_fmac_f32_dpp v115, v250, v122 row_newbcast:6 row_mask:0xf bank_mask:0xf
	v_fmac_f32_dpp v238, v249, v92 row_newbcast:13 row_mask:0xf bank_mask:0xf
	v_fmac_f32_dpp v239, v249, v86 row_newbcast:11 row_mask:0xf bank_mask:0xf
	s_nop 0
	v_fmac_f32_dpp v114, v250, v130 row_newbcast:8 row_mask:0xf bank_mask:0xf
	v_fmac_f32_dpp v115, v250, v138 row_newbcast:10 row_mask:0xf bank_mask:0xf
	v_fmac_f32_dpp v238, v250, v106 row_newbcast:1 row_mask:0xf bank_mask:0xf
	v_fmac_f32_dpp v239, v249, v98 row_newbcast:15 row_mask:0xf bank_mask:0xf
	s_nop 0
	v_fmac_f32_dpp v114, v250, v144 row_newbcast:12 row_mask:0xf bank_mask:0xf
	v_fmac_f32_dpp v115, v250, v136 row_newbcast:14 row_mask:0xf bank_mask:0xf
	s_nop 0
	v_fmac_f32_dpp v238, v250, v118 row_newbcast:5 row_mask:0xf bank_mask:0xf
	v_fmac_f32_dpp v239, v250, v112 row_newbcast:3 row_mask:0xf bank_mask:0xf
	v_fmac_f32_dpp v114, v251, v128 row_newbcast:0 row_mask:0xf bank_mask:0xf
	v_fmac_f32_dpp v115, v251, v120 row_newbcast:2 row_mask:0xf bank_mask:0xf
	s_waitcnt lgkmcnt(0)
	v_add_u32_e32 v254, 0xbe00, v208
	ds_read2_b32 v[242:243], v254 offset0:112 offset1:128
	v_fmac_f32_dpp v110, v252, v71 row_newbcast:0 row_mask:0xf bank_mask:0xf
	v_fmac_f32_dpp v111, v252, v235 row_newbcast:2 row_mask:0xf bank_mask:0xf
	v_fmac_f32_dpp v238, v250, v134 row_newbcast:9 row_mask:0xf bank_mask:0xf
	v_fmac_f32_dpp v239, v250, v126 row_newbcast:7 row_mask:0xf bank_mask:0xf
	v_add_u32_e32 v1, 0xbe00, v208
	v_fmac_f32_dpp v238, v250, v140 row_newbcast:13 row_mask:0xf bank_mask:0xf
	v_fmac_f32_dpp v239, v250, v142 row_newbcast:11 row_mask:0xf bank_mask:0xf
	v_fmac_f32_dpp v110, v252, v4 row_newbcast:4 row_mask:0xf bank_mask:0xf
	v_fmac_f32_dpp v111, v252, v8 row_newbcast:6 row_mask:0xf bank_mask:0xf
	s_nop 0
	v_fmac_f32_dpp v238, v251, v124 row_newbcast:1 row_mask:0xf bank_mask:0xf
	v_fmac_f32_dpp v239, v250, v132 row_newbcast:15 row_mask:0xf bank_mask:0xf
	v_fmac_f32_dpp v110, v252, v12 row_newbcast:8 row_mask:0xf bank_mask:0xf
	v_fmac_f32_dpp v111, v252, v18 row_newbcast:10 row_mask:0xf bank_mask:0xf
	s_nop 0
	v_pk_add_f32 v[114:115], v[114:115], v[238:239]
	v_mov_b32_e32 v238, v57
	v_fmac_f32_dpp v238, v252, v234 row_newbcast:1 row_mask:0xf bank_mask:0xf
	v_mov_b32_e32 v239, v57
	v_fmac_f32_dpp v239, v252, v2 row_newbcast:3 row_mask:0xf bank_mask:0xf
	v_fmac_f32_dpp v238, v252, v6 row_newbcast:5 row_mask:0xf bank_mask:0xf
	v_fmac_f32_dpp v110, v252, v22 row_newbcast:12 row_mask:0xf bank_mask:0xf
	v_fmac_f32_dpp v111, v252, v26 row_newbcast:14 row_mask:0xf bank_mask:0xf
	v_add_u32_e32 v1, 0xc000, v208
	v_fmac_f32_dpp v239, v252, v10 row_newbcast:7 row_mask:0xf bank_mask:0xf
	v_fmac_f32_dpp v238, v252, v14 row_newbcast:9 row_mask:0xf bank_mask:0xf
	v_fmac_f32_dpp v110, v253, v32 row_newbcast:0 row_mask:0xf bank_mask:0xf
	v_fmac_f32_dpp v111, v253, v38 row_newbcast:2 row_mask:0xf bank_mask:0xf
	v_pk_add_f32 v[114:115], v[114:115], v[114:115] op_sel:[0,1] op_sel_hi:[1,0]
	v_fmac_f32_dpp v239, v252, v20 row_newbcast:11 row_mask:0xf bank_mask:0xf
	v_fmac_f32_dpp v238, v252, v24 row_newbcast:13 row_mask:0xf bank_mask:0xf
	v_fmac_f32_dpp v110, v253, v42 row_newbcast:4 row_mask:0xf bank_mask:0xf
	v_fmac_f32_dpp v111, v253, v72 row_newbcast:6 row_mask:0xf bank_mask:0xf
	s_nop 0
	v_fmac_f32_dpp v239, v252, v30 row_newbcast:15 row_mask:0xf bank_mask:0xf
	v_fmac_f32_dpp v238, v253, v34 row_newbcast:1 row_mask:0xf bank_mask:0xf
	v_fmac_f32_dpp v110, v253, v78 row_newbcast:8 row_mask:0xf bank_mask:0xf
	v_fmac_f32_dpp v111, v253, v84 row_newbcast:10 row_mask:0xf bank_mask:0xf
	s_nop 0
	v_fmac_f32_dpp v239, v253, v40 row_newbcast:3 row_mask:0xf bank_mask:0xf
	v_fmac_f32_dpp v238, v253, v46 row_newbcast:5 row_mask:0xf bank_mask:0xf
	v_fmac_f32_dpp v110, v253, v90 row_newbcast:12 row_mask:0xf bank_mask:0xf
	v_fmac_f32_dpp v111, v253, v96 row_newbcast:14 row_mask:0xf bank_mask:0xf
	s_nop 0
	v_fmac_f32_dpp v239, v253, v74 row_newbcast:7 row_mask:0xf bank_mask:0xf
	v_fmac_f32_dpp v238, v253, v80 row_newbcast:9 row_mask:0xf bank_mask:0xf
	s_waitcnt lgkmcnt(0)
	v_add_u32_e32 v254, 0xc000, v208
	ds_read2_b32 v[246:247], v254 offset0:20 offset1:36
	v_fmac_f32_dpp v110, v242, v102 row_newbcast:0 row_mask:0xf bank_mask:0xf
	v_fmac_f32_dpp v111, v242, v108 row_newbcast:2 row_mask:0xf bank_mask:0xf
	v_fmac_f32_dpp v239, v253, v86 row_newbcast:11 row_mask:0xf bank_mask:0xf
	v_fmac_f32_dpp v238, v253, v92 row_newbcast:13 row_mask:0xf bank_mask:0xf
	s_nop 0
	v_fmac_f32_dpp v110, v242, v116 row_newbcast:4 row_mask:0xf bank_mask:0xf
	v_fmac_f32_dpp v111, v242, v122 row_newbcast:6 row_mask:0xf bank_mask:0xf
	v_fmac_f32_dpp v239, v253, v98 row_newbcast:15 row_mask:0xf bank_mask:0xf
	v_fmac_f32_dpp v238, v242, v106 row_newbcast:1 row_mask:0xf bank_mask:0xf
	s_nop 0
	v_fmac_f32_dpp v110, v242, v130 row_newbcast:8 row_mask:0xf bank_mask:0xf
	v_fmac_f32_dpp v111, v242, v138 row_newbcast:10 row_mask:0xf bank_mask:0xf
	s_nop 0
	v_fmac_f32_dpp v239, v242, v112 row_newbcast:3 row_mask:0xf bank_mask:0xf
	v_fmac_f32_dpp v238, v242, v118 row_newbcast:5 row_mask:0xf bank_mask:0xf
	v_fmac_f32_dpp v110, v242, v144 row_newbcast:12 row_mask:0xf bank_mask:0xf
	v_fmac_f32_dpp v111, v242, v136 row_newbcast:14 row_mask:0xf bank_mask:0xf
	s_waitcnt lgkmcnt(0)
; #define LAS __attribute__((address_space(3)))
; __device__ __forceinline__ void dn_prep_item(const Args& a, LAS unsigned char* lds, int item, int tid, int wave, int lane, int& cwh, int next_item) {
;     ...
;         { const LAS float* lrow = Lm + (lane & 15);
; #pragma unroll
;         for (int i = 1; i < 64; ++i) { float sa[4] = { x[i], 0.f, 0.f, 0.f };
;             int lr[4];
; #pragma unroll
;             for (int g = 0; g < (i + 15) / 16; ++g) lr[g] = __float_as_int(lrow[i * 68 + 16 * g]);
; #pragma unroll
;             for (int j = 0; j < i; ++j) { fmac_rowbcast_sel(sa[j & 3], lr[j >> 4], x[j], j); }
;             x[i] = (sa[0] + sa[1]) + (sa[2] + sa[3]); } }
	v_add_u32_e32 v254, 0xc000, v208
	ds_read2_b32 v[248:249], v254 offset0:52 offset1:68
	v_fmac_f32_dpp v104, v246, v71 row_newbcast:0 row_mask:0xf bank_mask:0xf
	v_fmac_f32_dpp v105, v246, v235 row_newbcast:2 row_mask:0xf bank_mask:0xf
	v_fmac_f32_dpp v239, v242, v126 row_newbcast:7 row_mask:0xf bank_mask:0xf
	v_fmac_f32_dpp v238, v242, v134 row_newbcast:9 row_mask:0xf bank_mask:0xf
	v_fmac_f32_dpp v110, v243, v128 row_newbcast:0 row_mask:0xf bank_mask:0xf
	v_fmac_f32_dpp v111, v243, v120 row_newbcast:2 row_mask:0xf bank_mask:0xf
	s_nop 0
	v_fmac_f32_dpp v104, v246, v4 row_newbcast:4 row_mask:0xf bank_mask:0xf
	v_fmac_f32_dpp v105, v246, v8 row_newbcast:6 row_mask:0xf bank_mask:0xf
	v_fmac_f32_dpp v239, v242, v142 row_newbcast:11 row_mask:0xf bank_mask:0xf
	v_fmac_f32_dpp v238, v242, v140 row_newbcast:13 row_mask:0xf bank_mask:0xf
	s_nop 0
	v_fmac_f32_dpp v239, v242, v132 row_newbcast:15 row_mask:0xf bank_mask:0xf
	v_fmac_f32_dpp v238, v243, v124 row_newbcast:1 row_mask:0xf bank_mask:0xf
	v_fmac_f32_dpp v104, v246, v12 row_newbcast:8 row_mask:0xf bank_mask:0xf
	v_fmac_f32_dpp v105, v246, v18 row_newbcast:10 row_mask:0xf bank_mask:0xf
	s_nop 0
	v_fmac_f32_dpp v239, v243, v114 row_newbcast:3 row_mask:0xf bank_mask:0xf
	v_fmac_f32_dpp v104, v246, v22 row_newbcast:12 row_mask:0xf bank_mask:0xf
	v_fmac_f32_dpp v105, v246, v26 row_newbcast:14 row_mask:0xf bank_mask:0xf
	s_nop 0
	v_pk_add_f32 v[110:111], v[110:111], v[238:239]
	v_mov_b32_e32 v238, v57
	v_fmac_f32_dpp v238, v246, v234 row_newbcast:1 row_mask:0xf bank_mask:0xf
	v_mov_b32_e32 v239, v57
	v_fmac_f32_dpp v239, v246, v2 row_newbcast:3 row_mask:0xf bank_mask:0xf
	v_fmac_f32_dpp v238, v246, v6 row_newbcast:5 row_mask:0xf bank_mask:0xf
	v_fmac_f32_dpp v104, v247, v32 row_newbcast:0 row_mask:0xf bank_mask:0xf
	v_fmac_f32_dpp v105, v247, v38 row_newbcast:2 row_mask:0xf bank_mask:0xf
	v_pk_add_f32 v[110:111], v[110:111], v[110:111] op_sel:[0,1] op_sel_hi:[1,0]
	v_fmac_f32_dpp v239, v246, v10 row_newbcast:7 row_mask:0xf bank_mask:0xf
	v_fmac_f32_dpp v238, v246, v14 row_newbcast:9 row_mask:0xf bank_mask:0xf
	v_fmac_f32_dpp v104, v247, v42 row_newbcast:4 row_mask:0xf bank_mask:0xf
	v_fmac_f32_dpp v105, v247, v72 row_newbcast:6 row_mask:0xf bank_mask:0xf
	s_nop 0
	v_fmac_f32_dpp v239, v246, v20 row_newbcast:11 row_mask:0xf bank_mask:0xf
	v_fmac_f32_dpp v238, v246, v24 row_newbcast:13 row_mask:0xf bank_mask:0xf
	v_fmac_f32_dpp v104, v247, v78 row_newbcast:8 row_mask:0xf bank_mask:0xf
	v_fmac_f32_dpp v105, v247, v84 row_newbcast:10 row_mask:0xf bank_mask:0xf
	s_nop 0
	v_fmac_f32_dpp v239, v246, v30 row_newbcast:15 row_mask:0xf bank_mask:0xf
	v_fmac_f32_dpp v238, v247, v34 row_newbcast:1 row_mask:0xf bank_mask:0xf
	v_fmac_f32_dpp v104, v247, v90 row_newbcast:12 row_mask:0xf bank_mask:0xf
	v_fmac_f32_dpp v105, v247, v96 row_newbcast:14 row_mask:0xf bank_mask:0xf
	s_nop 0
	v_fmac_f32_dpp v239, v247, v40 row_newbcast:3 row_mask:0xf bank_mask:0xf
	v_fmac_f32_dpp v238, v247, v46 row_newbcast:5 row_mask:0xf bank_mask:0xf
	s_waitcnt lgkmcnt(0)
	v_add_u32_e32 v254, 0xc000, v208
	ds_read2_b32 v[250:251], v254 offset0:88 offset1:104
	v_fmac_f32_dpp v104, v248, v102 row_newbcast:0 row_mask:0xf bank_mask:0xf
	v_fmac_f32_dpp v105, v248, v108 row_newbcast:2 row_mask:0xf bank_mask:0xf
	v_fmac_f32_dpp v239, v247, v74 row_newbcast:7 row_mask:0xf bank_mask:0xf
	v_fmac_f32_dpp v238, v247, v80 row_newbcast:9 row_mask:0xf bank_mask:0xf
	s_nop 0
	v_fmac_f32_dpp v104, v248, v116 row_newbcast:4 row_mask:0xf bank_mask:0xf
	v_fmac_f32_dpp v105, v248, v122 row_newbcast:6 row_mask:0xf bank_mask:0xf
	v_fmac_f32_dpp v239, v247, v86 row_newbcast:11 row_mask:0xf bank_mask:0xf
	v_fmac_f32_dpp v238, v247, v92 row_newbcast:13 row_mask:0xf bank_mask:0xf
	s_nop 0
	v_fmac_f32_dpp v104, v248, v130 row_newbcast:8 row_mask:0xf bank_mask:0xf
	v_fmac_f32_dpp v105, v248, v138 row_newbcast:10 row_mask:0xf bank_mask:0xf
	v_fmac_f32_dpp v239, v247, v98 row_newbcast:15 row_mask:0xf bank_mask:0xf
	v_fmac_f32_dpp v238, v248, v106 row_newbcast:1 row_mask:0xf bank_mask:0xf
	s_nop 0
	v_fmac_f32_dpp v104, v248, v144 row_newbcast:12 row_mask:0xf bank_mask:0xf
	v_fmac_f32_dpp v105, v248, v136 row_newbcast:14 row_mask:0xf bank_mask:0xf
	s_nop 0
	v_fmac_f32_dpp v239, v248, v112 row_newbcast:3 row_mask:0xf bank_mask:0xf
	v_fmac_f32_dpp v238, v248, v118 row_newbcast:5 row_mask:0xf bank_mask:0xf
	v_fmac_f32_dpp v104, v249, v128 row_newbcast:0 row_mask:0xf bank_mask:0xf
	v_fmac_f32_dpp v105, v249, v120 row_newbcast:2 row_mask:0xf bank_mask:0xf
	s_waitcnt lgkmcnt(0)
; #define LAS __attribute__((address_space(3)))
; __device__ __forceinline__ void dn_prep_item(const Args& a, LAS unsigned char* lds, int item, int tid, int wave, int lane, int& cwh, int next_item) {
;     ...
;         { const LAS float* lrow = Lm + (lane & 15);
; #pragma unroll
;         for (int i = 1; i < 64; ++i) { float sa[4] = { x[i], 0.f, 0.f, 0.f };
;             int lr[4];
; #pragma unroll
;             for (int g = 0; g < (i + 15) / 16; ++g) lr[g] = __float_as_int(lrow[i * 68 + 16 * g]);
; #pragma unroll
;             for (int j = 0; j < i; ++j) { fmac_rowbcast_sel(sa[j & 3], lr[j >> 4], x[j], j); }
;             x[i] = (sa[0] + sa[1]) + (sa[2] + sa[3]); } }
	v_add_u32_e32 v254, 0xc000, v208
	ds_read2_b32 v[252:253], v254 offset0:120 offset1:136
	v_fmac_f32_dpp v100, v250, v71 row_newbcast:0 row_mask:0xf bank_mask:0xf
	v_fmac_f32_dpp v101, v250, v235 row_newbcast:2 row_mask:0xf bank_mask:0xf
	v_fmac_f32_dpp v239, v248, v126 row_newbcast:7 row_mask:0xf bank_mask:0xf
	v_fmac_f32_dpp v238, v248, v134 row_newbcast:9 row_mask:0xf bank_mask:0xf
	v_fmac_f32_dpp v104, v249, v110 row_newbcast:4 row_mask:0xf bank_mask:0xf
	s_nop 0
	v_fmac_f32_dpp v239, v248, v142 row_newbcast:11 row_mask:0xf bank_mask:0xf
	v_fmac_f32_dpp v238, v248, v140 row_newbcast:13 row_mask:0xf bank_mask:0xf
	v_fmac_f32_dpp v100, v250, v4 row_newbcast:4 row_mask:0xf bank_mask:0xf
	v_fmac_f32_dpp v101, v250, v8 row_newbcast:6 row_mask:0xf bank_mask:0xf
	s_nop 0
	v_fmac_f32_dpp v239, v248, v132 row_newbcast:15 row_mask:0xf bank_mask:0xf
	v_fmac_f32_dpp v238, v249, v124 row_newbcast:1 row_mask:0xf bank_mask:0xf
	v_fmac_f32_dpp v100, v250, v12 row_newbcast:8 row_mask:0xf bank_mask:0xf
	v_fmac_f32_dpp v101, v250, v18 row_newbcast:10 row_mask:0xf bank_mask:0xf
	s_nop 0
	v_fmac_f32_dpp v239, v249, v114 row_newbcast:3 row_mask:0xf bank_mask:0xf
	v_fmac_f32_dpp v100, v250, v22 row_newbcast:12 row_mask:0xf bank_mask:0xf
	v_fmac_f32_dpp v101, v250, v26 row_newbcast:14 row_mask:0xf bank_mask:0xf
	s_nop 0
	v_pk_add_f32 v[104:105], v[104:105], v[238:239]
	v_mov_b32_e32 v238, v57
	v_fmac_f32_dpp v238, v250, v234 row_newbcast:1 row_mask:0xf bank_mask:0xf
	v_mov_b32_e32 v239, v57
	v_fmac_f32_dpp v238, v250, v6 row_newbcast:5 row_mask:0xf bank_mask:0xf
	v_fmac_f32_dpp v239, v250, v2 row_newbcast:3 row_mask:0xf bank_mask:0xf
	v_fmac_f32_dpp v100, v251, v32 row_newbcast:0 row_mask:0xf bank_mask:0xf
	v_fmac_f32_dpp v101, v251, v38 row_newbcast:2 row_mask:0xf bank_mask:0xf
	v_pk_add_f32 v[104:105], v[104:105], v[104:105] op_sel:[0,1] op_sel_hi:[1,0]
	v_fmac_f32_dpp v238, v250, v14 row_newbcast:9 row_mask:0xf bank_mask:0xf
	v_fmac_f32_dpp v239, v250, v10 row_newbcast:7 row_mask:0xf bank_mask:0xf
	v_fmac_f32_dpp v100, v251, v42 row_newbcast:4 row_mask:0xf bank_mask:0xf
	v_fmac_f32_dpp v101, v251, v72 row_newbcast:6 row_mask:0xf bank_mask:0xf
	s_nop 0
	v_fmac_f32_dpp v238, v250, v24 row_newbcast:13 row_mask:0xf bank_mask:0xf
	v_fmac_f32_dpp v239, v250, v20 row_newbcast:11 row_mask:0xf bank_mask:0xf
	v_fmac_f32_dpp v100, v251, v78 row_newbcast:8 row_mask:0xf bank_mask:0xf
	v_fmac_f32_dpp v101, v251, v84 row_newbcast:10 row_mask:0xf bank_mask:0xf
	s_nop 0
	v_fmac_f32_dpp v238, v251, v34 row_newbcast:1 row_mask:0xf bank_mask:0xf
	v_fmac_f32_dpp v239, v250, v30 row_newbcast:15 row_mask:0xf bank_mask:0xf
	v_fmac_f32_dpp v100, v251, v90 row_newbcast:12 row_mask:0xf bank_mask:0xf
	v_fmac_f32_dpp v101, v251, v96 row_newbcast:14 row_mask:0xf bank_mask:0xf
	s_nop 0
	v_fmac_f32_dpp v238, v251, v46 row_newbcast:5 row_mask:0xf bank_mask:0xf
	v_fmac_f32_dpp v239, v251, v40 row_newbcast:3 row_mask:0xf bank_mask:0xf
	s_waitcnt lgkmcnt(0)
	v_add_u32_e32 v254, 0xc000, v208
	ds_read2_b32 v[242:243], v254 offset0:156 offset1:172
	v_fmac_f32_dpp v100, v252, v102 row_newbcast:0 row_mask:0xf bank_mask:0xf
	v_fmac_f32_dpp v101, v252, v108 row_newbcast:2 row_mask:0xf bank_mask:0xf
	v_fmac_f32_dpp v238, v251, v80 row_newbcast:9 row_mask:0xf bank_mask:0xf
	v_fmac_f32_dpp v239, v251, v74 row_newbcast:7 row_mask:0xf bank_mask:0xf
	s_nop 0
	v_fmac_f32_dpp v100, v252, v116 row_newbcast:4 row_mask:0xf bank_mask:0xf
	v_fmac_f32_dpp v101, v252, v122 row_newbcast:6 row_mask:0xf bank_mask:0xf
	v_fmac_f32_dpp v238, v251, v92 row_newbcast:13 row_mask:0xf bank_mask:0xf
	v_fmac_f32_dpp v239, v251, v86 row_newbcast:11 row_mask:0xf bank_mask:0xf
	s_nop 0
	v_fmac_f32_dpp v100, v252, v130 row_newbcast:8 row_mask:0xf bank_mask:0xf
	v_fmac_f32_dpp v101, v252, v138 row_newbcast:10 row_mask:0xf bank_mask:0xf
	v_fmac_f32_dpp v238, v252, v106 row_newbcast:1 row_mask:0xf bank_mask:0xf
	v_fmac_f32_dpp v239, v251, v98 row_newbcast:15 row_mask:0xf bank_mask:0xf
	s_nop 0
	v_fmac_f32_dpp v100, v252, v144 row_newbcast:12 row_mask:0xf bank_mask:0xf
	v_fmac_f32_dpp v101, v252, v136 row_newbcast:14 row_mask:0xf bank_mask:0xf
	s_nop 0
	v_fmac_f32_dpp v238, v252, v118 row_newbcast:5 row_mask:0xf bank_mask:0xf
	v_fmac_f32_dpp v239, v252, v112 row_newbcast:3 row_mask:0xf bank_mask:0xf
	v_fmac_f32_dpp v100, v253, v128 row_newbcast:0 row_mask:0xf bank_mask:0xf
	v_fmac_f32_dpp v101, v253, v120 row_newbcast:2 row_mask:0xf bank_mask:0xf
	s_waitcnt lgkmcnt(0)
; #define LAS __attribute__((address_space(3)))
; __device__ __forceinline__ void dn_prep_item(const Args& a, LAS unsigned char* lds, int item, int tid, int wave, int lane, int& cwh, int next_item) {
;     ...
;         { const LAS float* lrow = Lm + (lane & 15);
; #pragma unroll
;         for (int i = 1; i < 64; ++i) { float sa[4] = { x[i], 0.f, 0.f, 0.f };
;             int lr[4];
; #pragma unroll
;             for (int g = 0; g < (i + 15) / 16; ++g) lr[g] = __float_as_int(lrow[i * 68 + 16 * g]);
; #pragma unroll
;             for (int j = 0; j < i; ++j) { fmac_rowbcast_sel(sa[j & 3], lr[j >> 4], x[j], j); }
;             x[i] = (sa[0] + sa[1]) + (sa[2] + sa[3]); } }
	v_add_u32_e32 v254, 0xc000, v208
	ds_read2_b32 v[246:247], v254 offset0:188 offset1:204
	v_fmac_f32_dpp v94, v242, v71 row_newbcast:0 row_mask:0xf bank_mask:0xf
	v_fmac_f32_dpp v95, v242, v235 row_newbcast:2 row_mask:0xf bank_mask:0xf
	v_fmac_f32_dpp v238, v252, v134 row_newbcast:9 row_mask:0xf bank_mask:0xf
	v_fmac_f32_dpp v239, v252, v126 row_newbcast:7 row_mask:0xf bank_mask:0xf
	v_fmac_f32_dpp v100, v253, v110 row_newbcast:4 row_mask:0xf bank_mask:0xf
	s_nop 0
	v_fmac_f32_dpp v238, v252, v140 row_newbcast:13 row_mask:0xf bank_mask:0xf
	v_fmac_f32_dpp v239, v252, v142 row_newbcast:11 row_mask:0xf bank_mask:0xf
	v_fmac_f32_dpp v94, v242, v4 row_newbcast:4 row_mask:0xf bank_mask:0xf
	v_fmac_f32_dpp v95, v242, v8 row_newbcast:6 row_mask:0xf bank_mask:0xf
	s_nop 0
	v_fmac_f32_dpp v238, v253, v124 row_newbcast:1 row_mask:0xf bank_mask:0xf
	v_fmac_f32_dpp v239, v252, v132 row_newbcast:15 row_mask:0xf bank_mask:0xf
	v_fmac_f32_dpp v94, v242, v12 row_newbcast:8 row_mask:0xf bank_mask:0xf
	v_fmac_f32_dpp v95, v242, v18 row_newbcast:10 row_mask:0xf bank_mask:0xf
	s_nop 0
	v_fmac_f32_dpp v238, v253, v104 row_newbcast:5 row_mask:0xf bank_mask:0xf
	v_fmac_f32_dpp v239, v253, v114 row_newbcast:3 row_mask:0xf bank_mask:0xf
	v_fmac_f32_dpp v94, v242, v22 row_newbcast:12 row_mask:0xf bank_mask:0xf
	v_fmac_f32_dpp v95, v242, v26 row_newbcast:14 row_mask:0xf bank_mask:0xf
	s_nop 0
	v_pk_add_f32 v[100:101], v[100:101], v[238:239]
	v_mov_b32_e32 v238, v57
	v_fmac_f32_dpp v238, v242, v234 row_newbcast:1 row_mask:0xf bank_mask:0xf
	v_mov_b32_e32 v239, v57
	v_fmac_f32_dpp v238, v242, v6 row_newbcast:5 row_mask:0xf bank_mask:0xf
	v_fmac_f32_dpp v239, v242, v2 row_newbcast:3 row_mask:0xf bank_mask:0xf
	v_fmac_f32_dpp v94, v243, v32 row_newbcast:0 row_mask:0xf bank_mask:0xf
	v_fmac_f32_dpp v95, v243, v38 row_newbcast:2 row_mask:0xf bank_mask:0xf
	v_pk_add_f32 v[100:101], v[100:101], v[100:101] op_sel:[0,1] op_sel_hi:[1,0]
	v_fmac_f32_dpp v238, v242, v14 row_newbcast:9 row_mask:0xf bank_mask:0xf
	v_fmac_f32_dpp v239, v242, v10 row_newbcast:7 row_mask:0xf bank_mask:0xf
	v_fmac_f32_dpp v94, v243, v42 row_newbcast:4 row_mask:0xf bank_mask:0xf
	v_fmac_f32_dpp v95, v243, v72 row_newbcast:6 row_mask:0xf bank_mask:0xf
	s_nop 0
	v_fmac_f32_dpp v238, v242, v24 row_newbcast:13 row_mask:0xf bank_mask:0xf
	v_fmac_f32_dpp v239, v242, v20 row_newbcast:11 row_mask:0xf bank_mask:0xf
	v_fmac_f32_dpp v94, v243, v78 row_newbcast:8 row_mask:0xf bank_mask:0xf
	v_fmac_f32_dpp v95, v243, v84 row_newbcast:10 row_mask:0xf bank_mask:0xf
	s_nop 0
	v_fmac_f32_dpp v238, v243, v34 row_newbcast:1 row_mask:0xf bank_mask:0xf
	v_fmac_f32_dpp v239, v242, v30 row_newbcast:15 row_mask:0xf bank_mask:0xf
	v_fmac_f32_dpp v94, v243, v90 row_newbcast:12 row_mask:0xf bank_mask:0xf
	v_fmac_f32_dpp v95, v243, v96 row_newbcast:14 row_mask:0xf bank_mask:0xf
	s_nop 0
	v_fmac_f32_dpp v238, v243, v46 row_newbcast:5 row_mask:0xf bank_mask:0xf
	v_fmac_f32_dpp v239, v243, v40 row_newbcast:3 row_mask:0xf bank_mask:0xf
	s_waitcnt lgkmcnt(0)
	v_add_u32_e32 v254, 0xc000, v208
	ds_read2_b32 v[248:249], v254 offset0:224 offset1:240
	v_fmac_f32_dpp v94, v246, v102 row_newbcast:0 row_mask:0xf bank_mask:0xf
	v_fmac_f32_dpp v95, v246, v108 row_newbcast:2 row_mask:0xf bank_mask:0xf
	v_fmac_f32_dpp v238, v243, v80 row_newbcast:9 row_mask:0xf bank_mask:0xf
	v_fmac_f32_dpp v239, v243, v74 row_newbcast:7 row_mask:0xf bank_mask:0xf
	s_nop 0
	v_fmac_f32_dpp v94, v246, v116 row_newbcast:4 row_mask:0xf bank_mask:0xf
	v_fmac_f32_dpp v95, v246, v122 row_newbcast:6 row_mask:0xf bank_mask:0xf
	v_fmac_f32_dpp v238, v243, v92 row_newbcast:13 row_mask:0xf bank_mask:0xf
	v_fmac_f32_dpp v239, v243, v86 row_newbcast:11 row_mask:0xf bank_mask:0xf
	s_nop 0
	v_fmac_f32_dpp v94, v246, v130 row_newbcast:8 row_mask:0xf bank_mask:0xf
	v_fmac_f32_dpp v95, v246, v138 row_newbcast:10 row_mask:0xf bank_mask:0xf
	v_fmac_f32_dpp v238, v246, v106 row_newbcast:1 row_mask:0xf bank_mask:0xf
	v_fmac_f32_dpp v239, v243, v98 row_newbcast:15 row_mask:0xf bank_mask:0xf
	s_nop 0
	v_fmac_f32_dpp v94, v246, v144 row_newbcast:12 row_mask:0xf bank_mask:0xf
	v_fmac_f32_dpp v95, v246, v136 row_newbcast:14 row_mask:0xf bank_mask:0xf
	s_nop 0
	v_fmac_f32_dpp v238, v246, v118 row_newbcast:5 row_mask:0xf bank_mask:0xf
	v_fmac_f32_dpp v239, v246, v112 row_newbcast:3 row_mask:0xf bank_mask:0xf
	v_fmac_f32_dpp v94, v247, v128 row_newbcast:0 row_mask:0xf bank_mask:0xf
	v_fmac_f32_dpp v95, v247, v120 row_newbcast:2 row_mask:0xf bank_mask:0xf
	s_waitcnt lgkmcnt(0)
; #define LAS __attribute__((address_space(3)))
; __device__ __forceinline__ void dn_prep_item(const Args& a, LAS unsigned char* lds, int item, int tid, int wave, int lane, int& cwh, int next_item) {
;     ...
;         { const LAS float* lrow = Lm + (lane & 15);
; #pragma unroll
;         for (int i = 1; i < 64; ++i) { float sa[4] = { x[i], 0.f, 0.f, 0.f };
;             int lr[4];
; #pragma unroll
;             for (int g = 0; g < (i + 15) / 16; ++g) lr[g] = __float_as_int(lrow[i * 68 + 16 * g]);
; #pragma unroll
;             for (int j = 0; j < i; ++j) { fmac_rowbcast_sel(sa[j & 3], lr[j >> 4], x[j], j); }
;             x[i] = (sa[0] + sa[1]) + (sa[2] + sa[3]); } }
	v_add_u32_e32 v254, 0xc400, v208
	ds_read2_b32 v[250:251], v254 offset1:16
	v_fmac_f32_dpp v88, v248, v71 row_newbcast:0 row_mask:0xf bank_mask:0xf
	v_fmac_f32_dpp v89, v248, v235 row_newbcast:2 row_mask:0xf bank_mask:0xf
	v_fmac_f32_dpp v238, v246, v134 row_newbcast:9 row_mask:0xf bank_mask:0xf
	v_fmac_f32_dpp v239, v246, v126 row_newbcast:7 row_mask:0xf bank_mask:0xf
	v_fmac_f32_dpp v94, v247, v110 row_newbcast:4 row_mask:0xf bank_mask:0xf
	v_fmac_f32_dpp v95, v247, v100 row_newbcast:6 row_mask:0xf bank_mask:0xf
	s_nop 0
	v_fmac_f32_dpp v88, v248, v4 row_newbcast:4 row_mask:0xf bank_mask:0xf
	v_fmac_f32_dpp v89, v248, v8 row_newbcast:6 row_mask:0xf bank_mask:0xf
	v_fmac_f32_dpp v238, v246, v140 row_newbcast:13 row_mask:0xf bank_mask:0xf
	v_fmac_f32_dpp v239, v246, v142 row_newbcast:11 row_mask:0xf bank_mask:0xf
	v_add_u32_e32 v1, 0xc400, v208
	v_fmac_f32_dpp v238, v247, v124 row_newbcast:1 row_mask:0xf bank_mask:0xf
	v_fmac_f32_dpp v239, v246, v132 row_newbcast:15 row_mask:0xf bank_mask:0xf
	v_fmac_f32_dpp v88, v248, v12 row_newbcast:8 row_mask:0xf bank_mask:0xf
	v_fmac_f32_dpp v89, v248, v18 row_newbcast:10 row_mask:0xf bank_mask:0xf
	s_nop 0
	v_fmac_f32_dpp v238, v247, v104 row_newbcast:5 row_mask:0xf bank_mask:0xf
	v_fmac_f32_dpp v239, v247, v114 row_newbcast:3 row_mask:0xf bank_mask:0xf
	v_fmac_f32_dpp v88, v248, v22 row_newbcast:12 row_mask:0xf bank_mask:0xf
	v_fmac_f32_dpp v89, v248, v26 row_newbcast:14 row_mask:0xf bank_mask:0xf
	s_nop 0
	v_pk_add_f32 v[94:95], v[94:95], v[238:239]
	v_mov_b32_e32 v238, v57
	v_fmac_f32_dpp v238, v248, v234 row_newbcast:1 row_mask:0xf bank_mask:0xf
	v_mov_b32_e32 v239, v57
	v_fmac_f32_dpp v239, v248, v2 row_newbcast:3 row_mask:0xf bank_mask:0xf
	v_fmac_f32_dpp v238, v248, v6 row_newbcast:5 row_mask:0xf bank_mask:0xf
	v_fmac_f32_dpp v88, v249, v32 row_newbcast:0 row_mask:0xf bank_mask:0xf
	v_fmac_f32_dpp v89, v249, v38 row_newbcast:2 row_mask:0xf bank_mask:0xf
	v_pk_add_f32 v[94:95], v[94:95], v[94:95] op_sel:[0,1] op_sel_hi:[1,0]
	v_fmac_f32_dpp v239, v248, v10 row_newbcast:7 row_mask:0xf bank_mask:0xf
	v_fmac_f32_dpp v238, v248, v14 row_newbcast:9 row_mask:0xf bank_mask:0xf
	v_fmac_f32_dpp v88, v249, v42 row_newbcast:4 row_mask:0xf bank_mask:0xf
	v_fmac_f32_dpp v89, v249, v72 row_newbcast:6 row_mask:0xf bank_mask:0xf
	s_nop 0
	v_fmac_f32_dpp v239, v248, v20 row_newbcast:11 row_mask:0xf bank_mask:0xf
	v_fmac_f32_dpp v238, v248, v24 row_newbcast:13 row_mask:0xf bank_mask:0xf
	v_fmac_f32_dpp v88, v249, v78 row_newbcast:8 row_mask:0xf bank_mask:0xf
	v_fmac_f32_dpp v89, v249, v84 row_newbcast:10 row_mask:0xf bank_mask:0xf
	s_nop 0
	v_fmac_f32_dpp v239, v248, v30 row_newbcast:15 row_mask:0xf bank_mask:0xf
	v_fmac_f32_dpp v238, v249, v34 row_newbcast:1 row_mask:0xf bank_mask:0xf
	v_fmac_f32_dpp v88, v249, v90 row_newbcast:12 row_mask:0xf bank_mask:0xf
	v_fmac_f32_dpp v89, v249, v96 row_newbcast:14 row_mask:0xf bank_mask:0xf
	s_nop 0
	v_fmac_f32_dpp v239, v249, v40 row_newbcast:3 row_mask:0xf bank_mask:0xf
	v_fmac_f32_dpp v238, v249, v46 row_newbcast:5 row_mask:0xf bank_mask:0xf
	s_waitcnt lgkmcnt(0)
	v_add_u32_e32 v254, 0xc400, v208
	ds_read2_b32 v[252:253], v254 offset0:36 offset1:52
	v_fmac_f32_dpp v88, v250, v102 row_newbcast:0 row_mask:0xf bank_mask:0xf
	v_fmac_f32_dpp v89, v250, v108 row_newbcast:2 row_mask:0xf bank_mask:0xf
	v_fmac_f32_dpp v239, v249, v74 row_newbcast:7 row_mask:0xf bank_mask:0xf
	v_fmac_f32_dpp v238, v249, v80 row_newbcast:9 row_mask:0xf bank_mask:0xf
	s_nop 0
	v_fmac_f32_dpp v88, v250, v116 row_newbcast:4 row_mask:0xf bank_mask:0xf
	v_fmac_f32_dpp v89, v250, v122 row_newbcast:6 row_mask:0xf bank_mask:0xf
	v_fmac_f32_dpp v239, v249, v86 row_newbcast:11 row_mask:0xf bank_mask:0xf
	v_fmac_f32_dpp v238, v249, v92 row_newbcast:13 row_mask:0xf bank_mask:0xf
	s_nop 0
	v_fmac_f32_dpp v88, v250, v130 row_newbcast:8 row_mask:0xf bank_mask:0xf
	v_fmac_f32_dpp v89, v250, v138 row_newbcast:10 row_mask:0xf bank_mask:0xf
	v_fmac_f32_dpp v239, v249, v98 row_newbcast:15 row_mask:0xf bank_mask:0xf
	v_fmac_f32_dpp v238, v250, v106 row_newbcast:1 row_mask:0xf bank_mask:0xf
	s_nop 0
	v_fmac_f32_dpp v88, v250, v144 row_newbcast:12 row_mask:0xf bank_mask:0xf
	v_fmac_f32_dpp v89, v250, v136 row_newbcast:14 row_mask:0xf bank_mask:0xf
	s_nop 0
	v_fmac_f32_dpp v239, v250, v112 row_newbcast:3 row_mask:0xf bank_mask:0xf
	v_fmac_f32_dpp v238, v250, v118 row_newbcast:5 row_mask:0xf bank_mask:0xf
	v_fmac_f32_dpp v88, v251, v128 row_newbcast:0 row_mask:0xf bank_mask:0xf
	v_fmac_f32_dpp v89, v251, v120 row_newbcast:2 row_mask:0xf bank_mask:0xf
	s_waitcnt lgkmcnt(0)
; #define LAS __attribute__((address_space(3)))
; __device__ __forceinline__ void dn_prep_item(const Args& a, LAS unsigned char* lds, int item, int tid, int wave, int lane, int& cwh, int next_item) {
;     ...
;         { const LAS float* lrow = Lm + (lane & 15);
; #pragma unroll
;         for (int i = 1; i < 64; ++i) { float sa[4] = { x[i], 0.f, 0.f, 0.f };
;             int lr[4];
; #pragma unroll
;             for (int g = 0; g < (i + 15) / 16; ++g) lr[g] = __float_as_int(lrow[i * 68 + 16 * g]);
; #pragma unroll
;             for (int j = 0; j < i; ++j) { fmac_rowbcast_sel(sa[j & 3], lr[j >> 4], x[j], j); }
;             x[i] = (sa[0] + sa[1]) + (sa[2] + sa[3]); } }
	v_add_u32_e32 v254, 0xc400, v208
	ds_read2_b32 v[242:243], v254 offset0:68 offset1:84
	v_fmac_f32_dpp v82, v252, v71 row_newbcast:0 row_mask:0xf bank_mask:0xf
	v_fmac_f32_dpp v83, v252, v235 row_newbcast:2 row_mask:0xf bank_mask:0xf
	v_fmac_f32_dpp v239, v250, v126 row_newbcast:7 row_mask:0xf bank_mask:0xf
	v_fmac_f32_dpp v238, v250, v134 row_newbcast:9 row_mask:0xf bank_mask:0xf
	v_fmac_f32_dpp v88, v251, v110 row_newbcast:4 row_mask:0xf bank_mask:0xf
	v_fmac_f32_dpp v89, v251, v100 row_newbcast:6 row_mask:0xf bank_mask:0xf
	s_nop 0
	v_fmac_f32_dpp v82, v252, v4 row_newbcast:4 row_mask:0xf bank_mask:0xf
	v_fmac_f32_dpp v83, v252, v8 row_newbcast:6 row_mask:0xf bank_mask:0xf
	v_fmac_f32_dpp v239, v250, v142 row_newbcast:11 row_mask:0xf bank_mask:0xf
	v_fmac_f32_dpp v238, v250, v140 row_newbcast:13 row_mask:0xf bank_mask:0xf
	s_nop 0
	v_fmac_f32_dpp v239, v250, v132 row_newbcast:15 row_mask:0xf bank_mask:0xf
	v_fmac_f32_dpp v238, v251, v124 row_newbcast:1 row_mask:0xf bank_mask:0xf
	v_fmac_f32_dpp v82, v252, v12 row_newbcast:8 row_mask:0xf bank_mask:0xf
	v_fmac_f32_dpp v83, v252, v18 row_newbcast:10 row_mask:0xf bank_mask:0xf
	s_nop 0
	v_fmac_f32_dpp v239, v251, v114 row_newbcast:3 row_mask:0xf bank_mask:0xf
	v_fmac_f32_dpp v238, v251, v104 row_newbcast:5 row_mask:0xf bank_mask:0xf
	v_fmac_f32_dpp v82, v252, v22 row_newbcast:12 row_mask:0xf bank_mask:0xf
	v_fmac_f32_dpp v83, v252, v26 row_newbcast:14 row_mask:0xf bank_mask:0xf
	s_nop 0
	v_fmac_f32_dpp v239, v251, v94 row_newbcast:7 row_mask:0xf bank_mask:0xf
	v_fmac_f32_dpp v82, v253, v32 row_newbcast:0 row_mask:0xf bank_mask:0xf
	v_fmac_f32_dpp v83, v253, v38 row_newbcast:2 row_mask:0xf bank_mask:0xf
	s_nop 0
	v_pk_add_f32 v[88:89], v[88:89], v[238:239]
	v_mov_b32_e32 v238, v57
	v_fmac_f32_dpp v238, v252, v234 row_newbcast:1 row_mask:0xf bank_mask:0xf
	v_mov_b32_e32 v239, v57
	v_fmac_f32_dpp v239, v252, v2 row_newbcast:3 row_mask:0xf bank_mask:0xf
	v_fmac_f32_dpp v238, v252, v6 row_newbcast:5 row_mask:0xf bank_mask:0xf
	v_fmac_f32_dpp v82, v253, v42 row_newbcast:4 row_mask:0xf bank_mask:0xf
	v_fmac_f32_dpp v83, v253, v72 row_newbcast:6 row_mask:0xf bank_mask:0xf
	v_pk_add_f32 v[88:89], v[88:89], v[88:89] op_sel:[0,1] op_sel_hi:[1,0]
	v_fmac_f32_dpp v239, v252, v10 row_newbcast:7 row_mask:0xf bank_mask:0xf
	v_fmac_f32_dpp v238, v252, v14 row_newbcast:9 row_mask:0xf bank_mask:0xf
	v_fmac_f32_dpp v82, v253, v78 row_newbcast:8 row_mask:0xf bank_mask:0xf
	v_fmac_f32_dpp v83, v253, v84 row_newbcast:10 row_mask:0xf bank_mask:0xf
	s_nop 0
	v_fmac_f32_dpp v239, v252, v20 row_newbcast:11 row_mask:0xf bank_mask:0xf
	v_fmac_f32_dpp v238, v252, v24 row_newbcast:13 row_mask:0xf bank_mask:0xf
	v_fmac_f32_dpp v82, v253, v90 row_newbcast:12 row_mask:0xf bank_mask:0xf
	v_fmac_f32_dpp v83, v253, v96 row_newbcast:14 row_mask:0xf bank_mask:0xf
	s_nop 0
	v_fmac_f32_dpp v239, v252, v30 row_newbcast:15 row_mask:0xf bank_mask:0xf
	v_fmac_f32_dpp v238, v253, v34 row_newbcast:1 row_mask:0xf bank_mask:0xf
	s_waitcnt lgkmcnt(0)
	v_add_u32_e32 v254, 0xc400, v208
	ds_read2_b32 v[246:247], v254 offset0:104 offset1:120
	v_fmac_f32_dpp v82, v242, v102 row_newbcast:0 row_mask:0xf bank_mask:0xf
	v_fmac_f32_dpp v83, v242, v108 row_newbcast:2 row_mask:0xf bank_mask:0xf
	v_fmac_f32_dpp v239, v253, v40 row_newbcast:3 row_mask:0xf bank_mask:0xf
	v_fmac_f32_dpp v238, v253, v46 row_newbcast:5 row_mask:0xf bank_mask:0xf
	s_nop 0
	v_fmac_f32_dpp v82, v242, v116 row_newbcast:4 row_mask:0xf bank_mask:0xf
	v_fmac_f32_dpp v83, v242, v122 row_newbcast:6 row_mask:0xf bank_mask:0xf
	v_fmac_f32_dpp v239, v253, v74 row_newbcast:7 row_mask:0xf bank_mask:0xf
	v_fmac_f32_dpp v238, v253, v80 row_newbcast:9 row_mask:0xf bank_mask:0xf
	s_nop 0
	v_fmac_f32_dpp v82, v242, v130 row_newbcast:8 row_mask:0xf bank_mask:0xf
	v_fmac_f32_dpp v83, v242, v138 row_newbcast:10 row_mask:0xf bank_mask:0xf
	v_fmac_f32_dpp v239, v253, v86 row_newbcast:11 row_mask:0xf bank_mask:0xf
	v_fmac_f32_dpp v238, v253, v92 row_newbcast:13 row_mask:0xf bank_mask:0xf
	s_nop 0
	v_fmac_f32_dpp v82, v242, v144 row_newbcast:12 row_mask:0xf bank_mask:0xf
	v_fmac_f32_dpp v83, v242, v136 row_newbcast:14 row_mask:0xf bank_mask:0xf
	v_fmac_f32_dpp v239, v253, v98 row_newbcast:15 row_mask:0xf bank_mask:0xf
	v_fmac_f32_dpp v238, v242, v106 row_newbcast:1 row_mask:0xf bank_mask:0xf
	s_nop 0
	v_fmac_f32_dpp v82, v243, v128 row_newbcast:0 row_mask:0xf bank_mask:0xf
	v_fmac_f32_dpp v83, v243, v120 row_newbcast:2 row_mask:0xf bank_mask:0xf
	s_nop 0
	v_fmac_f32_dpp v239, v242, v112 row_newbcast:3 row_mask:0xf bank_mask:0xf
	v_fmac_f32_dpp v238, v242, v118 row_newbcast:5 row_mask:0xf bank_mask:0xf
	v_fmac_f32_dpp v82, v243, v110 row_newbcast:4 row_mask:0xf bank_mask:0xf
	v_fmac_f32_dpp v83, v243, v100 row_newbcast:6 row_mask:0xf bank_mask:0xf
	s_waitcnt lgkmcnt(0)
; #define LAS __attribute__((address_space(3)))
; __device__ __forceinline__ void dn_prep_item(const Args& a, LAS unsigned char* lds, int item, int tid, int wave, int lane, int& cwh, int next_item) {
;     ...
;         { const LAS float* lrow = Lm + (lane & 15);
; #pragma unroll
;         for (int i = 1; i < 64; ++i) { float sa[4] = { x[i], 0.f, 0.f, 0.f };
;             int lr[4];
; #pragma unroll
;             for (int g = 0; g < (i + 15) / 16; ++g) lr[g] = __float_as_int(lrow[i * 68 + 16 * g]);
; #pragma unroll
;             for (int j = 0; j < i; ++j) { fmac_rowbcast_sel(sa[j & 3], lr[j >> 4], x[j], j); }
;             x[i] = (sa[0] + sa[1]) + (sa[2] + sa[3]); } }
	v_add_u32_e32 v254, 0xc400, v208
	ds_read2_b32 v[248:249], v254 offset0:136 offset1:152
	v_fmac_f32_dpp v76, v246, v71 row_newbcast:0 row_mask:0xf bank_mask:0xf
	v_fmac_f32_dpp v77, v246, v235 row_newbcast:2 row_mask:0xf bank_mask:0xf
	v_fmac_f32_dpp v239, v242, v126 row_newbcast:7 row_mask:0xf bank_mask:0xf
	v_fmac_f32_dpp v238, v242, v134 row_newbcast:9 row_mask:0xf bank_mask:0xf
	v_fmac_f32_dpp v82, v243, v88 row_newbcast:8 row_mask:0xf bank_mask:0xf
	s_nop 0
	v_fmac_f32_dpp v239, v242, v142 row_newbcast:11 row_mask:0xf bank_mask:0xf
	v_fmac_f32_dpp v238, v242, v140 row_newbcast:13 row_mask:0xf bank_mask:0xf
	v_fmac_f32_dpp v76, v246, v4 row_newbcast:4 row_mask:0xf bank_mask:0xf
	v_fmac_f32_dpp v77, v246, v8 row_newbcast:6 row_mask:0xf bank_mask:0xf
	s_nop 0
	v_fmac_f32_dpp v239, v242, v132 row_newbcast:15 row_mask:0xf bank_mask:0xf
	v_fmac_f32_dpp v238, v243, v124 row_newbcast:1 row_mask:0xf bank_mask:0xf
	v_fmac_f32_dpp v76, v246, v12 row_newbcast:8 row_mask:0xf bank_mask:0xf
	v_fmac_f32_dpp v77, v246, v18 row_newbcast:10 row_mask:0xf bank_mask:0xf
	s_nop 0
	v_fmac_f32_dpp v239, v243, v114 row_newbcast:3 row_mask:0xf bank_mask:0xf
	v_fmac_f32_dpp v238, v243, v104 row_newbcast:5 row_mask:0xf bank_mask:0xf
	v_fmac_f32_dpp v76, v246, v22 row_newbcast:12 row_mask:0xf bank_mask:0xf
	v_fmac_f32_dpp v77, v246, v26 row_newbcast:14 row_mask:0xf bank_mask:0xf
	s_nop 0
	v_fmac_f32_dpp v239, v243, v94 row_newbcast:7 row_mask:0xf bank_mask:0xf
	v_fmac_f32_dpp v76, v247, v32 row_newbcast:0 row_mask:0xf bank_mask:0xf
	v_fmac_f32_dpp v77, v247, v38 row_newbcast:2 row_mask:0xf bank_mask:0xf
	s_nop 0
	v_pk_add_f32 v[82:83], v[82:83], v[238:239]
	v_mov_b32_e32 v238, v57
	v_fmac_f32_dpp v238, v246, v234 row_newbcast:1 row_mask:0xf bank_mask:0xf
	v_mov_b32_e32 v239, v57
	v_fmac_f32_dpp v238, v246, v6 row_newbcast:5 row_mask:0xf bank_mask:0xf
	v_fmac_f32_dpp v239, v246, v2 row_newbcast:3 row_mask:0xf bank_mask:0xf
	v_fmac_f32_dpp v76, v247, v42 row_newbcast:4 row_mask:0xf bank_mask:0xf
	v_fmac_f32_dpp v77, v247, v72 row_newbcast:6 row_mask:0xf bank_mask:0xf
	v_pk_add_f32 v[82:83], v[82:83], v[82:83] op_sel:[0,1] op_sel_hi:[1,0]
	v_fmac_f32_dpp v238, v246, v14 row_newbcast:9 row_mask:0xf bank_mask:0xf
	v_fmac_f32_dpp v239, v246, v10 row_newbcast:7 row_mask:0xf bank_mask:0xf
	v_fmac_f32_dpp v76, v247, v78 row_newbcast:8 row_mask:0xf bank_mask:0xf
	v_fmac_f32_dpp v77, v247, v84 row_newbcast:10 row_mask:0xf bank_mask:0xf
	s_nop 0
	v_fmac_f32_dpp v238, v246, v24 row_newbcast:13 row_mask:0xf bank_mask:0xf
	v_fmac_f32_dpp v239, v246, v20 row_newbcast:11 row_mask:0xf bank_mask:0xf
	v_fmac_f32_dpp v76, v247, v90 row_newbcast:12 row_mask:0xf bank_mask:0xf
	v_fmac_f32_dpp v77, v247, v96 row_newbcast:14 row_mask:0xf bank_mask:0xf
	s_nop 0
	v_fmac_f32_dpp v238, v247, v34 row_newbcast:1 row_mask:0xf bank_mask:0xf
	v_fmac_f32_dpp v239, v246, v30 row_newbcast:15 row_mask:0xf bank_mask:0xf
	s_waitcnt lgkmcnt(0)
	v_add_u32_e32 v254, 0xc400, v208
	ds_read2_b32 v[250:251], v254 offset0:172 offset1:188
	v_fmac_f32_dpp v76, v248, v102 row_newbcast:0 row_mask:0xf bank_mask:0xf
	v_fmac_f32_dpp v77, v248, v108 row_newbcast:2 row_mask:0xf bank_mask:0xf
	v_fmac_f32_dpp v238, v247, v46 row_newbcast:5 row_mask:0xf bank_mask:0xf
	v_fmac_f32_dpp v239, v247, v40 row_newbcast:3 row_mask:0xf bank_mask:0xf
	s_nop 0
	v_fmac_f32_dpp v76, v248, v116 row_newbcast:4 row_mask:0xf bank_mask:0xf
	v_fmac_f32_dpp v77, v248, v122 row_newbcast:6 row_mask:0xf bank_mask:0xf
	v_fmac_f32_dpp v238, v247, v80 row_newbcast:9 row_mask:0xf bank_mask:0xf
	v_fmac_f32_dpp v239, v247, v74 row_newbcast:7 row_mask:0xf bank_mask:0xf
	s_nop 0
	v_fmac_f32_dpp v76, v248, v130 row_newbcast:8 row_mask:0xf bank_mask:0xf
	v_fmac_f32_dpp v77, v248, v138 row_newbcast:10 row_mask:0xf bank_mask:0xf
	v_fmac_f32_dpp v238, v247, v92 row_newbcast:13 row_mask:0xf bank_mask:0xf
	v_fmac_f32_dpp v239, v247, v86 row_newbcast:11 row_mask:0xf bank_mask:0xf
	s_nop 0
	v_fmac_f32_dpp v76, v248, v144 row_newbcast:12 row_mask:0xf bank_mask:0xf
	v_fmac_f32_dpp v77, v248, v136 row_newbcast:14 row_mask:0xf bank_mask:0xf
	v_fmac_f32_dpp v238, v248, v106 row_newbcast:1 row_mask:0xf bank_mask:0xf
	v_fmac_f32_dpp v239, v247, v98 row_newbcast:15 row_mask:0xf bank_mask:0xf
	s_nop 0
	v_fmac_f32_dpp v76, v249, v128 row_newbcast:0 row_mask:0xf bank_mask:0xf
	v_fmac_f32_dpp v77, v249, v120 row_newbcast:2 row_mask:0xf bank_mask:0xf
	s_nop 0
	v_fmac_f32_dpp v238, v248, v118 row_newbcast:5 row_mask:0xf bank_mask:0xf
	v_fmac_f32_dpp v239, v248, v112 row_newbcast:3 row_mask:0xf bank_mask:0xf
	v_fmac_f32_dpp v76, v249, v110 row_newbcast:4 row_mask:0xf bank_mask:0xf
	v_fmac_f32_dpp v77, v249, v100 row_newbcast:6 row_mask:0xf bank_mask:0xf
	s_waitcnt lgkmcnt(0)
; #define LAS __attribute__((address_space(3)))
; __device__ __forceinline__ void dn_prep_item(const Args& a, LAS unsigned char* lds, int item, int tid, int wave, int lane, int& cwh, int next_item) {
;     ...
;         { const LAS float* lrow = Lm + (lane & 15);
; #pragma unroll
;         for (int i = 1; i < 64; ++i) { float sa[4] = { x[i], 0.f, 0.f, 0.f };
;             int lr[4];
; #pragma unroll
;             for (int g = 0; g < (i + 15) / 16; ++g) lr[g] = __float_as_int(lrow[i * 68 + 16 * g]);
; #pragma unroll
;             for (int j = 0; j < i; ++j) { fmac_rowbcast_sel(sa[j & 3], lr[j >> 4], x[j], j); }
;             x[i] = (sa[0] + sa[1]) + (sa[2] + sa[3]); } }
	v_add_u32_e32 v254, 0xc400, v208
	ds_read2_b32 v[252:253], v254 offset0:204 offset1:220
	v_fmac_f32_dpp v44, v250, v71 row_newbcast:0 row_mask:0xf bank_mask:0xf
	v_fmac_f32_dpp v45, v250, v235 row_newbcast:2 row_mask:0xf bank_mask:0xf
	v_fmac_f32_dpp v238, v248, v134 row_newbcast:9 row_mask:0xf bank_mask:0xf
	v_fmac_f32_dpp v239, v248, v126 row_newbcast:7 row_mask:0xf bank_mask:0xf
	v_fmac_f32_dpp v76, v249, v88 row_newbcast:8 row_mask:0xf bank_mask:0xf
	s_nop 0
	v_fmac_f32_dpp v238, v248, v140 row_newbcast:13 row_mask:0xf bank_mask:0xf
	v_fmac_f32_dpp v239, v248, v142 row_newbcast:11 row_mask:0xf bank_mask:0xf
	v_fmac_f32_dpp v44, v250, v4 row_newbcast:4 row_mask:0xf bank_mask:0xf
	v_fmac_f32_dpp v45, v250, v8 row_newbcast:6 row_mask:0xf bank_mask:0xf
	s_nop 0
	v_fmac_f32_dpp v238, v249, v124 row_newbcast:1 row_mask:0xf bank_mask:0xf
	v_fmac_f32_dpp v239, v248, v132 row_newbcast:15 row_mask:0xf bank_mask:0xf
	v_fmac_f32_dpp v44, v250, v12 row_newbcast:8 row_mask:0xf bank_mask:0xf
	v_fmac_f32_dpp v45, v250, v18 row_newbcast:10 row_mask:0xf bank_mask:0xf
	s_nop 0
	v_fmac_f32_dpp v238, v249, v104 row_newbcast:5 row_mask:0xf bank_mask:0xf
	v_fmac_f32_dpp v239, v249, v114 row_newbcast:3 row_mask:0xf bank_mask:0xf
	v_fmac_f32_dpp v44, v250, v22 row_newbcast:12 row_mask:0xf bank_mask:0xf
	v_fmac_f32_dpp v45, v250, v26 row_newbcast:14 row_mask:0xf bank_mask:0xf
	s_nop 0
	v_fmac_f32_dpp v238, v249, v82 row_newbcast:9 row_mask:0xf bank_mask:0xf
	v_fmac_f32_dpp v239, v249, v94 row_newbcast:7 row_mask:0xf bank_mask:0xf
	v_fmac_f32_dpp v44, v251, v32 row_newbcast:0 row_mask:0xf bank_mask:0xf
	v_fmac_f32_dpp v45, v251, v38 row_newbcast:2 row_mask:0xf bank_mask:0xf
	s_nop 0
	v_pk_add_f32 v[76:77], v[76:77], v[238:239]
	v_mov_b32_e32 v238, v57
	v_fmac_f32_dpp v238, v250, v234 row_newbcast:1 row_mask:0xf bank_mask:0xf
	v_mov_b32_e32 v239, v57
	v_fmac_f32_dpp v239, v250, v2 row_newbcast:3 row_mask:0xf bank_mask:0xf
	v_fmac_f32_dpp v238, v250, v6 row_newbcast:5 row_mask:0xf bank_mask:0xf
	v_fmac_f32_dpp v44, v251, v42 row_newbcast:4 row_mask:0xf bank_mask:0xf
	v_fmac_f32_dpp v45, v251, v72 row_newbcast:6 row_mask:0xf bank_mask:0xf
	v_pk_add_f32 v[76:77], v[76:77], v[76:77] op_sel:[0,1] op_sel_hi:[1,0]
	v_fmac_f32_dpp v239, v250, v10 row_newbcast:7 row_mask:0xf bank_mask:0xf
	v_fmac_f32_dpp v238, v250, v14 row_newbcast:9 row_mask:0xf bank_mask:0xf
	v_fmac_f32_dpp v44, v251, v78 row_newbcast:8 row_mask:0xf bank_mask:0xf
	v_fmac_f32_dpp v45, v251, v84 row_newbcast:10 row_mask:0xf bank_mask:0xf
	v_add_u32_e32 v1, 0xc600, v208
	v_fmac_f32_dpp v239, v250, v20 row_newbcast:11 row_mask:0xf bank_mask:0xf
	v_fmac_f32_dpp v238, v250, v24 row_newbcast:13 row_mask:0xf bank_mask:0xf
	v_fmac_f32_dpp v44, v251, v90 row_newbcast:12 row_mask:0xf bank_mask:0xf
	v_fmac_f32_dpp v45, v251, v96 row_newbcast:14 row_mask:0xf bank_mask:0xf
	s_nop 0
	v_fmac_f32_dpp v239, v250, v30 row_newbcast:15 row_mask:0xf bank_mask:0xf
	v_fmac_f32_dpp v238, v251, v34 row_newbcast:1 row_mask:0xf bank_mask:0xf
	s_waitcnt lgkmcnt(0)
	v_add_u32_e32 v254, 0xc600, v208
	ds_read2_b32 v[242:243], v254 offset0:112 offset1:128
	v_fmac_f32_dpp v44, v252, v102 row_newbcast:0 row_mask:0xf bank_mask:0xf
	v_fmac_f32_dpp v45, v252, v108 row_newbcast:2 row_mask:0xf bank_mask:0xf
	v_fmac_f32_dpp v239, v251, v40 row_newbcast:3 row_mask:0xf bank_mask:0xf
	v_fmac_f32_dpp v238, v251, v46 row_newbcast:5 row_mask:0xf bank_mask:0xf
	s_nop 0
	v_fmac_f32_dpp v44, v252, v116 row_newbcast:4 row_mask:0xf bank_mask:0xf
	v_fmac_f32_dpp v45, v252, v122 row_newbcast:6 row_mask:0xf bank_mask:0xf
	v_fmac_f32_dpp v239, v251, v74 row_newbcast:7 row_mask:0xf bank_mask:0xf
	v_fmac_f32_dpp v238, v251, v80 row_newbcast:9 row_mask:0xf bank_mask:0xf
	s_nop 0
	v_fmac_f32_dpp v44, v252, v130 row_newbcast:8 row_mask:0xf bank_mask:0xf
	v_fmac_f32_dpp v45, v252, v138 row_newbcast:10 row_mask:0xf bank_mask:0xf
	v_fmac_f32_dpp v239, v251, v86 row_newbcast:11 row_mask:0xf bank_mask:0xf
	v_fmac_f32_dpp v238, v251, v92 row_newbcast:13 row_mask:0xf bank_mask:0xf
	s_nop 0
	v_fmac_f32_dpp v44, v252, v144 row_newbcast:12 row_mask:0xf bank_mask:0xf
	v_fmac_f32_dpp v45, v252, v136 row_newbcast:14 row_mask:0xf bank_mask:0xf
	v_fmac_f32_dpp v239, v251, v98 row_newbcast:15 row_mask:0xf bank_mask:0xf
	v_fmac_f32_dpp v238, v252, v106 row_newbcast:1 row_mask:0xf bank_mask:0xf
	s_nop 0
	v_fmac_f32_dpp v44, v253, v128 row_newbcast:0 row_mask:0xf bank_mask:0xf
	v_fmac_f32_dpp v45, v253, v120 row_newbcast:2 row_mask:0xf bank_mask:0xf
	s_nop 0
	v_fmac_f32_dpp v239, v252, v112 row_newbcast:3 row_mask:0xf bank_mask:0xf
	v_fmac_f32_dpp v238, v252, v118 row_newbcast:5 row_mask:0xf bank_mask:0xf
	v_fmac_f32_dpp v44, v253, v110 row_newbcast:4 row_mask:0xf bank_mask:0xf
	v_fmac_f32_dpp v45, v253, v100 row_newbcast:6 row_mask:0xf bank_mask:0xf
	s_waitcnt lgkmcnt(0)
	v_add_u32_e32 v254, 0xc800, v208
	ds_read2_b32 v[246:247], v254 offset0:52 offset1:68
	v_fmac_f32_dpp v36, v242, v71 row_newbcast:0 row_mask:0xf bank_mask:0xf
	v_fmac_f32_dpp v37, v242, v235 row_newbcast:2 row_mask:0xf bank_mask:0xf
	v_fmac_f32_dpp v239, v252, v126 row_newbcast:7 row_mask:0xf bank_mask:0xf
	v_fmac_f32_dpp v238, v252, v134 row_newbcast:9 row_mask:0xf bank_mask:0xf
	v_fmac_f32_dpp v44, v253, v88 row_newbcast:8 row_mask:0xf bank_mask:0xf
	v_fmac_f32_dpp v45, v253, v76 row_newbcast:10 row_mask:0xf bank_mask:0xf
	s_nop 0
	v_fmac_f32_dpp v36, v242, v4 row_newbcast:4 row_mask:0xf bank_mask:0xf
	v_fmac_f32_dpp v37, v242, v8 row_newbcast:6 row_mask:0xf bank_mask:0xf
	v_fmac_f32_dpp v239, v252, v142 row_newbcast:11 row_mask:0xf bank_mask:0xf
	v_fmac_f32_dpp v238, v252, v140 row_newbcast:13 row_mask:0xf bank_mask:0xf
	v_add_u32_e32 v1, 0xc800, v208
	v_fmac_f32_dpp v239, v252, v132 row_newbcast:15 row_mask:0xf bank_mask:0xf
	v_fmac_f32_dpp v238, v253, v124 row_newbcast:1 row_mask:0xf bank_mask:0xf
	v_fmac_f32_dpp v36, v242, v12 row_newbcast:8 row_mask:0xf bank_mask:0xf
	v_fmac_f32_dpp v37, v242, v18 row_newbcast:10 row_mask:0xf bank_mask:0xf
	s_nop 0
	v_fmac_f32_dpp v239, v253, v114 row_newbcast:3 row_mask:0xf bank_mask:0xf
	v_fmac_f32_dpp v238, v253, v104 row_newbcast:5 row_mask:0xf bank_mask:0xf
	v_fmac_f32_dpp v36, v242, v22 row_newbcast:12 row_mask:0xf bank_mask:0xf
	v_fmac_f32_dpp v37, v242, v26 row_newbcast:14 row_mask:0xf bank_mask:0xf
	s_waitcnt lgkmcnt(0)
; #define LAS __attribute__((address_space(3)))
; __device__ __forceinline__ void dn_prep_item(const Args& a, LAS unsigned char* lds, int item, int tid, int wave, int lane, int& cwh, int next_item) {
;     ...
;         { const LAS float* lrow = Lm + (lane & 15);
; #pragma unroll
;         for (int i = 1; i < 64; ++i) { float sa[4] = { x[i], 0.f, 0.f, 0.f };
;             int lr[4];
; #pragma unroll
;             for (int g = 0; g < (i + 15) / 16; ++g) lr[g] = __float_as_int(lrow[i * 68 + 16 * g]);
; #pragma unroll
;             for (int j = 0; j < i; ++j) { fmac_rowbcast_sel(sa[j & 3], lr[j >> 4], x[j], j); }
;             x[i] = (sa[0] + sa[1]) + (sa[2] + sa[3]); } }
	v_add_u32_e32 v254, 0xc800, v208
	ds_read2_b32 v[248:249], v254 offset0:16 offset1:32
	v_fmac_f32_dpp v28, v246, v71 row_newbcast:0 row_mask:0xf bank_mask:0xf
	v_fmac_f32_dpp v29, v246, v235 row_newbcast:2 row_mask:0xf bank_mask:0xf
	v_fmac_f32_dpp v239, v253, v94 row_newbcast:7 row_mask:0xf bank_mask:0xf
	v_fmac_f32_dpp v238, v253, v82 row_newbcast:9 row_mask:0xf bank_mask:0xf
	v_fmac_f32_dpp v36, v243, v32 row_newbcast:0 row_mask:0xf bank_mask:0xf
	v_fmac_f32_dpp v37, v243, v38 row_newbcast:2 row_mask:0xf bank_mask:0xf
	s_nop 0
	v_pk_add_f32 v[44:45], v[44:45], v[238:239]
	v_mov_b32_e32 v238, v57
	v_mov_b32_e32 v239, v57
	v_fmac_f32_dpp v238, v242, v234 row_newbcast:1 row_mask:0xf bank_mask:0xf
	v_fmac_f32_dpp v239, v242, v2 row_newbcast:3 row_mask:0xf bank_mask:0xf
	v_fmac_f32_dpp v36, v243, v42 row_newbcast:4 row_mask:0xf bank_mask:0xf
	v_fmac_f32_dpp v37, v243, v72 row_newbcast:6 row_mask:0xf bank_mask:0xf
	v_pk_add_f32 v[44:45], v[44:45], v[44:45] op_sel:[0,1] op_sel_hi:[1,0]
	v_fmac_f32_dpp v238, v242, v6 row_newbcast:5 row_mask:0xf bank_mask:0xf
	v_fmac_f32_dpp v239, v242, v10 row_newbcast:7 row_mask:0xf bank_mask:0xf
	v_fmac_f32_dpp v36, v243, v78 row_newbcast:8 row_mask:0xf bank_mask:0xf
	v_fmac_f32_dpp v37, v243, v84 row_newbcast:10 row_mask:0xf bank_mask:0xf
	v_fmac_f32_dpp v28, v246, v4 row_newbcast:4 row_mask:0xf bank_mask:0xf
	v_fmac_f32_dpp v29, v246, v8 row_newbcast:6 row_mask:0xf bank_mask:0xf
	s_nop 0
	v_fmac_f32_dpp v238, v242, v14 row_newbcast:9 row_mask:0xf bank_mask:0xf
	v_fmac_f32_dpp v239, v242, v20 row_newbcast:11 row_mask:0xf bank_mask:0xf
	v_fmac_f32_dpp v36, v243, v90 row_newbcast:12 row_mask:0xf bank_mask:0xf
	v_fmac_f32_dpp v37, v243, v96 row_newbcast:14 row_mask:0xf bank_mask:0xf
	v_fmac_f32_dpp v28, v246, v12 row_newbcast:8 row_mask:0xf bank_mask:0xf
	v_fmac_f32_dpp v29, v246, v18 row_newbcast:10 row_mask:0xf bank_mask:0xf
	s_nop 0
	v_fmac_f32_dpp v238, v242, v24 row_newbcast:13 row_mask:0xf bank_mask:0xf
	v_fmac_f32_dpp v239, v242, v30 row_newbcast:15 row_mask:0xf bank_mask:0xf
	s_waitcnt lgkmcnt(0)
	v_add_u32_e32 v254, 0xc800, v208
	ds_read2_b32 v[250:251], v254 offset0:84 offset1:100
	v_fmac_f32_dpp v36, v248, v102 row_newbcast:0 row_mask:0xf bank_mask:0xf
	v_fmac_f32_dpp v37, v248, v108 row_newbcast:2 row_mask:0xf bank_mask:0xf
	v_fmac_f32_dpp v28, v246, v22 row_newbcast:12 row_mask:0xf bank_mask:0xf
	v_fmac_f32_dpp v29, v246, v26 row_newbcast:14 row_mask:0xf bank_mask:0xf
	v_fmac_f32_dpp v238, v243, v34 row_newbcast:1 row_mask:0xf bank_mask:0xf
	v_fmac_f32_dpp v239, v243, v40 row_newbcast:3 row_mask:0xf bank_mask:0xf
	s_nop 0
	v_fmac_f32_dpp v36, v248, v116 row_newbcast:4 row_mask:0xf bank_mask:0xf
	v_fmac_f32_dpp v37, v248, v122 row_newbcast:6 row_mask:0xf bank_mask:0xf
	v_fmac_f32_dpp v28, v247, v32 row_newbcast:0 row_mask:0xf bank_mask:0xf
	v_fmac_f32_dpp v29, v247, v38 row_newbcast:2 row_mask:0xf bank_mask:0xf
	v_fmac_f32_dpp v238, v243, v46 row_newbcast:5 row_mask:0xf bank_mask:0xf
	v_fmac_f32_dpp v239, v243, v74 row_newbcast:7 row_mask:0xf bank_mask:0xf
	s_nop 0
	v_fmac_f32_dpp v36, v248, v130 row_newbcast:8 row_mask:0xf bank_mask:0xf
	v_fmac_f32_dpp v37, v248, v138 row_newbcast:10 row_mask:0xf bank_mask:0xf
	v_fmac_f32_dpp v28, v247, v42 row_newbcast:4 row_mask:0xf bank_mask:0xf
	v_fmac_f32_dpp v29, v247, v72 row_newbcast:6 row_mask:0xf bank_mask:0xf
	v_fmac_f32_dpp v238, v243, v80 row_newbcast:9 row_mask:0xf bank_mask:0xf
	v_fmac_f32_dpp v239, v243, v86 row_newbcast:11 row_mask:0xf bank_mask:0xf
	s_nop 0
	v_fmac_f32_dpp v36, v248, v144 row_newbcast:12 row_mask:0xf bank_mask:0xf
	v_fmac_f32_dpp v37, v248, v136 row_newbcast:14 row_mask:0xf bank_mask:0xf
	v_fmac_f32_dpp v28, v247, v78 row_newbcast:8 row_mask:0xf bank_mask:0xf
	v_fmac_f32_dpp v29, v247, v84 row_newbcast:10 row_mask:0xf bank_mask:0xf
	v_fmac_f32_dpp v238, v243, v92 row_newbcast:13 row_mask:0xf bank_mask:0xf
	v_fmac_f32_dpp v239, v243, v98 row_newbcast:15 row_mask:0xf bank_mask:0xf
	s_nop 0
	v_fmac_f32_dpp v36, v249, v128 row_newbcast:0 row_mask:0xf bank_mask:0xf
	v_fmac_f32_dpp v37, v249, v120 row_newbcast:2 row_mask:0xf bank_mask:0xf
	v_fmac_f32_dpp v28, v247, v90 row_newbcast:12 row_mask:0xf bank_mask:0xf
	s_nop 0
	v_fmac_f32_dpp v238, v248, v106 row_newbcast:1 row_mask:0xf bank_mask:0xf
	v_fmac_f32_dpp v239, v248, v112 row_newbcast:3 row_mask:0xf bank_mask:0xf
	v_fmac_f32_dpp v36, v249, v110 row_newbcast:4 row_mask:0xf bank_mask:0xf
	v_fmac_f32_dpp v37, v249, v100 row_newbcast:6 row_mask:0xf bank_mask:0xf
	v_fmac_f32_dpp v29, v247, v96 row_newbcast:14 row_mask:0xf bank_mask:0xf
	s_waitcnt lgkmcnt(0)
; #define LAS __attribute__((address_space(3)))
; __device__ __forceinline__ void dn_prep_item(const Args& a, LAS unsigned char* lds, int item, int tid, int wave, int lane, int& cwh, int next_item) {
;     ...
;         { const LAS float* lrow = Lm + (lane & 15);
; #pragma unroll
;         for (int i = 1; i < 64; ++i) { float sa[4] = { x[i], 0.f, 0.f, 0.f };
;             int lr[4];
; #pragma unroll
;             for (int g = 0; g < (i + 15) / 16; ++g) lr[g] = __float_as_int(lrow[i * 68 + 16 * g]);
; #pragma unroll
;             for (int j = 0; j < i; ++j) { fmac_rowbcast_sel(sa[j & 3], lr[j >> 4], x[j], j); }
;             x[i] = (sa[0] + sa[1]) + (sa[2] + sa[3]); } }
	v_add_u32_e32 v254, 0xc800, v208
	ds_read2_b32 v[252:253], v254 offset0:120 offset1:136
	v_fmac_f32_dpp v28, v250, v102 row_newbcast:0 row_mask:0xf bank_mask:0xf
	v_fmac_f32_dpp v238, v248, v118 row_newbcast:5 row_mask:0xf bank_mask:0xf
	v_fmac_f32_dpp v239, v248, v126 row_newbcast:7 row_mask:0xf bank_mask:0xf
	v_fmac_f32_dpp v36, v249, v88 row_newbcast:8 row_mask:0xf bank_mask:0xf
	v_fmac_f32_dpp v37, v249, v76 row_newbcast:10 row_mask:0xf bank_mask:0xf
	v_fmac_f32_dpp v29, v250, v108 row_newbcast:2 row_mask:0xf bank_mask:0xf
	s_nop 0
	v_fmac_f32_dpp v28, v250, v116 row_newbcast:4 row_mask:0xf bank_mask:0xf
	v_fmac_f32_dpp v238, v248, v134 row_newbcast:9 row_mask:0xf bank_mask:0xf
	v_fmac_f32_dpp v239, v248, v142 row_newbcast:11 row_mask:0xf bank_mask:0xf
	s_nop 0
	v_fmac_f32_dpp v238, v248, v140 row_newbcast:13 row_mask:0xf bank_mask:0xf
	v_fmac_f32_dpp v239, v248, v132 row_newbcast:15 row_mask:0xf bank_mask:0xf
	v_mov_b32_e32 v236, v57
	v_fmac_f32_dpp v238, v249, v124 row_newbcast:1 row_mask:0xf bank_mask:0xf
	v_fmac_f32_dpp v239, v249, v114 row_newbcast:3 row_mask:0xf bank_mask:0xf
	v_fmac_f32_dpp v236, v246, v234 row_newbcast:1 row_mask:0xf bank_mask:0xf
	v_fmac_f32_dpp v29, v250, v122 row_newbcast:6 row_mask:0xf bank_mask:0xf
	v_fmac_f32_dpp v28, v250, v130 row_newbcast:8 row_mask:0xf bank_mask:0xf
	s_nop 0
	v_fmac_f32_dpp v238, v249, v104 row_newbcast:5 row_mask:0xf bank_mask:0xf
	v_fmac_f32_dpp v239, v249, v94 row_newbcast:7 row_mask:0xf bank_mask:0xf
	v_fmac_f32_dpp v236, v246, v6 row_newbcast:5 row_mask:0xf bank_mask:0xf
	v_fmac_f32_dpp v29, v250, v138 row_newbcast:10 row_mask:0xf bank_mask:0xf
	v_fmac_f32_dpp v28, v250, v144 row_newbcast:12 row_mask:0xf bank_mask:0xf
	s_nop 0
	v_fmac_f32_dpp v238, v249, v82 row_newbcast:9 row_mask:0xf bank_mask:0xf
	v_fmac_f32_dpp v239, v249, v44 row_newbcast:11 row_mask:0xf bank_mask:0xf
	v_mov_b32_e32 v237, v57
	v_fmac_f32_dpp v237, v246, v2 row_newbcast:3 row_mask:0xf bank_mask:0xf
	v_fmac_f32_dpp v236, v246, v14 row_newbcast:9 row_mask:0xf bank_mask:0xf
	v_fmac_f32_dpp v29, v250, v136 row_newbcast:14 row_mask:0xf bank_mask:0xf
	v_fmac_f32_dpp v28, v251, v128 row_newbcast:0 row_mask:0xf bank_mask:0xf
	v_pk_add_f32 v[36:37], v[36:37], v[238:239]
	v_fmac_f32_dpp v237, v246, v10 row_newbcast:7 row_mask:0xf bank_mask:0xf
	v_fmac_f32_dpp v236, v246, v24 row_newbcast:13 row_mask:0xf bank_mask:0xf
	v_fmac_f32_dpp v29, v251, v120 row_newbcast:2 row_mask:0xf bank_mask:0xf
	v_fmac_f32_dpp v28, v251, v110 row_newbcast:4 row_mask:0xf bank_mask:0xf
	s_nop 0
	v_fmac_f32_dpp v237, v246, v20 row_newbcast:11 row_mask:0xf bank_mask:0xf
	v_fmac_f32_dpp v236, v247, v34 row_newbcast:1 row_mask:0xf bank_mask:0xf
	v_fmac_f32_dpp v29, v251, v100 row_newbcast:6 row_mask:0xf bank_mask:0xf
	v_fmac_f32_dpp v28, v251, v88 row_newbcast:8 row_mask:0xf bank_mask:0xf
	v_pk_add_f32 v[36:37], v[36:37], v[36:37] op_sel:[0,1] op_sel_hi:[1,0]
	v_fmac_f32_dpp v237, v246, v30 row_newbcast:15 row_mask:0xf bank_mask:0xf
	v_fmac_f32_dpp v236, v247, v46 row_newbcast:5 row_mask:0xf bank_mask:0xf
	v_fmac_f32_dpp v29, v251, v76 row_newbcast:10 row_mask:0xf bank_mask:0xf
	s_waitcnt lgkmcnt(0)
	v_add_u32_e32 v254, 0xc800, v208
	ds_read2_b32 v[242:243], v254 offset0:152 offset1:168
	v_fmac_f32_dpp v16, v252, v71 row_newbcast:0 row_mask:0xf bank_mask:0xf
	v_fmac_f32_dpp v17, v252, v235 row_newbcast:2 row_mask:0xf bank_mask:0xf
	v_fmac_f32_dpp v28, v251, v36 row_newbcast:12 row_mask:0xf bank_mask:0xf
	v_fmac_f32_dpp v237, v247, v40 row_newbcast:3 row_mask:0xf bank_mask:0xf
	v_fmac_f32_dpp v236, v247, v80 row_newbcast:9 row_mask:0xf bank_mask:0xf
	s_nop 0
	v_fmac_f32_dpp v237, v247, v74 row_newbcast:7 row_mask:0xf bank_mask:0xf
	v_fmac_f32_dpp v236, v247, v92 row_newbcast:13 row_mask:0xf bank_mask:0xf
	v_fmac_f32_dpp v16, v252, v4 row_newbcast:4 row_mask:0xf bank_mask:0xf
	v_fmac_f32_dpp v17, v252, v8 row_newbcast:6 row_mask:0xf bank_mask:0xf
	s_nop 0
	v_fmac_f32_dpp v237, v247, v86 row_newbcast:11 row_mask:0xf bank_mask:0xf
	v_fmac_f32_dpp v236, v250, v106 row_newbcast:1 row_mask:0xf bank_mask:0xf
	v_fmac_f32_dpp v16, v252, v12 row_newbcast:8 row_mask:0xf bank_mask:0xf
	v_fmac_f32_dpp v17, v252, v18 row_newbcast:10 row_mask:0xf bank_mask:0xf
	s_nop 0
	v_fmac_f32_dpp v237, v247, v98 row_newbcast:15 row_mask:0xf bank_mask:0xf
	v_fmac_f32_dpp v236, v250, v118 row_newbcast:5 row_mask:0xf bank_mask:0xf
	v_fmac_f32_dpp v16, v252, v22 row_newbcast:12 row_mask:0xf bank_mask:0xf
	v_fmac_f32_dpp v17, v252, v26 row_newbcast:14 row_mask:0xf bank_mask:0xf
	s_nop 0
	v_fmac_f32_dpp v237, v250, v112 row_newbcast:3 row_mask:0xf bank_mask:0xf
	v_fmac_f32_dpp v236, v250, v134 row_newbcast:9 row_mask:0xf bank_mask:0xf
	v_fmac_f32_dpp v16, v253, v32 row_newbcast:0 row_mask:0xf bank_mask:0xf
	v_fmac_f32_dpp v17, v253, v38 row_newbcast:2 row_mask:0xf bank_mask:0xf
	s_nop 0
	v_fmac_f32_dpp v237, v250, v126 row_newbcast:7 row_mask:0xf bank_mask:0xf
	v_fmac_f32_dpp v236, v250, v140 row_newbcast:13 row_mask:0xf bank_mask:0xf
	v_fmac_f32_dpp v16, v253, v42 row_newbcast:4 row_mask:0xf bank_mask:0xf
	v_fmac_f32_dpp v17, v253, v72 row_newbcast:6 row_mask:0xf bank_mask:0xf
	s_nop 0
	v_fmac_f32_dpp v237, v250, v142 row_newbcast:11 row_mask:0xf bank_mask:0xf
	v_fmac_f32_dpp v236, v251, v124 row_newbcast:1 row_mask:0xf bank_mask:0xf
	v_fmac_f32_dpp v16, v253, v78 row_newbcast:8 row_mask:0xf bank_mask:0xf
	v_fmac_f32_dpp v17, v253, v84 row_newbcast:10 row_mask:0xf bank_mask:0xf
	s_nop 0
	v_fmac_f32_dpp v237, v250, v132 row_newbcast:15 row_mask:0xf bank_mask:0xf
	v_fmac_f32_dpp v236, v251, v104 row_newbcast:5 row_mask:0xf bank_mask:0xf
	v_fmac_f32_dpp v16, v253, v90 row_newbcast:12 row_mask:0xf bank_mask:0xf
	v_fmac_f32_dpp v17, v253, v96 row_newbcast:14 row_mask:0xf bank_mask:0xf
	s_nop 0
	v_fmac_f32_dpp v237, v251, v114 row_newbcast:3 row_mask:0xf bank_mask:0xf
	v_fmac_f32_dpp v236, v251, v82 row_newbcast:9 row_mask:0xf bank_mask:0xf
	s_nop 0
	v_fmac_f32_dpp v237, v251, v94 row_newbcast:7 row_mask:0xf bank_mask:0xf
	s_nop 0
	v_fmac_f32_dpp v237, v251, v44 row_newbcast:11 row_mask:0xf bank_mask:0xf
	s_nop 0
	v_pk_add_f32 v[28:29], v[28:29], v[236:237]
	v_mov_b32_e32 v236, v57
	v_fmac_f32_dpp v236, v252, v234 row_newbcast:1 row_mask:0xf bank_mask:0xf
	v_mov_b32_e32 v237, v57
	v_fmac_f32_dpp v237, v252, v2 row_newbcast:3 row_mask:0xf bank_mask:0xf
	v_fmac_f32_dpp v236, v252, v6 row_newbcast:5 row_mask:0xf bank_mask:0xf
	s_waitcnt lgkmcnt(0)
; #define LAS __attribute__((address_space(3)))
; __device__ __forceinline__ void dn_prep_item(const Args& a, LAS unsigned char* lds, int item, int tid, int wave, int lane, int& cwh, int next_item) {
;     ...
;         { const LAS float* lrow = Lm + (lane & 15);
; #pragma unroll
;         for (int i = 1; i < 64; ++i) { float sa[4] = { x[i], 0.f, 0.f, 0.f };
;             int lr[4];
; #pragma unroll
;             for (int g = 0; g < (i + 15) / 16; ++g) lr[g] = __float_as_int(lrow[i * 68 + 16 * g]);
; #pragma unroll
;             for (int j = 0; j < i; ++j) { fmac_rowbcast_sel(sa[j & 3], lr[j >> 4], x[j], j); }
;             x[i] = (sa[0] + sa[1]) + (sa[2] + sa[3]); } }
	v_add_u32_e32 v254, 0xc800, v208
	ds_read2_b32 v[246:247], v254 offset0:188 offset1:204
	v_fmac_f32_dpp v16, v242, v102 row_newbcast:0 row_mask:0xf bank_mask:0xf
	v_fmac_f32_dpp v17, v242, v108 row_newbcast:2 row_mask:0xf bank_mask:0xf
	v_pk_add_f32 v[28:29], v[28:29], v[28:29] op_sel:[0,1] op_sel_hi:[1,0]
	v_fmac_f32_dpp v237, v252, v10 row_newbcast:7 row_mask:0xf bank_mask:0xf
	v_fmac_f32_dpp v236, v252, v14 row_newbcast:9 row_mask:0xf bank_mask:0xf
	v_fmac_f32_dpp v16, v242, v116 row_newbcast:4 row_mask:0xf bank_mask:0xf
	v_fmac_f32_dpp v17, v242, v122 row_newbcast:6 row_mask:0xf bank_mask:0xf
	s_nop 0
	v_fmac_f32_dpp v237, v252, v20 row_newbcast:11 row_mask:0xf bank_mask:0xf
	v_fmac_f32_dpp v236, v252, v24 row_newbcast:13 row_mask:0xf bank_mask:0xf
	v_fmac_f32_dpp v16, v242, v130 row_newbcast:8 row_mask:0xf bank_mask:0xf
	v_fmac_f32_dpp v17, v242, v138 row_newbcast:10 row_mask:0xf bank_mask:0xf
	s_nop 0
	v_fmac_f32_dpp v237, v252, v30 row_newbcast:15 row_mask:0xf bank_mask:0xf
	v_fmac_f32_dpp v236, v253, v34 row_newbcast:1 row_mask:0xf bank_mask:0xf
	v_fmac_f32_dpp v16, v242, v144 row_newbcast:12 row_mask:0xf bank_mask:0xf
	v_fmac_f32_dpp v17, v242, v136 row_newbcast:14 row_mask:0xf bank_mask:0xf
	s_nop 0
	v_fmac_f32_dpp v237, v253, v40 row_newbcast:3 row_mask:0xf bank_mask:0xf
	v_fmac_f32_dpp v236, v253, v46 row_newbcast:5 row_mask:0xf bank_mask:0xf
	v_fmac_f32_dpp v16, v243, v128 row_newbcast:0 row_mask:0xf bank_mask:0xf
	v_fmac_f32_dpp v17, v243, v120 row_newbcast:2 row_mask:0xf bank_mask:0xf
	s_nop 0
	v_fmac_f32_dpp v237, v253, v74 row_newbcast:7 row_mask:0xf bank_mask:0xf
	v_fmac_f32_dpp v236, v253, v80 row_newbcast:9 row_mask:0xf bank_mask:0xf
	v_fmac_f32_dpp v16, v243, v110 row_newbcast:4 row_mask:0xf bank_mask:0xf
	v_fmac_f32_dpp v17, v243, v100 row_newbcast:6 row_mask:0xf bank_mask:0xf
	s_nop 0
	v_fmac_f32_dpp v237, v253, v86 row_newbcast:11 row_mask:0xf bank_mask:0xf
	v_fmac_f32_dpp v236, v253, v92 row_newbcast:13 row_mask:0xf bank_mask:0xf
	v_fmac_f32_dpp v16, v243, v88 row_newbcast:8 row_mask:0xf bank_mask:0xf
	v_fmac_f32_dpp v17, v243, v76 row_newbcast:10 row_mask:0xf bank_mask:0xf
	s_nop 0
	v_fmac_f32_dpp v237, v253, v98 row_newbcast:15 row_mask:0xf bank_mask:0xf
	v_fmac_f32_dpp v236, v242, v106 row_newbcast:1 row_mask:0xf bank_mask:0xf
	v_fmac_f32_dpp v16, v243, v36 row_newbcast:12 row_mask:0xf bank_mask:0xf
	s_nop 0
	v_fmac_f32_dpp v237, v242, v112 row_newbcast:3 row_mask:0xf bank_mask:0xf
	v_fmac_f32_dpp v236, v242, v118 row_newbcast:5 row_mask:0xf bank_mask:0xf
	s_waitcnt lgkmcnt(0)
	v_add_u32_e32 v254, 0xc800, v208
	ds_read2_b32 v[248:249], v254 offset0:220 offset1:236
	v_fmac_f32_dpp v0, v246, v71 row_newbcast:0 row_mask:0xf bank_mask:0xf
	v_fmac_f32_dpp v237, v242, v126 row_newbcast:7 row_mask:0xf bank_mask:0xf
	v_fmac_f32_dpp v236, v242, v134 row_newbcast:9 row_mask:0xf bank_mask:0xf
	s_nop 0
	v_fmac_f32_dpp v0, v246, v4 row_newbcast:4 row_mask:0xf bank_mask:0xf
	v_fmac_f32_dpp v237, v242, v142 row_newbcast:11 row_mask:0xf bank_mask:0xf
	v_fmac_f32_dpp v236, v242, v140 row_newbcast:13 row_mask:0xf bank_mask:0xf
	s_nop 0
	v_fmac_f32_dpp v0, v246, v12 row_newbcast:8 row_mask:0xf bank_mask:0xf
	v_fmac_f32_dpp v237, v242, v132 row_newbcast:15 row_mask:0xf bank_mask:0xf
	v_fmac_f32_dpp v236, v243, v124 row_newbcast:1 row_mask:0xf bank_mask:0xf
	s_nop 0
	v_fmac_f32_dpp v0, v246, v22 row_newbcast:12 row_mask:0xf bank_mask:0xf
	v_fmac_f32_dpp v237, v243, v114 row_newbcast:3 row_mask:0xf bank_mask:0xf
	v_fmac_f32_dpp v236, v243, v104 row_newbcast:5 row_mask:0xf bank_mask:0xf
	s_nop 0
	v_fmac_f32_dpp v0, v247, v32 row_newbcast:0 row_mask:0xf bank_mask:0xf
	v_fmac_f32_dpp v237, v243, v94 row_newbcast:7 row_mask:0xf bank_mask:0xf
	v_fmac_f32_dpp v236, v243, v82 row_newbcast:9 row_mask:0xf bank_mask:0xf
	s_nop 0
	v_fmac_f32_dpp v0, v247, v42 row_newbcast:4 row_mask:0xf bank_mask:0xf
	v_fmac_f32_dpp v237, v243, v44 row_newbcast:11 row_mask:0xf bank_mask:0xf
	v_fmac_f32_dpp v236, v243, v28 row_newbcast:13 row_mask:0xf bank_mask:0xf
	s_nop 0
	v_mov_b32_e32 v1, v57
	v_pk_add_f32 v[16:17], v[16:17], v[236:237]
	v_mov_b32_e32 v236, v57
	v_fmac_f32_dpp v1, v246, v235 row_newbcast:2 row_mask:0xf bank_mask:0xf
	v_fmac_f32_dpp v236, v246, v234 row_newbcast:1 row_mask:0xf bank_mask:0xf
	v_mov_b32_e32 v237, v57
	v_fmac_f32_dpp v1, v246, v8 row_newbcast:6 row_mask:0xf bank_mask:0xf
	v_fmac_f32_dpp v237, v246, v2 row_newbcast:3 row_mask:0xf bank_mask:0xf
	v_fmac_f32_dpp v236, v246, v6 row_newbcast:5 row_mask:0xf bank_mask:0xf
	v_fmac_f32_dpp v0, v247, v78 row_newbcast:8 row_mask:0xf bank_mask:0xf
	v_pk_add_f32 v[16:17], v[16:17], v[16:17] op_sel:[0,1] op_sel_hi:[1,0]
	v_fmac_f32_dpp v1, v246, v18 row_newbcast:10 row_mask:0xf bank_mask:0xf
	v_fmac_f32_dpp v237, v246, v10 row_newbcast:7 row_mask:0xf bank_mask:0xf
	v_fmac_f32_dpp v236, v246, v14 row_newbcast:9 row_mask:0xf bank_mask:0xf
	v_fmac_f32_dpp v0, v247, v90 row_newbcast:12 row_mask:0xf bank_mask:0xf
	s_nop 0
	v_fmac_f32_dpp v1, v246, v26 row_newbcast:14 row_mask:0xf bank_mask:0xf
	v_fmac_f32_dpp v237, v246, v20 row_newbcast:11 row_mask:0xf bank_mask:0xf
	v_fmac_f32_dpp v236, v246, v24 row_newbcast:13 row_mask:0xf bank_mask:0xf
	s_waitcnt lgkmcnt(0)
; #define LAS __attribute__((address_space(3)))
; __device__ __forceinline__ unsigned pk2(float lo, float hi) { const f32x2_t v = {lo, hi}; const bf16x2_t b = __builtin_convertvector(v, bf16x2_t); return __builtin_bit_cast(unsigned, b); }
; __device__ __forceinline__ void dn_prep_item(const Args& a, LAS unsigned char* lds, int item, int tid, int wave, int lane, int& cwh, int next_item) {
;     ...
;         for (int i = 1; i < 64; ++i) { float sa[4] = { x[i], 0.f, 0.f, 0.f };
;             int lr[4];
; #pragma unroll
;             for (int g = 0; g < (i + 15) / 16; ++g) lr[g] = __float_as_int(lrow[i * 68 + 16 * g]);
; #pragma unroll
;             for (int j = 0; j < i; ++j) { fmac_rowbcast_sel(sa[j & 3], lr[j >> 4], x[j], j); }
;             x[i] = (sa[0] + sa[1]) + (sa[2] + sa[3]); } }
; #pragma unroll
;         for (int q = 0; q < 8; ++q) { v4u w; w.x = pk2(x[8 * q], x[8 * q + 1]); w.y = pk2(x[8 * q + 2], x[8 * q + 3]); w.z = pk2(x[8 * q + 4], x[8 * q + 5]); w.w = pk2(x[8 * q + 6], x[8 * q + 7]);
;             *(LAS v4u*)(lds + L_SOL + tid * AS_ + 16 * q) = w; }
	v_fmac_f32_dpp v0, v248, v102 row_newbcast:0 row_mask:0xf bank_mask:0xf
	v_fmac_f32_dpp v1, v247, v38 row_newbcast:2 row_mask:0xf bank_mask:0xf
	v_fmac_f32_dpp v237, v246, v30 row_newbcast:15 row_mask:0xf bank_mask:0xf
	v_fmac_f32_dpp v236, v247, v34 row_newbcast:1 row_mask:0xf bank_mask:0xf
	s_nop 0
	v_fmac_f32_dpp v0, v248, v116 row_newbcast:4 row_mask:0xf bank_mask:0xf
	v_fmac_f32_dpp v1, v247, v72 row_newbcast:6 row_mask:0xf bank_mask:0xf
	v_fmac_f32_dpp v237, v247, v40 row_newbcast:3 row_mask:0xf bank_mask:0xf
	v_fmac_f32_dpp v236, v247, v46 row_newbcast:5 row_mask:0xf bank_mask:0xf
	s_nop 0
	v_fmac_f32_dpp v0, v248, v130 row_newbcast:8 row_mask:0xf bank_mask:0xf
	v_fmac_f32_dpp v1, v247, v84 row_newbcast:10 row_mask:0xf bank_mask:0xf
	v_fmac_f32_dpp v237, v247, v74 row_newbcast:7 row_mask:0xf bank_mask:0xf
	v_fmac_f32_dpp v236, v247, v80 row_newbcast:9 row_mask:0xf bank_mask:0xf
	s_nop 0
	v_fmac_f32_dpp v0, v248, v144 row_newbcast:12 row_mask:0xf bank_mask:0xf
	v_fmac_f32_dpp v1, v247, v96 row_newbcast:14 row_mask:0xf bank_mask:0xf
	v_fmac_f32_dpp v237, v247, v86 row_newbcast:11 row_mask:0xf bank_mask:0xf
	v_fmac_f32_dpp v236, v247, v92 row_newbcast:13 row_mask:0xf bank_mask:0xf
	s_nop 0
	v_fmac_f32_dpp v0, v249, v128 row_newbcast:0 row_mask:0xf bank_mask:0xf
	v_fmac_f32_dpp v1, v248, v108 row_newbcast:2 row_mask:0xf bank_mask:0xf
	v_fmac_f32_dpp v237, v247, v98 row_newbcast:15 row_mask:0xf bank_mask:0xf
	v_fmac_f32_dpp v236, v248, v106 row_newbcast:1 row_mask:0xf bank_mask:0xf
	s_nop 0
	v_fmac_f32_dpp v0, v249, v110 row_newbcast:4 row_mask:0xf bank_mask:0xf
	v_fmac_f32_dpp v1, v248, v122 row_newbcast:6 row_mask:0xf bank_mask:0xf
	v_fmac_f32_dpp v237, v248, v112 row_newbcast:3 row_mask:0xf bank_mask:0xf
	v_fmac_f32_dpp v236, v248, v118 row_newbcast:5 row_mask:0xf bank_mask:0xf
	s_nop 0
	v_fmac_f32_dpp v0, v249, v88 row_newbcast:8 row_mask:0xf bank_mask:0xf
	v_fmac_f32_dpp v1, v248, v138 row_newbcast:10 row_mask:0xf bank_mask:0xf
	v_fmac_f32_dpp v237, v248, v126 row_newbcast:7 row_mask:0xf bank_mask:0xf
	v_fmac_f32_dpp v236, v248, v134 row_newbcast:9 row_mask:0xf bank_mask:0xf
	s_nop 0
	v_fmac_f32_dpp v0, v249, v36 row_newbcast:12 row_mask:0xf bank_mask:0xf
	v_fmac_f32_dpp v1, v248, v136 row_newbcast:14 row_mask:0xf bank_mask:0xf
	v_fmac_f32_dpp v237, v248, v142 row_newbcast:11 row_mask:0xf bank_mask:0xf
	v_fmac_f32_dpp v236, v248, v140 row_newbcast:13 row_mask:0xf bank_mask:0xf
	s_nop 0
	v_fmac_f32_dpp v1, v249, v120 row_newbcast:2 row_mask:0xf bank_mask:0xf
	v_fmac_f32_dpp v237, v248, v132 row_newbcast:15 row_mask:0xf bank_mask:0xf
	v_fmac_f32_dpp v236, v249, v124 row_newbcast:1 row_mask:0xf bank_mask:0xf
	s_nop 0
	v_fmac_f32_dpp v1, v249, v100 row_newbcast:6 row_mask:0xf bank_mask:0xf
	v_fmac_f32_dpp v237, v249, v114 row_newbcast:3 row_mask:0xf bank_mask:0xf
	v_fmac_f32_dpp v236, v249, v104 row_newbcast:5 row_mask:0xf bank_mask:0xf
	s_nop 0
	v_fmac_f32_dpp v1, v249, v76 row_newbcast:10 row_mask:0xf bank_mask:0xf
	v_fmac_f32_dpp v237, v249, v94 row_newbcast:7 row_mask:0xf bank_mask:0xf
	v_fmac_f32_dpp v236, v249, v82 row_newbcast:9 row_mask:0xf bank_mask:0xf
	s_nop 0
	v_fmac_f32_dpp v1, v249, v16 row_newbcast:14 row_mask:0xf bank_mask:0xf
	v_fmac_f32_dpp v237, v249, v44 row_newbcast:11 row_mask:0xf bank_mask:0xf
	v_fmac_f32_dpp v236, v249, v28 row_newbcast:13 row_mask:0xf bank_mask:0xf
	s_nop 0
	v_pk_add_f32 v[0:1], v[0:1], v[236:237]
	s_nop 0
	v_pk_add_f32 v[146:147], v[0:1], v[0:1] op_sel_hi:[0,1]
	v_cvt_pk_bf16_f32 v0, v71, v234
	v_cvt_pk_bf16_f32 v1, v235, v2
	v_cvt_pk_bf16_f32 v2, v4, v6
	ds_write_b128 v223, v[0:3] offset:61440
	v_cvt_pk_bf16_f32 v0, v12, v14
	v_cvt_pk_bf16_f32 v1, v18, v20
	v_cvt_pk_bf16_f32 v2, v22, v24
	v_cvt_pk_bf16_f32 v3, v26, v30
	ds_write_b128 v223, v[0:3] offset:61456
	v_cvt_pk_bf16_f32 v0, v32, v34
	v_cvt_pk_bf16_f32 v1, v38, v40
	v_cvt_pk_bf16_f32 v2, v42, v46
	v_cvt_pk_bf16_f32 v3, v72, v74
	ds_write_b128 v223, v[0:3] offset:61472
	v_cvt_pk_bf16_f32 v0, v78, v80
	v_cvt_pk_bf16_f32 v1, v84, v86
	v_cvt_pk_bf16_f32 v2, v90, v92
	v_cvt_pk_bf16_f32 v3, v96, v98
	ds_write_b128 v223, v[0:3] offset:61488
	v_cvt_pk_bf16_f32 v0, v102, v106
	v_cvt_pk_bf16_f32 v1, v108, v112
	v_cvt_pk_bf16_f32 v2, v116, v118
	v_cvt_pk_bf16_f32 v3, v122, v126
	ds_write_b128 v223, v[0:3] offset:61504
	v_cvt_pk_bf16_f32 v0, v130, v134
	v_cvt_pk_bf16_f32 v1, v138, v142
	v_cvt_pk_bf16_f32 v2, v144, v140
	v_cvt_pk_bf16_f32 v3, v136, v132
	ds_write_b128 v223, v[0:3] offset:61520
	v_cvt_pk_bf16_f32 v0, v128, v124
	v_cvt_pk_bf16_f32 v1, v120, v114
	v_cvt_pk_bf16_f32 v2, v110, v104
	v_cvt_pk_bf16_f32 v3, v100, v94
	ds_write_b128 v223, v[0:3] offset:61536
	v_cvt_pk_bf16_f32 v0, v88, v82
	v_cvt_pk_bf16_f32 v1, v76, v44
	v_cvt_pk_bf16_f32 v2, v36, v28
	v_cvt_pk_bf16_f32 v3, v16, v147
	ds_write_b128 v223, v[0:3] offset:61552

; __global__ void __launch_bounds__(NTHR, 2) fwd_kernel(Args args) {
	.amdhsa_kernel _Z10fwd_kernel4Args
		.amdhsa_group_segment_fixed_size 0
		.amdhsa_private_segment_fixed_size 0
		.amdhsa_kernarg_size 448
		.amdhsa_user_sgpr_count 2
		.amdhsa_user_sgpr_dispatch_ptr 0
		.amdhsa_user_sgpr_queue_ptr 0
		.amdhsa_user_sgpr_kernarg_segment_ptr 1
		.amdhsa_user_sgpr_dispatch_id 0
		.amdhsa_user_sgpr_kernarg_preload_length 0
		.amdhsa_user_sgpr_kernarg_preload_offset 0
		.amdhsa_user_sgpr_private_segment_size 0
		.amdhsa_uses_dynamic_stack 0
		.amdhsa_enable_private_segment 0
		.amdhsa_system_sgpr_workgroup_id_x 1
		.amdhsa_system_sgpr_workgroup_id_y 0
		.amdhsa_system_sgpr_workgroup_id_z 0
		.amdhsa_system_sgpr_workgroup_info 0
		.amdhsa_system_vgpr_workitem_id 2
		.amdhsa_next_free_vgpr 256
		.amdhsa_next_free_sgpr 98
		.amdhsa_accum_offset 256
		.amdhsa_reserve_vcc 1
		.amdhsa_float_round_mode_32 0
		.amdhsa_float_round_mode_16_64 0
		.amdhsa_float_denorm_mode_32 3
		.amdhsa_float_denorm_mode_16_64 3
		.amdhsa_dx10_clamp 1
		.amdhsa_ieee_mode 1
		.amdhsa_fp16_overflow 0
		.amdhsa_tg_split 0
		.amdhsa_exception_fp_ieee_invalid_op 0
		.amdhsa_exception_fp_denorm_src 0
		.amdhsa_exception_fp_ieee_div_zero 0
		.amdhsa_exception_fp_ieee_overflow 0
		.amdhsa_exception_fp_ieee_underflow 0
		.amdhsa_exception_fp_ieee_inexact 0
		.amdhsa_exception_int_div_zero 0
	.end_amdhsa_kernel

; __global__ void __launch_bounds__(NTHR, 2) fwd_kernel(Args args) {
amdhsa.kernels:
  - .agpr_count:     0
    .args:
      - .offset:         0
        .size:           192
        .value_kind:     by_value
      - .offset:         192
        .size:           4
        .value_kind:     hidden_block_count_x
      - .offset:         196
        .size:           4
        .value_kind:     hidden_block_count_y
      - .offset:         200
        .size:           4
        .value_kind:     hidden_block_count_z
      - .offset:         204
        .size:           2
        .value_kind:     hidden_group_size_x
      - .offset:         206
        .size:           2
        .value_kind:     hidden_group_size_y
      - .offset:         208
        .size:           2
        .value_kind:     hidden_group_size_z
      - .offset:         210
        .size:           2
        .value_kind:     hidden_remainder_x
      - .offset:         212
        .size:           2
        .value_kind:     hidden_remainder_y
      - .offset:         214
        .size:           2
        .value_kind:     hidden_remainder_z
      - .offset:         232
        .size:           8
        .value_kind:     hidden_global_offset_x
      - .offset:         240
        .size:           8
        .value_kind:     hidden_global_offset_y
      - .offset:         248
        .size:           8
        .value_kind:     hidden_global_offset_z
      - .offset:         256
        .size:           2
        .value_kind:     hidden_grid_dims
      - .offset:         280
        .size:           8
        .value_kind:     hidden_multigrid_sync_arg
      - .offset:         312
        .size:           4
        .value_kind:     hidden_dynamic_lds_size
    .group_segment_fixed_size: 0
    .kernarg_segment_align: 8
    .kernarg_segment_size: 448
    .language:       OpenCL C
    .language_version:
      - 2
      - 0
    .max_flat_workgroup_size: 512
    .name:           _Z10fwd_kernel4Args
    .private_segment_fixed_size: 0
    .sgpr_count:     104
    .sgpr_spill_count: 56
    .symbol:         _Z10fwd_kernel4Args.kd
    .uniform_work_group_size: 1
    .uses_dynamic_stack: false
    .vgpr_count:     256
    .vgpr_spill_count: 0
    .wavefront_size: 64
